# GEMM epilogue flat_load/flat_store -> global_load/global_store so lgkmcnt(0) no longer waits for row stores (plus earlier edits)
# baseline (speedup 1.0000x reference)
; __device__ __forceinline__ unsigned pk2(float lo, float hi) { return pg8::cvt_pk_bf16(lo, hi); }
;     __device__ __forceinline__ void operator()(const f32x4 (&acc)[2][2][4][2], const Unit& u, int wr, int wc, int fr, int fq) const {
;     ...
;         const int row0 = u.pm * 256 + wr * 64 + fr, col0 = u.pn * 128 + wc * 32 + 8 * fq;
;         float rsv[2][4];
;         { f32x4 pp[2][4];
; #pragma unroll
;           for (int ai = 0; ai < 2; ++ai)
; #pragma unroll
;             for (int m = 0; m < 4; ++m) pp[ai][m] = *(const f32x4*)(rss + (size_t)(row0 + ai * 128 + m * 16) * 4);
; #pragma unroll
;           for (int ai = 0; ai < 2; ++ai)
; #pragma unroll
;             for (int m = 0; m < 4; ++m) rsv[ai][m] = __builtin_amdgcn_rsqf(((pp[ai][m][0] + pp[ai][m][1]) + (pp[ai][m][2] + pp[ai][m][3])) * (1.0f / D) + EPS); }
; #pragma unroll
;         for (int ai = 0; ai < 2; ++ai)
; #pragma unroll
;             for (int m = 0; m < 4; ++m) {
;                 bf16_t* rowp = O + (size_t)(row0 + ai * 128 + m * 16) * FF + col0;
;                 const float rs = rsv[ai][m];
;                 float v[8];
; #pragma unroll
;                 for (int n = 0; n < 2; ++n)
; #pragma unroll
;                     for (int j = 0; j < 4; ++j) { const float g = acc[ai][0][m][n][j] * rs, up = acc[ai][1][m][n][j] * rs; v[n * 4 + j] = g * __builtin_amdgcn_rcpf(1.0f + __expf(-g)) * up; }
;                 u32x4v w; w.x = pk2(v[0], v[1]); w.y = pk2(v[2], v[3]); w.z = pk2(v[4], v[5]); w.w = pk2(v[6], v[7]);
;                 *(u32x4v*)rowp = w;
.LBB0_322:
	v_readlane_b32 s58, v250, 28
	v_readlane_b32 s70, v251, 4
	v_lshl_add_u32 v180, s56, 8, v147
	v_readlane_b32 s59, v250, 29
	v_readlane_b32 s71, v251, 5
	v_ashrrev_i32_e32 v181, 31, v180
	v_or_b32_e32 v176, 16, v180
	v_lshl_add_u64 v[140:141], v[180:181], 4, s[58:59]
	global_load_dwordx4 v[182:185], v[140:141], off
	v_ashrrev_i32_e32 v177, 31, v176
	v_or_b32_e32 v172, 32, v180
	v_lshl_add_u64 v[140:141], v[176:177], 4, s[58:59]
	v_ashrrev_i32_e32 v173, 31, v172
	v_or_b32_e32 v168, 48, v180
	global_load_dwordx4 v[186:189], v[140:141], off
	v_lshl_add_u64 v[140:141], v[172:173], 4, s[58:59]
	v_ashrrev_i32_e32 v169, 31, v168
	v_add_u32_e32 v154, 0x80, v180
	global_load_dwordx4 v[190:193], v[140:141], off
	v_lshl_add_u64 v[140:141], v[168:169], 4, s[58:59]
	v_ashrrev_i32_e32 v155, 31, v154
	v_add_u32_e32 v150, 0x90, v180
	global_load_dwordx4 v[194:197], v[140:141], off
	v_lshl_add_u64 v[140:141], v[154:155], 4, s[58:59]
	v_ashrrev_i32_e32 v151, 31, v150
	v_add_u32_e32 v142, 0xa0, v180
	global_load_dwordx4 v[198:201], v[140:141], off
	v_lshl_add_u64 v[140:141], v[150:151], 4, s[58:59]
	v_ashrrev_i32_e32 v143, 31, v142
	global_load_dwordx4 v[202:205], v[140:141], off
	v_lshl_add_u64 v[140:141], v[142:143], 4, s[58:59]
	global_load_dwordx4 v[210:213], v[140:141], off
	v_add_u32_e32 v140, 0xb0, v180
	v_ashrrev_i32_e32 v141, 31, v140
	v_lshl_add_u64 v[144:145], v[140:141], 4, s[58:59]
	global_load_dwordx4 v[214:217], v[144:145], off
	s_and_b64 vcc, exec, s[40:41]
	s_waitcnt vmcnt(0) lgkmcnt(0)
	v_mov_b32_e32 v144, v183
	v_mov_b32_e32 v145, v184
	v_mov_b32_e32 v183, v185
	v_pk_add_f32 v[144:145], v[144:145], v[182:183]
	v_mov_b32_e32 v184, v126
	v_add_f32_e32 v141, v144, v145
	v_fmamk_f32 v141, v141, 0x3a800000, v159
	v_rsq_f32_e32 v182, v141
	v_mov_b32_e32 v185, v122
	v_mov_b32_e32 v144, v187
	v_mov_b32_e32 v145, v188
	v_pk_mul_f32 v[184:185], v[184:185], v[182:183] op_sel_hi:[1,0]
	v_mov_b32_e32 v187, v189
	v_mul_f32_e32 v122, 0xbfb8aa3b, v185
	v_exp_f32_e32 v122, v122
	v_pk_add_f32 v[144:145], v[144:145], v[186:187]
	v_add_f32_e32 v122, 1.0, v122
	v_rcp_f32_e32 v122, v122
	v_add_f32_e32 v141, v144, v145
	v_mov_b32_e32 v144, v191
	v_mov_b32_e32 v145, v192
	v_mul_f32_e32 v122, v185, v122
	v_mul_f32_e32 v126, v184, v122
	v_mov_b32_e32 v122, v127
	v_pk_mul_f32 v[122:123], v[122:123], v[182:183] op_sel_hi:[1,0]
	v_mov_b32_e32 v191, v193
	v_mul_f32_e32 v127, 0xbfb8aa3b, v123
	v_exp_f32_e32 v127, v127
	v_fmamk_f32 v141, v141, 0x3a800000, v159
	v_pk_add_f32 v[144:145], v[144:145], v[190:191]
	v_rsq_f32_e32 v178, v141
	v_add_f32_e32 v127, 1.0, v127
	v_rcp_f32_e32 v127, v127
	v_add_f32_e32 v141, v144, v145
	v_mov_b32_e32 v144, v195
	v_mov_b32_e32 v145, v196
	v_mul_f32_e32 v123, v123, v127
	v_mul_f32_e32 v127, v122, v123
	v_mov_b32_e32 v122, v128
	v_mov_b32_e32 v123, v124
	v_pk_mul_f32 v[122:123], v[122:123], v[182:183] op_sel_hi:[1,0]
	v_mov_b32_e32 v195, v197
	v_mul_f32_e32 v124, 0xbfb8aa3b, v123
	v_exp_f32_e32 v124, v124
	v_fmamk_f32 v141, v141, 0x3a800000, v159
	v_pk_add_f32 v[144:145], v[144:145], v[194:195]
	v_rsq_f32_e32 v174, v141
	v_add_f32_e32 v124, 1.0, v124
	v_rcp_f32_e32 v124, v124
	v_add_f32_e32 v141, v144, v145
	v_mov_b32_e32 v144, v199
	v_mov_b32_e32 v145, v200
	v_mul_f32_e32 v123, v123, v124
	v_mov_b32_e32 v124, v129
	v_mul_f32_e32 v128, v122, v123
	v_pk_mul_f32 v[122:123], v[124:125], v[182:183] op_sel_hi:[1,0]
	v_mov_b32_e32 v199, v201
	v_mul_f32_e32 v124, 0xbfb8aa3b, v123
	v_exp_f32_e32 v124, v124
	v_fmamk_f32 v141, v141, 0x3a800000, v159
	v_pk_add_f32 v[144:145], v[144:145], v[198:199]
	v_rsq_f32_e32 v170, v141
	v_add_f32_e32 v124, 1.0, v124
	v_rcp_f32_e32 v124, v124
	v_add_f32_e32 v141, v144, v145
	v_mov_b32_e32 v144, v203
	v_mov_b32_e32 v145, v204
	v_mul_f32_e32 v123, v123, v124
	v_mul_f32_e32 v124, v122, v123
	v_mov_b32_e32 v122, v118
	v_mov_b32_e32 v123, v114
	v_pk_mul_f32 v[122:123], v[122:123], v[182:183] op_sel_hi:[1,0]
	v_mov_b32_e32 v203, v205
	v_mul_f32_e32 v114, 0xbfb8aa3b, v123
	v_exp_f32_e32 v114, v114
	v_fmamk_f32 v141, v141, 0x3a800000, v159
	v_pk_add_f32 v[144:145], v[144:145], v[202:203]
	v_rsq_f32_e32 v156, v141
	v_add_f32_e32 v114, 1.0, v114
	v_rcp_f32_e32 v114, v114
	v_add_f32_e32 v141, v144, v145
	v_mov_b32_e32 v144, v211
	v_mov_b32_e32 v145, v212
	v_mul_f32_e32 v114, v123, v114
	v_mul_f32_e32 v122, v122, v114
	v_mov_b32_e32 v114, v119
	v_pk_mul_f32 v[114:115], v[114:115], v[182:183] op_sel_hi:[1,0]
	v_mov_b32_e32 v211, v213
	v_mul_f32_e32 v118, 0xbfb8aa3b, v115
	v_exp_f32_e32 v118, v118
	v_fmamk_f32 v141, v141, 0x3a800000, v159
	v_pk_add_f32 v[144:145], v[144:145], v[210:211]
	v_rsq_f32_e32 v152, v141
	v_add_f32_e32 v118, 1.0, v118
	v_rcp_f32_e32 v118, v118
	v_add_f32_e32 v141, v144, v145
	v_mov_b32_e32 v144, v215
	v_mov_b32_e32 v145, v216
	v_mul_f32_e32 v115, v115, v118
	v_mul_f32_e32 v123, v114, v115
	v_mov_b32_e32 v114, v120
	v_mov_b32_e32 v115, v116
	v_pk_mul_f32 v[114:115], v[114:115], v[182:183] op_sel_hi:[1,0]
	v_mov_b32_e32 v215, v217
	v_mul_f32_e32 v116, 0xbfb8aa3b, v115
	v_exp_f32_e32 v116, v116
	v_fmamk_f32 v141, v141, 0x3a800000, v159
	v_pk_add_f32 v[144:145], v[144:145], v[214:215]
	v_rsq_f32_e32 v148, v141
	v_add_f32_e32 v116, 1.0, v116
	v_rcp_f32_e32 v116, v116
	v_add_f32_e32 v141, v144, v145
	v_lshl_or_b32 v144, s55, 7, v153
	v_ashrrev_i32_e32 v145, 31, v144
	v_mul_f32_e32 v115, v115, v116
	v_mov_b32_e32 v116, v121
	v_mul_f32_e32 v120, v114, v115
	v_pk_mul_f32 v[114:115], v[116:117], v[182:183] op_sel_hi:[1,0]
	v_lshl_add_u64 v[144:145], v[144:145], 1, s[70:71]
	v_mul_f32_e32 v116, 0xbfb8aa3b, v115
	v_exp_f32_e32 v116, v116
	v_mad_i64_i32 v[118:119], s[56:57], v180, s85, v[144:145]
; __device__ __forceinline__ unsigned pk2(float lo, float hi) { return pg8::cvt_pk_bf16(lo, hi); }
;     __device__ __forceinline__ void operator()(const f32x4 (&acc)[2][2][4][2], const Unit& u, int wr, int wc, int fr, int fq) const {
;     ...
;             for (int m = 0; m < 4; ++m) {
;                 bf16_t* rowp = O + (size_t)(row0 + ai * 128 + m * 16) * FF + col0;
;                 const float rs = rsv[ai][m];
;                 float v[8];
; #pragma unroll
;                 for (int n = 0; n < 2; ++n)
; #pragma unroll
;                     for (int j = 0; j < 4; ++j) { const float g = acc[ai][0][m][n][j] * rs, up = acc[ai][1][m][n][j] * rs; v[n * 4 + j] = g * __builtin_amdgcn_rcpf(1.0f + __expf(-g)) * up; }
;                 u32x4v w; w.x = pk2(v[0], v[1]); w.y = pk2(v[2], v[3]); w.z = pk2(v[4], v[5]); w.w = pk2(v[6], v[7]);
;                 *(u32x4v*)rowp = w;
	v_fmamk_f32 v141, v141, 0x3a800000, v159
	v_add_f32_e32 v116, 1.0, v116
	v_rcp_f32_e32 v116, v116
	v_rsq_f32_e32 v146, v141
	s_mov_b64 s[70:71], -1
	v_mul_f32_e32 v115, v115, v116
	v_mul_f32_e32 v117, v114, v115
	v_cvt_pk_bf16_f32 v114, v126, v127
	v_cvt_pk_bf16_f32 v115, v128, v124
	v_cvt_pk_bf16_f32 v116, v122, v123
	v_cvt_pk_bf16_f32 v117, v120, v117
	global_store_dwordx4 v[118:119], v[114:117], off
	s_nop 1
	v_mov_b32_e32 v114, v110
	v_mov_b32_e32 v115, v106
	v_pk_mul_f32 v[114:115], v[114:115], v[178:179] op_sel_hi:[1,0]
	s_nop 0
	v_mul_f32_e32 v106, 0xbfb8aa3b, v115
	v_exp_f32_e32 v106, v106
	s_nop 0
	v_add_f32_e32 v106, 1.0, v106
	v_rcp_f32_e32 v106, v106
	s_nop 0
	v_mul_f32_e32 v106, v115, v106
	v_mul_f32_e32 v110, v114, v106
	v_mov_b32_e32 v106, v111
	v_pk_mul_f32 v[106:107], v[106:107], v[178:179] op_sel_hi:[1,0]
	s_nop 0
	v_mul_f32_e32 v111, 0xbfb8aa3b, v107
	v_exp_f32_e32 v111, v111
	s_nop 0
	v_add_f32_e32 v111, 1.0, v111
	v_rcp_f32_e32 v111, v111
	s_nop 0
	v_mul_f32_e32 v107, v107, v111
	v_mul_f32_e32 v111, v106, v107
	v_mov_b32_e32 v106, v112
	v_mov_b32_e32 v107, v108
	v_pk_mul_f32 v[106:107], v[106:107], v[178:179] op_sel_hi:[1,0]
	s_nop 0
	v_mul_f32_e32 v108, 0xbfb8aa3b, v107
	v_exp_f32_e32 v108, v108
	s_nop 0
	v_add_f32_e32 v108, 1.0, v108
	v_rcp_f32_e32 v108, v108
	s_nop 0
	v_mul_f32_e32 v107, v107, v108
	v_mov_b32_e32 v108, v113
	v_mul_f32_e32 v112, v106, v107
	v_pk_mul_f32 v[106:107], v[108:109], v[178:179] op_sel_hi:[1,0]
	s_nop 0
	v_mul_f32_e32 v108, 0xbfb8aa3b, v107
	v_exp_f32_e32 v108, v108
	s_nop 0
	v_add_f32_e32 v108, 1.0, v108
	v_rcp_f32_e32 v108, v108
	s_nop 0
	v_mul_f32_e32 v107, v107, v108
	v_mul_f32_e32 v108, v106, v107
	v_mov_b32_e32 v106, v102
	v_mov_b32_e32 v107, v98
	v_pk_mul_f32 v[106:107], v[106:107], v[178:179] op_sel_hi:[1,0]
	s_nop 0
	v_mul_f32_e32 v98, 0xbfb8aa3b, v107
	v_exp_f32_e32 v98, v98
	s_nop 0
	v_add_f32_e32 v98, 1.0, v98
	v_rcp_f32_e32 v98, v98
	s_nop 0
	v_mul_f32_e32 v98, v107, v98
	v_mul_f32_e32 v106, v106, v98
	v_mov_b32_e32 v98, v103
	v_pk_mul_f32 v[98:99], v[98:99], v[178:179] op_sel_hi:[1,0]
	s_nop 0
	v_mul_f32_e32 v102, 0xbfb8aa3b, v99
	v_exp_f32_e32 v102, v102
	s_nop 0
	v_add_f32_e32 v102, 1.0, v102
	v_rcp_f32_e32 v102, v102
	s_nop 0
	v_mul_f32_e32 v99, v99, v102
	v_mul_f32_e32 v107, v98, v99
	v_mov_b32_e32 v98, v104
	v_mov_b32_e32 v99, v100
	v_pk_mul_f32 v[98:99], v[98:99], v[178:179] op_sel_hi:[1,0]
	v_mad_i64_i32 v[102:103], s[56:57], v176, s85, v[144:145]
	v_mul_f32_e32 v100, 0xbfb8aa3b, v99
	v_exp_f32_e32 v100, v100
	s_nop 0
	v_add_f32_e32 v100, 1.0, v100
	v_rcp_f32_e32 v100, v100
	s_nop 0
	v_mul_f32_e32 v99, v99, v100
	v_mov_b32_e32 v100, v105
	v_mul_f32_e32 v104, v98, v99
	v_pk_mul_f32 v[98:99], v[100:101], v[178:179] op_sel_hi:[1,0]
	s_nop 0
	v_mul_f32_e32 v100, 0xbfb8aa3b, v99
	v_exp_f32_e32 v100, v100
	s_nop 0
	v_add_f32_e32 v100, 1.0, v100
	v_rcp_f32_e32 v100, v100
	s_nop 0
	v_mul_f32_e32 v99, v99, v100
	v_mul_f32_e32 v101, v98, v99
	v_cvt_pk_bf16_f32 v98, v110, v111
	v_cvt_pk_bf16_f32 v99, v112, v108
	v_cvt_pk_bf16_f32 v100, v106, v107
	v_cvt_pk_bf16_f32 v101, v104, v101
	global_store_dwordx4 v[102:103], v[98:101], off
	s_nop 1
	v_mov_b32_e32 v98, v94
	v_mov_b32_e32 v99, v90
	v_pk_mul_f32 v[98:99], v[98:99], v[174:175] op_sel_hi:[1,0]
	s_nop 0
	v_mul_f32_e32 v90, 0xbfb8aa3b, v99
	v_exp_f32_e32 v90, v90
	s_nop 0
	v_add_f32_e32 v90, 1.0, v90
	v_rcp_f32_e32 v90, v90
	s_nop 0
	v_mul_f32_e32 v90, v99, v90
	v_mul_f32_e32 v94, v98, v90
	v_mov_b32_e32 v90, v95
	v_pk_mul_f32 v[90:91], v[90:91], v[174:175] op_sel_hi:[1,0]
	s_nop 0
	v_mul_f32_e32 v95, 0xbfb8aa3b, v91
	v_exp_f32_e32 v95, v95
	s_nop 0
	v_add_f32_e32 v95, 1.0, v95
	v_rcp_f32_e32 v95, v95
	s_nop 0
	v_mul_f32_e32 v91, v91, v95
	v_mul_f32_e32 v95, v90, v91
	v_mov_b32_e32 v90, v96
	v_mov_b32_e32 v91, v92
	v_pk_mul_f32 v[90:91], v[90:91], v[174:175] op_sel_hi:[1,0]
	s_nop 0
	v_mul_f32_e32 v92, 0xbfb8aa3b, v91
	v_exp_f32_e32 v92, v92
	s_nop 0
	v_add_f32_e32 v92, 1.0, v92
	v_rcp_f32_e32 v92, v92
	s_nop 0
	v_mul_f32_e32 v91, v91, v92
	v_mov_b32_e32 v92, v97
	v_mul_f32_e32 v96, v90, v91
	v_pk_mul_f32 v[90:91], v[92:93], v[174:175] op_sel_hi:[1,0]
	s_nop 0
	v_mul_f32_e32 v92, 0xbfb8aa3b, v91
	v_exp_f32_e32 v92, v92
	s_nop 0
	v_add_f32_e32 v92, 1.0, v92
	v_rcp_f32_e32 v92, v92
	s_nop 0
	v_mul_f32_e32 v91, v91, v92
	v_mul_f32_e32 v92, v90, v91
	v_mov_b32_e32 v90, v86
	v_mov_b32_e32 v91, v82
	v_pk_mul_f32 v[90:91], v[90:91], v[174:175] op_sel_hi:[1,0]
	s_nop 0
	v_mul_f32_e32 v82, 0xbfb8aa3b, v91
	v_exp_f32_e32 v82, v82
	s_nop 0
	v_add_f32_e32 v82, 1.0, v82
	v_rcp_f32_e32 v82, v82
	s_nop 0
	v_mul_f32_e32 v82, v91, v82
	v_mul_f32_e32 v90, v90, v82
	v_mov_b32_e32 v82, v87
	v_pk_mul_f32 v[82:83], v[82:83], v[174:175] op_sel_hi:[1,0]
	s_nop 0
	v_mul_f32_e32 v86, 0xbfb8aa3b, v83
	v_exp_f32_e32 v86, v86
	s_nop 0
	v_add_f32_e32 v86, 1.0, v86
	v_rcp_f32_e32 v86, v86
	s_nop 0
	v_mul_f32_e32 v83, v83, v86
	v_mul_f32_e32 v91, v82, v83
	v_mov_b32_e32 v82, v88
	v_mov_b32_e32 v83, v84
	v_pk_mul_f32 v[82:83], v[82:83], v[174:175] op_sel_hi:[1,0]
	v_mad_i64_i32 v[86:87], s[56:57], v172, s85, v[144:145]
	v_mul_f32_e32 v84, 0xbfb8aa3b, v83
	v_exp_f32_e32 v84, v84
	s_nop 0
	v_add_f32_e32 v84, 1.0, v84
	v_rcp_f32_e32 v84, v84
	s_nop 0
	v_mul_f32_e32 v83, v83, v84
	v_mov_b32_e32 v84, v89
	v_mul_f32_e32 v88, v82, v83
	v_pk_mul_f32 v[82:83], v[84:85], v[174:175] op_sel_hi:[1,0]
	s_nop 0
	v_mul_f32_e32 v84, 0xbfb8aa3b, v83
	v_exp_f32_e32 v84, v84
	s_nop 0
	v_add_f32_e32 v84, 1.0, v84
	v_rcp_f32_e32 v84, v84
	s_nop 0
	v_mul_f32_e32 v83, v83, v84
	v_mul_f32_e32 v85, v82, v83
	v_cvt_pk_bf16_f32 v82, v94, v95
	v_cvt_pk_bf16_f32 v83, v96, v92
; __device__ __forceinline__ unsigned pk2(float lo, float hi) { return pg8::cvt_pk_bf16(lo, hi); }
;     __device__ __forceinline__ void operator()(const f32x4 (&acc)[2][2][4][2], const Unit& u, int wr, int wc, int fr, int fq) const {
;     ...
;             for (int m = 0; m < 4; ++m) {
;                 bf16_t* rowp = O + (size_t)(row0 + ai * 128 + m * 16) * FF + col0;
;                 const float rs = rsv[ai][m];
;                 float v[8];
; #pragma unroll
;                 for (int n = 0; n < 2; ++n)
; #pragma unroll
;                     for (int j = 0; j < 4; ++j) { const float g = acc[ai][0][m][n][j] * rs, up = acc[ai][1][m][n][j] * rs; v[n * 4 + j] = g * __builtin_amdgcn_rcpf(1.0f + __expf(-g)) * up; }
;                 u32x4v w; w.x = pk2(v[0], v[1]); w.y = pk2(v[2], v[3]); w.z = pk2(v[4], v[5]); w.w = pk2(v[6], v[7]);
;                 *(u32x4v*)rowp = w;
	v_cvt_pk_bf16_f32 v84, v90, v91
	v_cvt_pk_bf16_f32 v85, v88, v85
	global_store_dwordx4 v[86:87], v[82:85], off
	s_nop 1
	v_mov_b32_e32 v82, v78
	v_mov_b32_e32 v83, v74
	v_pk_mul_f32 v[82:83], v[82:83], v[170:171] op_sel_hi:[1,0]
	s_nop 0
	v_mul_f32_e32 v74, 0xbfb8aa3b, v83
	v_exp_f32_e32 v74, v74
	s_nop 0
	v_add_f32_e32 v74, 1.0, v74
	v_rcp_f32_e32 v74, v74
	s_nop 0
	v_mul_f32_e32 v74, v83, v74
	v_mul_f32_e32 v78, v82, v74
	v_mov_b32_e32 v74, v79
	v_pk_mul_f32 v[74:75], v[74:75], v[170:171] op_sel_hi:[1,0]
	s_nop 0
	v_mul_f32_e32 v79, 0xbfb8aa3b, v75
	v_exp_f32_e32 v79, v79
	s_nop 0
	v_add_f32_e32 v79, 1.0, v79
	v_rcp_f32_e32 v79, v79
	s_nop 0
	v_mul_f32_e32 v75, v75, v79
	v_mul_f32_e32 v79, v74, v75
	v_mov_b32_e32 v74, v80
	v_mov_b32_e32 v75, v76
	v_pk_mul_f32 v[74:75], v[74:75], v[170:171] op_sel_hi:[1,0]
	s_nop 0
	v_mul_f32_e32 v76, 0xbfb8aa3b, v75
	v_exp_f32_e32 v76, v76
	s_nop 0
	v_add_f32_e32 v76, 1.0, v76
	v_rcp_f32_e32 v76, v76
	s_nop 0
	v_mul_f32_e32 v75, v75, v76
	v_mov_b32_e32 v76, v81
	v_mul_f32_e32 v80, v74, v75
	v_pk_mul_f32 v[74:75], v[76:77], v[170:171] op_sel_hi:[1,0]
	s_nop 0
	v_mul_f32_e32 v76, 0xbfb8aa3b, v75
	v_exp_f32_e32 v76, v76
	s_nop 0
	v_add_f32_e32 v76, 1.0, v76
	v_rcp_f32_e32 v76, v76
	s_nop 0
	v_mul_f32_e32 v75, v75, v76
	v_mul_f32_e32 v76, v74, v75
	v_mov_b32_e32 v74, v70
	v_mov_b32_e32 v75, v66
	v_pk_mul_f32 v[74:75], v[74:75], v[170:171] op_sel_hi:[1,0]
	s_nop 0
	v_mul_f32_e32 v66, 0xbfb8aa3b, v75
	v_exp_f32_e32 v66, v66
	s_nop 0
	v_add_f32_e32 v66, 1.0, v66
	v_rcp_f32_e32 v66, v66
	s_nop 0
	v_mul_f32_e32 v66, v75, v66
	v_mul_f32_e32 v74, v74, v66
	v_mov_b32_e32 v66, v71
	v_pk_mul_f32 v[66:67], v[66:67], v[170:171] op_sel_hi:[1,0]
	s_nop 0
	v_mul_f32_e32 v70, 0xbfb8aa3b, v67
	v_exp_f32_e32 v70, v70
	s_nop 0
	v_add_f32_e32 v70, 1.0, v70
	v_rcp_f32_e32 v70, v70
	s_nop 0
	v_mul_f32_e32 v67, v67, v70
	v_mul_f32_e32 v75, v66, v67
	v_mov_b32_e32 v66, v72
	v_mov_b32_e32 v67, v68
	v_pk_mul_f32 v[66:67], v[66:67], v[170:171] op_sel_hi:[1,0]
	v_mad_i64_i32 v[70:71], s[56:57], v168, s85, v[144:145]
	v_mul_f32_e32 v68, 0xbfb8aa3b, v67
	v_exp_f32_e32 v68, v68
	s_nop 0
	v_add_f32_e32 v68, 1.0, v68
	v_rcp_f32_e32 v68, v68
	s_nop 0
	v_mul_f32_e32 v67, v67, v68
	v_mov_b32_e32 v68, v73
	v_mul_f32_e32 v72, v66, v67
	v_pk_mul_f32 v[66:67], v[68:69], v[170:171] op_sel_hi:[1,0]
	s_nop 0
	v_mul_f32_e32 v68, 0xbfb8aa3b, v67
	v_exp_f32_e32 v68, v68
	s_nop 0
	v_add_f32_e32 v68, 1.0, v68
	v_rcp_f32_e32 v68, v68
	s_nop 0
	v_mul_f32_e32 v67, v67, v68
	v_mul_f32_e32 v69, v66, v67
	v_cvt_pk_bf16_f32 v66, v78, v79
	v_cvt_pk_bf16_f32 v67, v80, v76
	v_cvt_pk_bf16_f32 v68, v74, v75
	v_cvt_pk_bf16_f32 v69, v72, v69
	global_store_dwordx4 v[70:71], v[66:69], off
	s_nop 1
	v_mov_b32_e32 v66, v62
	v_mov_b32_e32 v67, v58
	v_pk_mul_f32 v[66:67], v[66:67], v[156:157] op_sel_hi:[1,0]
	s_nop 0
	v_mul_f32_e32 v58, 0xbfb8aa3b, v67
	v_exp_f32_e32 v58, v58
	s_nop 0
	v_add_f32_e32 v58, 1.0, v58
	v_rcp_f32_e32 v58, v58
	s_nop 0
	v_mul_f32_e32 v58, v67, v58
	v_mul_f32_e32 v62, v66, v58
	v_mov_b32_e32 v58, v63
	v_pk_mul_f32 v[58:59], v[58:59], v[156:157] op_sel_hi:[1,0]
	s_nop 0
	v_mul_f32_e32 v63, 0xbfb8aa3b, v59
	v_exp_f32_e32 v63, v63
	s_nop 0
	v_add_f32_e32 v63, 1.0, v63
	v_rcp_f32_e32 v63, v63
	s_nop 0
	v_mul_f32_e32 v59, v59, v63
	v_mul_f32_e32 v63, v58, v59
	v_mov_b32_e32 v58, v64
	v_mov_b32_e32 v59, v60
	v_pk_mul_f32 v[58:59], v[58:59], v[156:157] op_sel_hi:[1,0]
	s_nop 0
	v_mul_f32_e32 v60, 0xbfb8aa3b, v59
	v_exp_f32_e32 v60, v60
	s_nop 0
	v_add_f32_e32 v60, 1.0, v60
	v_rcp_f32_e32 v60, v60
	s_nop 0
	v_mul_f32_e32 v59, v59, v60
	v_mov_b32_e32 v60, v65
	v_mul_f32_e32 v64, v58, v59
	v_pk_mul_f32 v[58:59], v[60:61], v[156:157] op_sel_hi:[1,0]
	s_nop 0
	v_mul_f32_e32 v60, 0xbfb8aa3b, v59
	v_exp_f32_e32 v60, v60
	s_nop 0
	v_add_f32_e32 v60, 1.0, v60
	v_rcp_f32_e32 v60, v60
	s_nop 0
	v_mul_f32_e32 v59, v59, v60
	v_mul_f32_e32 v60, v58, v59
	v_mov_b32_e32 v58, v54
	v_mov_b32_e32 v59, v50
	v_pk_mul_f32 v[58:59], v[58:59], v[156:157] op_sel_hi:[1,0]
	s_nop 0
	v_mul_f32_e32 v50, 0xbfb8aa3b, v59
	v_exp_f32_e32 v50, v50
	s_nop 0
	v_add_f32_e32 v50, 1.0, v50
	v_rcp_f32_e32 v50, v50
	s_nop 0
	v_mul_f32_e32 v50, v59, v50
	v_mul_f32_e32 v58, v58, v50
	v_mov_b32_e32 v50, v55
	v_pk_mul_f32 v[50:51], v[50:51], v[156:157] op_sel_hi:[1,0]
	s_nop 0
	v_mul_f32_e32 v54, 0xbfb8aa3b, v51
	v_exp_f32_e32 v54, v54
	s_nop 0
	v_add_f32_e32 v54, 1.0, v54
	v_rcp_f32_e32 v54, v54
	s_nop 0
	v_mul_f32_e32 v51, v51, v54
	v_mul_f32_e32 v59, v50, v51
	v_mov_b32_e32 v50, v56
	v_mov_b32_e32 v51, v52
	v_pk_mul_f32 v[50:51], v[50:51], v[156:157] op_sel_hi:[1,0]
	v_mad_i64_i32 v[54:55], s[56:57], v154, s85, v[144:145]
	v_mul_f32_e32 v52, 0xbfb8aa3b, v51
	v_exp_f32_e32 v52, v52
	s_nop 0
	v_add_f32_e32 v52, 1.0, v52
	v_rcp_f32_e32 v52, v52
	s_nop 0
	v_mul_f32_e32 v51, v51, v52
	v_mov_b32_e32 v52, v57
	v_mul_f32_e32 v56, v50, v51
	v_pk_mul_f32 v[50:51], v[52:53], v[156:157] op_sel_hi:[1,0]
	s_nop 0
	v_mul_f32_e32 v52, 0xbfb8aa3b, v51
	v_exp_f32_e32 v52, v52
	s_nop 0
	v_add_f32_e32 v52, 1.0, v52
	v_rcp_f32_e32 v52, v52
	s_nop 0
	v_mul_f32_e32 v51, v51, v52
	v_mul_f32_e32 v53, v50, v51
	v_cvt_pk_bf16_f32 v50, v62, v63
	v_cvt_pk_bf16_f32 v51, v64, v60
	v_cvt_pk_bf16_f32 v52, v58, v59
	v_cvt_pk_bf16_f32 v53, v56, v53
	global_store_dwordx4 v[54:55], v[50:53], off
	s_nop 1
	v_mov_b32_e32 v50, v46
	v_mov_b32_e32 v51, v42
	v_pk_mul_f32 v[50:51], v[50:51], v[152:153] op_sel_hi:[1,0]
	s_nop 0
	v_mul_f32_e32 v42, 0xbfb8aa3b, v51
	v_exp_f32_e32 v42, v42
	s_nop 0
	v_add_f32_e32 v42, 1.0, v42
	v_rcp_f32_e32 v42, v42
	s_nop 0
	v_mul_f32_e32 v42, v51, v42
	v_mul_f32_e32 v46, v50, v42
	v_mov_b32_e32 v42, v47
; __device__ __forceinline__ unsigned pk2(float lo, float hi) { return pg8::cvt_pk_bf16(lo, hi); }
;     __device__ __forceinline__ void operator()(const f32x4 (&acc)[2][2][4][2], const Unit& u, int wr, int wc, int fr, int fq) const {
;     ...
;             for (int m = 0; m < 4; ++m) {
;                 bf16_t* rowp = O + (size_t)(row0 + ai * 128 + m * 16) * FF + col0;
;                 const float rs = rsv[ai][m];
;                 float v[8];
; #pragma unroll
;                 for (int n = 0; n < 2; ++n)
; #pragma unroll
;                     for (int j = 0; j < 4; ++j) { const float g = acc[ai][0][m][n][j] * rs, up = acc[ai][1][m][n][j] * rs; v[n * 4 + j] = g * __builtin_amdgcn_rcpf(1.0f + __expf(-g)) * up; }
;                 u32x4v w; w.x = pk2(v[0], v[1]); w.y = pk2(v[2], v[3]); w.z = pk2(v[4], v[5]); w.w = pk2(v[6], v[7]);
;                 *(u32x4v*)rowp = w;
	v_pk_mul_f32 v[42:43], v[42:43], v[152:153] op_sel_hi:[1,0]
	s_nop 0
	v_mul_f32_e32 v47, 0xbfb8aa3b, v43
	v_exp_f32_e32 v47, v47
	s_nop 0
	v_add_f32_e32 v47, 1.0, v47
	v_rcp_f32_e32 v47, v47
	s_nop 0
	v_mul_f32_e32 v43, v43, v47
	v_mul_f32_e32 v47, v42, v43
	v_mov_b32_e32 v42, v48
	v_mov_b32_e32 v43, v44
	v_pk_mul_f32 v[42:43], v[42:43], v[152:153] op_sel_hi:[1,0]
	s_nop 0
	v_mul_f32_e32 v44, 0xbfb8aa3b, v43
	v_exp_f32_e32 v44, v44
	s_nop 0
	v_add_f32_e32 v44, 1.0, v44
	v_rcp_f32_e32 v44, v44
	s_nop 0
	v_mul_f32_e32 v43, v43, v44
	v_mov_b32_e32 v44, v49
	v_mul_f32_e32 v48, v42, v43
	v_pk_mul_f32 v[42:43], v[44:45], v[152:153] op_sel_hi:[1,0]
	s_nop 0
	v_mul_f32_e32 v44, 0xbfb8aa3b, v43
	v_exp_f32_e32 v44, v44
	s_nop 0
	v_add_f32_e32 v44, 1.0, v44
	v_rcp_f32_e32 v44, v44
	s_nop 0
	v_mul_f32_e32 v43, v43, v44
	v_mul_f32_e32 v44, v42, v43
	v_mov_b32_e32 v42, v38
	v_mov_b32_e32 v43, v34
	v_pk_mul_f32 v[42:43], v[42:43], v[152:153] op_sel_hi:[1,0]
	s_nop 0
	v_mul_f32_e32 v34, 0xbfb8aa3b, v43
	v_exp_f32_e32 v34, v34
	s_nop 0
	v_add_f32_e32 v34, 1.0, v34
	v_rcp_f32_e32 v34, v34
	s_nop 0
	v_mul_f32_e32 v34, v43, v34
	v_mul_f32_e32 v42, v42, v34
	v_mov_b32_e32 v34, v39
	v_pk_mul_f32 v[34:35], v[34:35], v[152:153] op_sel_hi:[1,0]
	s_nop 0
	v_mul_f32_e32 v38, 0xbfb8aa3b, v35
	v_exp_f32_e32 v38, v38
	s_nop 0
	v_add_f32_e32 v38, 1.0, v38
	v_rcp_f32_e32 v38, v38
	s_nop 0
	v_mul_f32_e32 v35, v35, v38
	v_mul_f32_e32 v43, v34, v35
	v_mov_b32_e32 v34, v40
	v_mov_b32_e32 v35, v36
	v_pk_mul_f32 v[34:35], v[34:35], v[152:153] op_sel_hi:[1,0]
	v_mad_i64_i32 v[38:39], s[56:57], v150, s85, v[144:145]
	v_mul_f32_e32 v36, 0xbfb8aa3b, v35
	v_exp_f32_e32 v36, v36
	s_nop 0
	v_add_f32_e32 v36, 1.0, v36
	v_rcp_f32_e32 v36, v36
	s_nop 0
	v_mul_f32_e32 v35, v35, v36
	v_mov_b32_e32 v36, v41
	v_mul_f32_e32 v40, v34, v35
	v_pk_mul_f32 v[34:35], v[36:37], v[152:153] op_sel_hi:[1,0]
	s_nop 0
	v_mul_f32_e32 v36, 0xbfb8aa3b, v35
	v_exp_f32_e32 v36, v36
	s_nop 0
	v_add_f32_e32 v36, 1.0, v36
	v_rcp_f32_e32 v36, v36
	s_nop 0
	v_mul_f32_e32 v35, v35, v36
	v_mul_f32_e32 v37, v34, v35
	v_cvt_pk_bf16_f32 v34, v46, v47
	v_cvt_pk_bf16_f32 v35, v48, v44
	v_cvt_pk_bf16_f32 v36, v42, v43
	v_cvt_pk_bf16_f32 v37, v40, v37
	global_store_dwordx4 v[38:39], v[34:37], off
	s_nop 1
	v_mov_b32_e32 v34, v30
	v_mov_b32_e32 v35, v26
	v_pk_mul_f32 v[34:35], v[34:35], v[148:149] op_sel_hi:[1,0]
	s_nop 0
	v_mul_f32_e32 v26, 0xbfb8aa3b, v35
	v_exp_f32_e32 v26, v26
	s_nop 0
	v_add_f32_e32 v26, 1.0, v26
	v_rcp_f32_e32 v26, v26
	s_nop 0
	v_mul_f32_e32 v26, v35, v26
	v_mul_f32_e32 v30, v34, v26
	v_mov_b32_e32 v26, v31
	v_pk_mul_f32 v[26:27], v[26:27], v[148:149] op_sel_hi:[1,0]
	s_nop 0
	v_mul_f32_e32 v31, 0xbfb8aa3b, v27
	v_exp_f32_e32 v31, v31
	s_nop 0
	v_add_f32_e32 v31, 1.0, v31
	v_rcp_f32_e32 v31, v31
	s_nop 0
	v_mul_f32_e32 v27, v27, v31
	v_mul_f32_e32 v31, v26, v27
	v_mov_b32_e32 v26, v32
	v_mov_b32_e32 v27, v28
	v_pk_mul_f32 v[26:27], v[26:27], v[148:149] op_sel_hi:[1,0]
	s_nop 0
	v_mul_f32_e32 v28, 0xbfb8aa3b, v27
	v_exp_f32_e32 v28, v28
	s_nop 0
	v_add_f32_e32 v28, 1.0, v28
	v_rcp_f32_e32 v28, v28
	s_nop 0
	v_mul_f32_e32 v27, v27, v28
	v_mov_b32_e32 v28, v33
	v_mul_f32_e32 v32, v26, v27
	v_pk_mul_f32 v[26:27], v[28:29], v[148:149] op_sel_hi:[1,0]
	s_nop 0
	v_mul_f32_e32 v28, 0xbfb8aa3b, v27
	v_exp_f32_e32 v28, v28
	s_nop 0
	v_add_f32_e32 v28, 1.0, v28
	v_rcp_f32_e32 v28, v28
	s_nop 0
	v_mul_f32_e32 v27, v27, v28
	v_mul_f32_e32 v28, v26, v27
	v_mov_b32_e32 v26, v22
	v_mov_b32_e32 v27, v18
	v_pk_mul_f32 v[26:27], v[26:27], v[148:149] op_sel_hi:[1,0]
	s_nop 0
	v_mul_f32_e32 v18, 0xbfb8aa3b, v27
	v_exp_f32_e32 v18, v18
	s_nop 0
	v_add_f32_e32 v18, 1.0, v18
	v_rcp_f32_e32 v18, v18
	s_nop 0
	v_mul_f32_e32 v18, v27, v18
; #define PG8_BAR __builtin_amdgcn_s_barrier()
; __device__ __forceinline__ unsigned pk2(float lo, float hi) { return pg8::cvt_pk_bf16(lo, hi); }
; template <class Epi, class Sched, bool ALIGN_EPI = false, bool SP2 = false>
; __device__ __forceinline__ void gemm_phase(PG8_LAS unsigned char* lds, const Gemm g, const Sched& S, const Epi& E) {
;     ...
;         if constexpr (ALIGN_EPI) { if (wr == 0) PG8_BAR; }
;         if constexpr (!Epi::AFTER_DRAIN) { E(acc, cur, wr, wc, fr, fq); S.done(cur); }
;         if (!has_next) break;
; #pragma unroll
;         for (int a = 0; a < 2; ++a)
; #pragma unroll
;             for (int b = 0; b < 2; ++b)
; #pragma unroll
;                 for (int m = 0; m < 4; ++m)
; #pragma unroll
;                     for (int n = 0; n < 2; ++n) acc[a][b][m][n] = (f32x4){0.f, 0.f, 0.f, 0.f};
;         cur = nxt; cA = nA; cB = nB; ++ui;
;         if constexpr (ALIGN_EPI) { if (wr == 1) PG8_BAR; }
;     }
;     __device__ __forceinline__ void operator()(const f32x4 (&acc)[2][2][4][2], const Unit& u, int wr, int wc, int fr, int fq) const {
;     ...
;             for (int m = 0; m < 4; ++m) {
;                 bf16_t* rowp = O + (size_t)(row0 + ai * 128 + m * 16) * FF + col0;
;                 const float rs = rsv[ai][m];
;                 float v[8];
; #pragma unroll
;                 for (int n = 0; n < 2; ++n)
; #pragma unroll
;                     for (int j = 0; j < 4; ++j) { const float g = acc[ai][0][m][n][j] * rs, up = acc[ai][1][m][n][j] * rs; v[n * 4 + j] = g * __builtin_amdgcn_rcpf(1.0f + __expf(-g)) * up; }
;                 u32x4v w; w.x = pk2(v[0], v[1]); w.y = pk2(v[2], v[3]); w.z = pk2(v[4], v[5]); w.w = pk2(v[6], v[7]);
;                 *(u32x4v*)rowp = w;
	v_mul_f32_e32 v26, v26, v18
	v_mov_b32_e32 v18, v23
	v_pk_mul_f32 v[18:19], v[18:19], v[148:149] op_sel_hi:[1,0]
	s_nop 0
	v_mul_f32_e32 v22, 0xbfb8aa3b, v19
	v_exp_f32_e32 v22, v22
	s_nop 0
	v_add_f32_e32 v22, 1.0, v22
	v_rcp_f32_e32 v22, v22
	s_nop 0
	v_mul_f32_e32 v19, v19, v22
	v_mul_f32_e32 v27, v18, v19
	v_mov_b32_e32 v18, v24
	v_mov_b32_e32 v19, v20
	v_pk_mul_f32 v[18:19], v[18:19], v[148:149] op_sel_hi:[1,0]
	v_mad_i64_i32 v[22:23], s[56:57], v142, s85, v[144:145]
	v_mul_f32_e32 v20, 0xbfb8aa3b, v19
	v_exp_f32_e32 v20, v20
	s_nop 0
	v_add_f32_e32 v20, 1.0, v20
	v_rcp_f32_e32 v20, v20
	s_nop 0
	v_mul_f32_e32 v19, v19, v20
	v_mov_b32_e32 v20, v25
	v_mul_f32_e32 v24, v18, v19
	v_pk_mul_f32 v[18:19], v[20:21], v[148:149] op_sel_hi:[1,0]
	s_nop 0
	v_mul_f32_e32 v20, 0xbfb8aa3b, v19
	v_exp_f32_e32 v20, v20
	s_nop 0
	v_add_f32_e32 v20, 1.0, v20
	v_rcp_f32_e32 v20, v20
	s_nop 0
	v_mul_f32_e32 v19, v19, v20
	v_mul_f32_e32 v21, v18, v19
	v_cvt_pk_bf16_f32 v18, v30, v31
	v_cvt_pk_bf16_f32 v19, v32, v28
	v_cvt_pk_bf16_f32 v20, v26, v27
	v_cvt_pk_bf16_f32 v21, v24, v21
	global_store_dwordx4 v[22:23], v[18:21], off
	s_nop 1
	v_mov_b32_e32 v18, v14
	v_mov_b32_e32 v19, v10
	v_pk_mul_f32 v[18:19], v[18:19], v[146:147] op_sel_hi:[1,0]
	s_nop 0
	v_mul_f32_e32 v10, 0xbfb8aa3b, v19
	v_exp_f32_e32 v10, v10
	s_nop 0
	v_add_f32_e32 v10, 1.0, v10
	v_rcp_f32_e32 v10, v10
	s_nop 0
	v_mul_f32_e32 v10, v19, v10
	v_mul_f32_e32 v14, v18, v10
	v_mov_b32_e32 v10, v15
	v_pk_mul_f32 v[10:11], v[10:11], v[146:147] op_sel_hi:[1,0]
	s_nop 0
	v_mul_f32_e32 v15, 0xbfb8aa3b, v11
	v_exp_f32_e32 v15, v15
	s_nop 0
	v_add_f32_e32 v15, 1.0, v15
	v_rcp_f32_e32 v15, v15
	s_nop 0
	v_mul_f32_e32 v11, v11, v15
	v_mul_f32_e32 v15, v10, v11
	v_mov_b32_e32 v10, v16
	v_mov_b32_e32 v11, v12
	v_pk_mul_f32 v[10:11], v[10:11], v[146:147] op_sel_hi:[1,0]
	s_nop 0
	v_mul_f32_e32 v12, 0xbfb8aa3b, v11
	v_exp_f32_e32 v12, v12
	s_nop 0
	v_add_f32_e32 v12, 1.0, v12
	v_rcp_f32_e32 v12, v12
	s_nop 0
	v_mul_f32_e32 v11, v11, v12
	v_mov_b32_e32 v12, v17
	v_mul_f32_e32 v16, v10, v11
	v_pk_mul_f32 v[10:11], v[12:13], v[146:147] op_sel_hi:[1,0]
	s_nop 0
	v_mul_f32_e32 v12, 0xbfb8aa3b, v11
	v_exp_f32_e32 v12, v12
	s_nop 0
	v_add_f32_e32 v12, 1.0, v12
	v_rcp_f32_e32 v12, v12
	s_nop 0
	v_mul_f32_e32 v11, v11, v12
	v_mul_f32_e32 v12, v10, v11
	v_mov_b32_e32 v10, v2
	v_mov_b32_e32 v11, v6
	v_pk_mul_f32 v[10:11], v[10:11], v[146:147] op_sel_hi:[1,0]
	v_mov_b32_e32 v6, v3
	v_mul_f32_e32 v2, 0xbfb8aa3b, v11
	v_exp_f32_e32 v2, v2
	s_nop 0
	v_add_f32_e32 v2, 1.0, v2
	v_rcp_f32_e32 v2, v2
	s_nop 0
	v_mul_f32_e32 v2, v11, v2
	v_mul_f32_e32 v10, v10, v2
	v_pk_mul_f32 v[2:3], v[6:7], v[146:147] op_sel_hi:[1,0]
	s_nop 0
	v_mul_f32_e32 v6, 0xbfb8aa3b, v3
	v_exp_f32_e32 v6, v6
	s_nop 0
	v_add_f32_e32 v6, 1.0, v6
	v_rcp_f32_e32 v6, v6
	s_nop 0
	v_mul_f32_e32 v3, v3, v6
	v_mul_f32_e32 v11, v2, v3
	v_mov_b32_e32 v2, v4
	v_mov_b32_e32 v3, v8
	v_pk_mul_f32 v[2:3], v[2:3], v[146:147] op_sel_hi:[1,0]
	v_mov_b32_e32 v8, v5
	v_mul_f32_e32 v4, 0xbfb8aa3b, v3
	v_exp_f32_e32 v4, v4
	v_mad_i64_i32 v[6:7], s[56:57], v140, s85, v[144:145]
	v_add_f32_e32 v4, 1.0, v4
	v_rcp_f32_e32 v4, v4
	s_nop 0
	v_mul_f32_e32 v3, v3, v4
	v_mul_f32_e32 v13, v2, v3
	v_pk_mul_f32 v[2:3], v[8:9], v[146:147] op_sel_hi:[1,0]
	s_nop 0
	v_mul_f32_e32 v4, 0xbfb8aa3b, v3
	v_exp_f32_e32 v4, v4
	s_nop 0
	v_add_f32_e32 v4, 1.0, v4
	v_rcp_f32_e32 v4, v4
	s_nop 0
	v_mul_f32_e32 v3, v3, v4
	v_mul_f32_e32 v5, v2, v3
	v_cvt_pk_bf16_f32 v2, v14, v15
	v_cvt_pk_bf16_f32 v3, v16, v12
	v_cvt_pk_bf16_f32 v4, v10, v11
	v_cvt_pk_bf16_f32 v5, v13, v5
	global_store_dwordx4 v[6:7], v[2:5], off
	s_cbranch_vccnz .LBB0_309
	s_andn2_b64 vcc, exec, s[38:39]
	s_cbranch_vccnz .LBB0_308
	s_barrier
	s_branch .LBB0_308

; __device__ __forceinline__ float bflo(unsigned w) { return __uint_as_float(w << 16); }
; __device__ __forceinline__ float bfhi(unsigned w) { return __uint_as_float(w & 0xffff0000u); }
; __device__ __forceinline__ unsigned pk2(float lo, float hi) { return pg8::cvt_pk_bf16(lo, hi); }
;     __device__ __forceinline__ void operator()(const f32x4 (&acc)[2][2][4][2], const Unit& u, int wr, int wc, int fr, int fq) const {
;     ...
;         const int row0 = u.pm * 256 + wr * 64 + fr, col0 = u.pn * 256 + wc * 32 + 4 * fq;
; #pragma unroll
;         for (int hb = 0; hb < 2; ++hb) {
;             u32x2v rin[4][4];
; #pragma unroll
;             for (int gg = 0; gg < 4; ++gg) { const int g = hb * 4 + gg; const size_t offn = (size_t)(row0 + (g >> 2) * 128 + (g & 3) * 16) * D + col0;
; #pragma unroll
;                 for (int k = 0; k < 4; ++k) rin[gg][k] = *(const u32x2v*)(in + offn + (k >> 1) * 128 + (k & 1) * 16); }
; #pragma unroll
;             for (int gg = 0; gg < 4; ++gg) {
;                 const int g = hb * 4 + gg, ai = g >> 2, m = g & 3, row = row0 + ai * 128 + m * 16;
;                 const size_t off = (size_t)row * D + col0;
;                 float ss = 0.f;
; #pragma unroll
;                 for (int k = 0; k < 4; ++k) { const int bj = k >> 1, n = k & 1; const size_t o = off + bj * 128 + n * 16; const f32x4 a = acc[ai][bj][m][n] * scale; const u32x2v w0 = rin[gg][k];
;                     f32x4 r; r[0] = bflo(w0.x) + a[0]; r[1] = bfhi(w0.x) + a[1]; r[2] = bflo(w0.y) + a[2]; r[3] = bfhi(w0.y) + a[3];
;                     u32x2v w; w.x = pk2(r[0], r[1]); w.y = pk2(r[2], r[3]); *(u32x2v*)(out + o) = w; ss += (r[0] * r[0] + r[1] * r[1]) + (r[2] * r[2] + r[3] * r[3]); }
;                 ss += __shfl_xor(ss, 16); ss += __shfl_xor(ss, 32);
;                 if (fq == 0) part[(ai * 128 + wr * 64 + m * 16 + fr) * 4 + wc] = ss;
.LBB0_398:
	s_lshl_b32 s15, s15, 8
	v_lshl_or_b32 v136, s14, 8, v171
	v_readlane_b32 s90, v251, 12
	v_add_u32_e32 v138, s15, v167
	v_ashrrev_i32_e32 v137, 31, v136
	s_mov_b64 s[56:57], s[12:13]
	s_mov_b32 s92, 0.5
	s_mov_b64 s[70:71], s[46:47]
	v_readlane_b32 s91, v251, 13
	v_lshlrev_b64 v[140:141], 1, v[136:137]
	v_ashrrev_i32_e32 v139, 31, v138
	v_lshlrev_b64 v[142:143], 11, v[138:139]
	v_lshl_add_u64 v[136:137], s[56:57], 0, v[140:141]
	v_lshl_add_u64 v[144:145], v[136:137], 0, v[142:143]
	global_load_dwordx2 v[174:175], v[144:145], off
	global_load_dwordx2 v[176:177], v[144:145], off offset:32
	global_load_dwordx2 v[178:179], v[144:145], off offset:256
	global_load_dwordx2 v[180:181], v[144:145], off offset:288
	v_or_b32_e32 v144, 16, v138
	v_or_b32_e32 v146, 32, v138
	v_or_b32_e32 v150, 48, v138
	v_ashrrev_i32_e32 v145, 31, v144
	v_ashrrev_i32_e32 v147, 31, v146
	v_ashrrev_i32_e32 v151, 31, v150
	v_lshlrev_b64 v[168:169], 11, v[144:145]
	v_lshlrev_b64 v[148:149], 11, v[146:147]
	v_pk_mul_f32 v[182:183], v[128:129], s[92:93] op_sel_hi:[1,0]
	v_pk_mul_f32 v[188:189], v[122:123], s[92:93] op_sel_hi:[1,0]
	v_pk_mul_f32 v[190:191], v[120:121], s[92:93] op_sel_hi:[1,0]
	v_pk_mul_f32 v[192:193], v[118:119], s[92:93] op_sel_hi:[1,0]
	v_lshl_add_u64 v[118:119], s[70:71], 0, v[140:141]
	v_lshlrev_b64 v[128:129], 11, v[150:151]
	v_lshl_add_u64 v[120:121], v[136:137], 0, v[168:169]
	v_lshl_add_u64 v[122:123], v[136:137], 0, v[148:149]
	v_pk_mul_f32 v[184:185], v[126:127], s[92:93] op_sel_hi:[1,0]
	v_pk_mul_f32 v[186:187], v[124:125], s[92:93] op_sel_hi:[1,0]
	v_lshl_add_u64 v[194:195], v[118:119], 0, v[142:143]
	v_lshl_add_u64 v[196:197], v[136:137], 0, v[128:129]
	global_load_dwordx2 v[156:157], v[120:121], off
	global_load_dwordx2 v[154:155], v[120:121], off offset:32
	global_load_dwordx2 v[152:153], v[120:121], off offset:256
	global_load_dwordx2 v[150:151], v[120:121], off offset:288
	global_load_dwordx2 v[146:147], v[122:123], off
	global_load_dwordx2 v[144:145], v[122:123], off offset:32
	global_load_dwordx2 v[142:143], v[122:123], off offset:256
	global_load_dwordx2 v[140:141], v[122:123], off offset:288
	global_load_dwordx2 v[126:127], v[196:197], off
	global_load_dwordx2 v[124:125], v[196:197], off offset:32
	s_nop 0
	global_load_dwordx2 v[122:123], v[196:197], off offset:256
	global_load_dwordx2 v[120:121], v[196:197], off offset:288
	v_pk_mul_f32 v[114:115], v[114:115], s[92:93] op_sel_hi:[1,0]
	v_pk_mul_f32 v[116:117], v[116:117], s[92:93] op_sel_hi:[1,0]
	s_waitcnt vmcnt(0) lgkmcnt(0)
	v_lshlrev_b32_e32 v196, 16, v174
	v_and_b32_e32 v174, 0xffff0000, v174
	v_lshlrev_b32_e32 v197, 16, v175
	v_and_b32_e32 v175, 0xffff0000, v175
	v_lshlrev_b32_e32 v198, 16, v176
	v_and_b32_e32 v176, 0xffff0000, v176
	v_lshlrev_b32_e32 v199, 16, v177
	v_and_b32_e32 v177, 0xffff0000, v177
	v_lshlrev_b32_e32 v201, 16, v179
	v_and_b32_e32 v179, 0xffff0000, v179
	v_add_f32_e32 v185, v185, v174
	v_add_f32_e32 v183, v183, v175
	v_add_f32_e32 v176, v189, v176
	v_add_f32_e32 v177, v187, v177
	v_add_f32_e32 v184, v184, v196
	v_add_f32_e32 v182, v182, v197
	v_add_f32_e32 v188, v188, v198
	v_add_f32_e32 v186, v186, v199
	v_add_f32_e32 v189, v190, v201
	v_add_f32_e32 v179, v191, v179
	v_cvt_pk_bf16_f32 v174, v184, v185
	v_cvt_pk_bf16_f32 v175, v182, v183
	v_mul_f32_e32 v185, v185, v185
	v_mul_f32_e32 v183, v183, v183
	v_mul_f32_e32 v190, v176, v176
	v_mul_f32_e32 v191, v177, v177
	v_lshlrev_b32_e32 v200, 16, v178
	v_and_b32_e32 v178, 0xffff0000, v178
	v_fmac_f32_e32 v185, v184, v184
	v_fmac_f32_e32 v183, v182, v182
	v_fmac_f32_e32 v190, v188, v188
	v_fmac_f32_e32 v191, v186, v186
	v_add_f32_e32 v178, v193, v178
	global_store_dwordx2 v[194:195], v[174:175], off
	v_cvt_pk_bf16_f32 v174, v188, v176
	v_add_f32_e32 v175, v185, v183
	v_add_f32_e32 v176, v190, v191
	v_add_f32_e32 v187, v192, v200
	v_mul_f32_e32 v192, v178, v178
	v_add_f32_e32 v175, v175, v176
	v_mul_f32_e32 v176, v179, v179
	v_fmac_f32_e32 v192, v187, v187
	v_fmac_f32_e32 v176, v189, v189
	v_add_f32_e32 v176, v192, v176
	v_add_f32_e32 v175, v175, v176
	v_lshlrev_b32_e32 v176, 16, v180
	v_add_f32_e32 v176, v114, v176
	v_and_b32_e32 v114, 0xffff0000, v180
	v_add_f32_e32 v180, v115, v114
	v_lshlrev_b32_e32 v114, 16, v181
	v_add_f32_e32 v182, v116, v114
	v_and_b32_e32 v114, 0xffff0000, v181
	v_add_f32_e32 v181, v117, v114
	v_mul_f32_e32 v114, v180, v180
	v_mul_f32_e32 v115, v181, v181
	v_fmac_f32_e32 v114, v176, v176
	v_fmac_f32_e32 v115, v182, v182
	v_add_f32_e32 v114, v114, v115
	v_and_b32_e32 v116, 64, v209
	v_add_f32_e32 v115, v175, v114
	v_xor_b32_e32 v114, 16, v209
	v_add_u32_e32 v117, 64, v116
	v_cmp_lt_i32_e32 vcc, v114, v117
	v_cvt_pk_bf16_f32 v175, v186, v177
	global_store_dwordx2 v[194:195], v[174:175], off offset:32
	v_cvt_pk_bf16_f32 v174, v187, v178
	v_cvt_pk_bf16_f32 v175, v189, v179
	global_store_dwordx2 v[194:195], v[174:175], off offset:256
	v_cndmask_b32_e32 v114, v209, v114, vcc
	v_lshlrev_b32_e32 v114, 2, v114
	ds_bpermute_b32 v116, v114, v115
	v_cvt_pk_bf16_f32 v174, v176, v180
	v_cvt_pk_bf16_f32 v175, v182, v181
	global_store_dwordx2 v[194:195], v[174:175], off offset:288
	s_waitcnt lgkmcnt(0)
	v_add_f32_e32 v116, v115, v116
	v_xor_b32_e32 v115, 32, v209
	v_cmp_lt_i32_e32 vcc, v115, v117
	s_nop 1
	v_cndmask_b32_e32 v115, v209, v115, vcc
	v_lshlrev_b32_e32 v115, 2, v115
	ds_bpermute_b32 v117, v115, v116
	s_and_saveexec_b64 s[70:71], s[40:41]
	s_cbranch_execz .LBB0_400
	s_waitcnt lgkmcnt(0)
	v_add_f32_e32 v116, v116, v117
	ds_write_b32 v172, v116
; __device__ __forceinline__ float bflo(unsigned w) { return __uint_as_float(w << 16); }
; __device__ __forceinline__ float bfhi(unsigned w) { return __uint_as_float(w & 0xffff0000u); }
; __device__ __forceinline__ unsigned pk2(float lo, float hi) { return pg8::cvt_pk_bf16(lo, hi); }
;     __device__ __forceinline__ void operator()(const f32x4 (&acc)[2][2][4][2], const Unit& u, int wr, int wc, int fr, int fq) const {
;     ...
;             for (int gg = 0; gg < 4; ++gg) {
;                 const int g = hb * 4 + gg, ai = g >> 2, m = g & 3, row = row0 + ai * 128 + m * 16;
;                 const size_t off = (size_t)row * D + col0;
;                 float ss = 0.f;
; #pragma unroll
;                 for (int k = 0; k < 4; ++k) { const int bj = k >> 1, n = k & 1; const size_t o = off + bj * 128 + n * 16; const f32x4 a = acc[ai][bj][m][n] * scale; const u32x2v w0 = rin[gg][k];
;                     f32x4 r; r[0] = bflo(w0.x) + a[0]; r[1] = bfhi(w0.x) + a[1]; r[2] = bflo(w0.y) + a[2]; r[3] = bfhi(w0.y) + a[3];
;                     u32x2v w; w.x = pk2(r[0], r[1]); w.y = pk2(r[2], r[3]); *(u32x2v*)(out + o) = w; ss += (r[0] * r[0] + r[1] * r[1]) + (r[2] * r[2] + r[3] * r[3]); }
;                 ss += __shfl_xor(ss, 16); ss += __shfl_xor(ss, 32);
;                 if (fq == 0) part[(ai * 128 + wr * 64 + m * 16 + fr) * 4 + wc] = ss;
.LBB0_400:
	s_or_b64 exec, exec, s[70:71]
	s_mov_b32 s93, s92
	s_waitcnt lgkmcnt(0)
	v_lshl_add_u64 v[116:117], v[118:119], 0, v[168:169]
	v_pk_mul_f32 v[110:111], v[110:111], s[92:93]
	v_lshlrev_b32_e32 v168, 16, v156
	s_mov_b32 s70, s92
	s_mov_b32 s71, s92
	v_add_f32_e32 v168, v110, v168
	v_and_b32_e32 v110, 0xffff0000, v156
	v_pk_mul_f32 v[112:113], v[112:113], s[70:71]
	v_add_f32_e32 v156, v111, v110
	v_lshlrev_b32_e32 v110, 16, v157
	v_add_f32_e32 v112, v112, v110
	v_and_b32_e32 v110, 0xffff0000, v157
	v_add_f32_e32 v113, v113, v110
	v_cvt_pk_bf16_f32 v110, v168, v156
	v_cvt_pk_bf16_f32 v111, v112, v113
	global_store_dwordx2 v[116:117], v[110:111], off
	v_mul_f32_e32 v110, v156, v156
	v_mul_f32_e32 v111, v113, v113
	v_fmac_f32_e32 v110, v168, v168
	v_fmac_f32_e32 v111, v112, v112
	v_add_f32_e32 v110, v110, v111
	v_pk_mul_f32 v[106:107], v[106:107], s[92:93]
	v_lshlrev_b32_e32 v111, 16, v154
	v_add_f32_e32 v111, v106, v111
	v_and_b32_e32 v106, 0xffff0000, v154
	v_pk_mul_f32 v[108:109], v[108:109], s[70:71]
	v_add_f32_e32 v107, v107, v106
	v_lshlrev_b32_e32 v106, 16, v155
	v_add_f32_e32 v108, v108, v106
	v_and_b32_e32 v106, 0xffff0000, v155
	v_add_f32_e32 v109, v109, v106
	v_cvt_pk_bf16_f32 v106, v111, v107
	v_mul_f32_e32 v107, v107, v107
	v_fmac_f32_e32 v107, v111, v111
	v_mul_f32_e32 v111, v109, v109
	v_fmac_f32_e32 v111, v108, v108
	v_add_f32_e32 v107, v107, v111
	v_add_f32_e32 v107, v110, v107
	v_pk_mul_f32 v[102:103], v[102:103], s[92:93]
	v_lshlrev_b32_e32 v110, 16, v152
	v_add_f32_e32 v102, v102, v110
	v_and_b32_e32 v110, 0xffff0000, v152
	v_pk_mul_f32 v[104:105], v[104:105], s[70:71]
	v_add_f32_e32 v103, v103, v110
	v_lshlrev_b32_e32 v110, 16, v153
	v_add_f32_e32 v104, v104, v110
	v_and_b32_e32 v110, 0xffff0000, v153
	v_add_f32_e32 v105, v105, v110
	v_mul_f32_e32 v110, v103, v103
	v_mul_f32_e32 v111, v105, v105
	v_fmac_f32_e32 v110, v102, v102
	v_fmac_f32_e32 v111, v104, v104
	v_add_f32_e32 v110, v110, v111
	v_add_f32_e32 v107, v107, v110
	v_pk_mul_f32 v[98:99], v[98:99], s[92:93]
	v_lshlrev_b32_e32 v110, 16, v150
	v_add_f32_e32 v110, v98, v110
	v_and_b32_e32 v98, 0xffff0000, v150
	v_pk_mul_f32 v[100:101], v[100:101], s[70:71]
	v_add_f32_e32 v111, v99, v98
	v_lshlrev_b32_e32 v98, 16, v151
	v_add_f32_e32 v112, v100, v98
	v_and_b32_e32 v98, 0xffff0000, v151
	v_add_f32_e32 v113, v101, v98
	v_mul_f32_e32 v98, v111, v111
	v_mul_f32_e32 v99, v113, v113
	v_fmac_f32_e32 v98, v110, v110
	v_fmac_f32_e32 v99, v112, v112
	v_add_f32_e32 v98, v98, v99
	v_add_f32_e32 v98, v107, v98
	ds_bpermute_b32 v99, v114, v98
	v_cvt_pk_bf16_f32 v107, v108, v109
	global_store_dwordx2 v[116:117], v[106:107], off offset:32
	v_cvt_pk_bf16_f32 v100, v102, v103
	v_cvt_pk_bf16_f32 v101, v104, v105
	s_waitcnt lgkmcnt(0)
	v_add_f32_e32 v98, v98, v99
	ds_bpermute_b32 v99, v115, v98
	global_store_dwordx2 v[116:117], v[100:101], off offset:256
	v_cvt_pk_bf16_f32 v100, v110, v111
	v_cvt_pk_bf16_f32 v101, v112, v113
	global_store_dwordx2 v[116:117], v[100:101], off offset:288
	s_and_saveexec_b64 vcc, s[40:41]
	s_cbranch_execz .LBB0_402
	s_waitcnt lgkmcnt(0)
	v_add_f32_e32 v98, v98, v99
	ds_write_b32 v172, v98 offset:256
.LBB0_402:
	s_or_b64 exec, exec, vcc
	v_pk_mul_f32 v[94:95], v[94:95], s[92:93]
	v_lshlrev_b32_e32 v100, 16, v146
	v_add_f32_e32 v100, v94, v100
	v_and_b32_e32 v94, 0xffff0000, v146
	v_pk_mul_f32 v[96:97], v[96:97], s[70:71]
	v_add_f32_e32 v101, v95, v94
	v_lshlrev_b32_e32 v94, 16, v147
	v_add_f32_e32 v96, v96, v94
	v_and_b32_e32 v94, 0xffff0000, v147
	s_waitcnt lgkmcnt(0)
	v_lshl_add_u64 v[98:99], v[118:119], 0, v[148:149]
	v_add_f32_e32 v97, v97, v94
	v_cvt_pk_bf16_f32 v94, v100, v101
	v_cvt_pk_bf16_f32 v95, v96, v97
	global_store_dwordx2 v[98:99], v[94:95], off
	v_mul_f32_e32 v94, v101, v101
	v_mul_f32_e32 v95, v97, v97
	v_fmac_f32_e32 v94, v100, v100
	v_fmac_f32_e32 v95, v96, v96
	v_add_f32_e32 v94, v94, v95
	v_pk_mul_f32 v[90:91], v[90:91], s[92:93]
	v_lshlrev_b32_e32 v95, 16, v144
	v_add_f32_e32 v95, v90, v95
	v_and_b32_e32 v90, 0xffff0000, v144
	v_pk_mul_f32 v[92:93], v[92:93], s[70:71]
	v_add_f32_e32 v91, v91, v90
	v_lshlrev_b32_e32 v90, 16, v145
	v_add_f32_e32 v92, v92, v90
	v_and_b32_e32 v90, 0xffff0000, v145
	v_add_f32_e32 v93, v93, v90
	v_cvt_pk_bf16_f32 v90, v95, v91
	v_mul_f32_e32 v91, v91, v91
	v_fmac_f32_e32 v91, v95, v95
	v_mul_f32_e32 v95, v93, v93
	v_fmac_f32_e32 v95, v92, v92
	v_add_f32_e32 v91, v91, v95
	v_add_f32_e32 v91, v94, v91
	v_pk_mul_f32 v[86:87], v[86:87], s[92:93]
	v_lshlrev_b32_e32 v94, 16, v142
	v_add_f32_e32 v86, v86, v94
	v_and_b32_e32 v94, 0xffff0000, v142
	v_pk_mul_f32 v[88:89], v[88:89], s[70:71]
	v_add_f32_e32 v87, v87, v94
	v_lshlrev_b32_e32 v94, 16, v143
	v_add_f32_e32 v88, v88, v94
	v_and_b32_e32 v94, 0xffff0000, v143
	v_add_f32_e32 v89, v89, v94
	v_mul_f32_e32 v94, v87, v87
	v_mul_f32_e32 v95, v89, v89
	v_fmac_f32_e32 v94, v86, v86
	v_fmac_f32_e32 v95, v88, v88
	v_add_f32_e32 v94, v94, v95
	v_add_f32_e32 v91, v91, v94
	v_pk_mul_f32 v[82:83], v[82:83], s[92:93]
	v_lshlrev_b32_e32 v94, 16, v140
	v_add_f32_e32 v94, v82, v94
	v_and_b32_e32 v82, 0xffff0000, v140
	v_pk_mul_f32 v[84:85], v[84:85], s[70:71]
	v_add_f32_e32 v95, v83, v82
	v_lshlrev_b32_e32 v82, 16, v141
	v_add_f32_e32 v96, v84, v82
	v_and_b32_e32 v82, 0xffff0000, v141
	v_add_f32_e32 v97, v85, v82
	v_mul_f32_e32 v82, v95, v95
	v_mul_f32_e32 v83, v97, v97
	v_fmac_f32_e32 v82, v94, v94
	v_fmac_f32_e32 v83, v96, v96
	v_add_f32_e32 v82, v82, v83
	v_add_f32_e32 v82, v91, v82
	ds_bpermute_b32 v83, v114, v82
	v_cvt_pk_bf16_f32 v91, v92, v93
	global_store_dwordx2 v[98:99], v[90:91], off offset:32
	v_cvt_pk_bf16_f32 v84, v86, v87
	v_cvt_pk_bf16_f32 v85, v88, v89
	s_waitcnt lgkmcnt(0)
	v_add_f32_e32 v82, v82, v83
	ds_bpermute_b32 v83, v115, v82
	global_store_dwordx2 v[98:99], v[84:85], off offset:256
	v_cvt_pk_bf16_f32 v84, v94, v95
	v_cvt_pk_bf16_f32 v85, v96, v97
	global_store_dwordx2 v[98:99], v[84:85], off offset:288
	s_and_saveexec_b64 s[70:71], s[40:41]
	s_cbranch_execz .LBB0_404
	s_waitcnt lgkmcnt(0)
	v_add_f32_e32 v82, v82, v83
	ds_write_b32 v172, v82 offset:512
; __device__ __forceinline__ float bflo(unsigned w) { return __uint_as_float(w << 16); }
; __device__ __forceinline__ float bfhi(unsigned w) { return __uint_as_float(w & 0xffff0000u); }
; __device__ __forceinline__ unsigned pk2(float lo, float hi) { return pg8::cvt_pk_bf16(lo, hi); }
;     __device__ __forceinline__ void operator()(const f32x4 (&acc)[2][2][4][2], const Unit& u, int wr, int wc, int fr, int fq) const {
;     ...
;             for (int gg = 0; gg < 4; ++gg) { const int g = hb * 4 + gg; const size_t offn = (size_t)(row0 + (g >> 2) * 128 + (g & 3) * 16) * D + col0;
; #pragma unroll
;                 for (int k = 0; k < 4; ++k) rin[gg][k] = *(const u32x2v*)(in + offn + (k >> 1) * 128 + (k & 1) * 16); }
; #pragma unroll
;             for (int gg = 0; gg < 4; ++gg) {
;                 const int g = hb * 4 + gg, ai = g >> 2, m = g & 3, row = row0 + ai * 128 + m * 16;
;                 const size_t off = (size_t)row * D + col0;
;                 float ss = 0.f;
; #pragma unroll
;                 for (int k = 0; k < 4; ++k) { const int bj = k >> 1, n = k & 1; const size_t o = off + bj * 128 + n * 16; const f32x4 a = acc[ai][bj][m][n] * scale; const u32x2v w0 = rin[gg][k];
;                     f32x4 r; r[0] = bflo(w0.x) + a[0]; r[1] = bfhi(w0.x) + a[1]; r[2] = bflo(w0.y) + a[2]; r[3] = bfhi(w0.y) + a[3];
;                     u32x2v w; w.x = pk2(r[0], r[1]); w.y = pk2(r[2], r[3]); *(u32x2v*)(out + o) = w; ss += (r[0] * r[0] + r[1] * r[1]) + (r[2] * r[2] + r[3] * r[3]); }
;                 ss += __shfl_xor(ss, 16); ss += __shfl_xor(ss, 32);
;                 if (fq == 0) part[(ai * 128 + wr * 64 + m * 16 + fr) * 4 + wc] = ss;
.LBB0_404:
	s_or_b64 exec, exec, s[70:71]
	v_pk_mul_f32 v[78:79], v[78:79], s[92:93]
	v_lshlrev_b32_e32 v84, 16, v126
	s_mov_b32 s70, s92
	s_mov_b32 s71, s92
	v_add_f32_e32 v84, v78, v84
	v_and_b32_e32 v78, 0xffff0000, v126
	v_pk_mul_f32 v[80:81], v[80:81], s[70:71]
	v_add_f32_e32 v85, v79, v78
	v_lshlrev_b32_e32 v78, 16, v127
	v_add_f32_e32 v80, v80, v78
	v_and_b32_e32 v78, 0xffff0000, v127
	s_waitcnt lgkmcnt(0)
	v_lshl_add_u64 v[82:83], v[118:119], 0, v[128:129]
	v_add_f32_e32 v81, v81, v78
	v_cvt_pk_bf16_f32 v78, v84, v85
	v_cvt_pk_bf16_f32 v79, v80, v81
	global_store_dwordx2 v[82:83], v[78:79], off
	v_mul_f32_e32 v78, v85, v85
	v_mul_f32_e32 v79, v81, v81
	v_fmac_f32_e32 v78, v84, v84
	v_fmac_f32_e32 v79, v80, v80
	v_add_f32_e32 v78, v78, v79
	v_pk_mul_f32 v[74:75], v[74:75], s[92:93]
	v_lshlrev_b32_e32 v79, 16, v124
	v_add_f32_e32 v79, v74, v79
	v_and_b32_e32 v74, 0xffff0000, v124
	v_pk_mul_f32 v[76:77], v[76:77], s[70:71]
	v_add_f32_e32 v75, v75, v74
	v_lshlrev_b32_e32 v74, 16, v125
	v_add_f32_e32 v76, v76, v74
	v_and_b32_e32 v74, 0xffff0000, v125
	v_add_f32_e32 v77, v77, v74
	v_cvt_pk_bf16_f32 v74, v79, v75
	v_mul_f32_e32 v75, v75, v75
	v_fmac_f32_e32 v75, v79, v79
	v_mul_f32_e32 v79, v77, v77
	v_fmac_f32_e32 v79, v76, v76
	v_add_f32_e32 v75, v75, v79
	v_add_f32_e32 v75, v78, v75
	v_pk_mul_f32 v[70:71], v[70:71], s[92:93]
	v_lshlrev_b32_e32 v78, 16, v122
	v_add_f32_e32 v70, v70, v78
	v_and_b32_e32 v78, 0xffff0000, v122
	v_pk_mul_f32 v[72:73], v[72:73], s[70:71]
	v_add_f32_e32 v71, v71, v78
	v_lshlrev_b32_e32 v78, 16, v123
	v_add_f32_e32 v72, v72, v78
	v_and_b32_e32 v78, 0xffff0000, v123
	v_add_f32_e32 v73, v73, v78
	v_mul_f32_e32 v78, v71, v71
	v_mul_f32_e32 v79, v73, v73
	v_fmac_f32_e32 v78, v70, v70
	v_fmac_f32_e32 v79, v72, v72
	v_add_f32_e32 v78, v78, v79
	v_add_f32_e32 v75, v75, v78
	v_pk_mul_f32 v[66:67], v[66:67], s[92:93]
	v_lshlrev_b32_e32 v78, 16, v120
	v_add_f32_e32 v78, v66, v78
	v_and_b32_e32 v66, 0xffff0000, v120
	v_pk_mul_f32 v[68:69], v[68:69], s[70:71]
	v_add_f32_e32 v79, v67, v66
	v_lshlrev_b32_e32 v66, 16, v121
	v_add_f32_e32 v80, v68, v66
	v_and_b32_e32 v66, 0xffff0000, v121
	v_add_f32_e32 v81, v69, v66
	v_mul_f32_e32 v66, v79, v79
	v_mul_f32_e32 v67, v81, v81
	v_fmac_f32_e32 v66, v78, v78
	v_fmac_f32_e32 v67, v80, v80
	v_add_f32_e32 v66, v66, v67
	v_add_f32_e32 v66, v75, v66
	ds_bpermute_b32 v67, v114, v66
	v_cvt_pk_bf16_f32 v75, v76, v77
	global_store_dwordx2 v[82:83], v[74:75], off offset:32
	v_cvt_pk_bf16_f32 v68, v70, v71
	v_cvt_pk_bf16_f32 v69, v72, v73
	s_waitcnt lgkmcnt(0)
	v_add_f32_e32 v66, v66, v67
	ds_bpermute_b32 v67, v115, v66
	global_store_dwordx2 v[82:83], v[68:69], off offset:256
	v_cvt_pk_bf16_f32 v68, v78, v79
	v_cvt_pk_bf16_f32 v69, v80, v81
	global_store_dwordx2 v[82:83], v[68:69], off offset:288
	s_and_saveexec_b64 vcc, s[40:41]
	s_cbranch_execz .LBB0_406
	s_waitcnt lgkmcnt(0)
	v_add_f32_e32 v66, v66, v67
	ds_write_b32 v172, v66 offset:768
.LBB0_406:
	s_or_b64 exec, exec, vcc
	s_waitcnt lgkmcnt(0)
	v_lshlrev_b64 v[66:67], 11, v[138:139]
	v_lshl_add_u64 v[98:99], v[66:67], 0, s[88:89]
	v_lshl_add_u64 v[68:69], v[136:137], 0, v[98:99]
	global_load_dwordx2 v[102:103], v[68:69], off
	global_load_dwordx2 v[104:105], v[68:69], off offset:32
	global_load_dwordx2 v[100:101], v[68:69], off offset:256
	global_load_dwordx2 v[96:97], v[68:69], off offset:288
	s_mov_b64 s[56:57], 0x48000
	v_lshl_add_u64 v[94:95], v[66:67], 0, s[56:57]
	s_mov_b64 s[56:57], 0x50000
	v_lshl_add_u64 v[84:85], v[66:67], 0, s[56:57]
	s_mov_b64 s[56:57], 0x58000
	v_lshl_add_u64 v[68:69], v[136:137], 0, v[94:95]
	v_lshl_add_u64 v[70:71], v[66:67], 0, s[56:57]
	global_load_dwordx2 v[92:93], v[68:69], off
	global_load_dwordx2 v[90:91], v[68:69], off offset:32
	global_load_dwordx2 v[88:89], v[68:69], off offset:256
	global_load_dwordx2 v[86:87], v[68:69], off offset:288
	v_lshl_add_u64 v[68:69], v[136:137], 0, v[84:85]
	v_lshl_add_u64 v[66:67], v[136:137], 0, v[70:71]
	global_load_dwordx2 v[82:83], v[68:69], off
	global_load_dwordx2 v[80:81], v[68:69], off offset:32
	global_load_dwordx2 v[78:79], v[68:69], off offset:256
	global_load_dwordx2 v[74:75], v[68:69], off offset:288
	global_load_dwordx2 v[76:77], v[66:67], off
	global_load_dwordx2 v[72:73], v[66:67], off offset:32
	s_nop 0
	global_load_dwordx2 v[68:69], v[66:67], off offset:256
	s_nop 0
	global_load_dwordx2 v[66:67], v[66:67], off offset:288
	v_pk_mul_f32 v[62:63], v[62:63], s[92:93]
	v_pk_mul_f32 v[64:65], v[64:65], s[70:71]
	v_lshl_add_u64 v[98:99], v[118:119], 0, v[98:99]
	v_pk_mul_f32 v[58:59], v[58:59], s[92:93]
	v_pk_mul_f32 v[60:61], v[60:61], s[70:71]
	v_pk_mul_f32 v[54:55], v[54:55], s[92:93]
	v_pk_mul_f32 v[56:57], v[56:57], s[70:71]
	v_pk_mul_f32 v[50:51], v[50:51], s[92:93]
	v_pk_mul_f32 v[52:53], v[52:53], s[70:71]
	s_waitcnt vmcnt(0) lgkmcnt(0)
; __device__ __forceinline__ float bflo(unsigned w) { return __uint_as_float(w << 16); }
; __device__ __forceinline__ float bfhi(unsigned w) { return __uint_as_float(w & 0xffff0000u); }
; __device__ __forceinline__ unsigned pk2(float lo, float hi) { return pg8::cvt_pk_bf16(lo, hi); }
;     __device__ __forceinline__ void operator()(const f32x4 (&acc)[2][2][4][2], const Unit& u, int wr, int wc, int fr, int fq) const {
;     ...
;             for (int gg = 0; gg < 4; ++gg) {
;                 const int g = hb * 4 + gg, ai = g >> 2, m = g & 3, row = row0 + ai * 128 + m * 16;
;                 const size_t off = (size_t)row * D + col0;
;                 float ss = 0.f;
; #pragma unroll
;                 for (int k = 0; k < 4; ++k) { const int bj = k >> 1, n = k & 1; const size_t o = off + bj * 128 + n * 16; const f32x4 a = acc[ai][bj][m][n] * scale; const u32x2v w0 = rin[gg][k];
;                     f32x4 r; r[0] = bflo(w0.x) + a[0]; r[1] = bfhi(w0.x) + a[1]; r[2] = bflo(w0.y) + a[2]; r[3] = bfhi(w0.y) + a[3];
;                     u32x2v w; w.x = pk2(r[0], r[1]); w.y = pk2(r[2], r[3]); *(u32x2v*)(out + o) = w; ss += (r[0] * r[0] + r[1] * r[1]) + (r[2] * r[2] + r[3] * r[3]); }
;                 ss += __shfl_xor(ss, 16); ss += __shfl_xor(ss, 32);
;                 if (fq == 0) part[(ai * 128 + wr * 64 + m * 16 + fr) * 4 + wc] = ss;
	v_lshlrev_b32_e32 v106, 16, v102
	v_add_f32_e32 v106, v62, v106
	v_and_b32_e32 v62, 0xffff0000, v102
	v_add_f32_e32 v102, v63, v62
	v_lshlrev_b32_e32 v62, 16, v103
	v_add_f32_e32 v64, v64, v62
	v_and_b32_e32 v62, 0xffff0000, v103
	v_add_f32_e32 v65, v65, v62
	v_cvt_pk_bf16_f32 v62, v106, v102
	v_cvt_pk_bf16_f32 v63, v64, v65
	global_store_dwordx2 v[98:99], v[62:63], off
	v_mul_f32_e32 v62, v102, v102
	v_mul_f32_e32 v63, v65, v65
	v_fmac_f32_e32 v62, v106, v106
	v_fmac_f32_e32 v63, v64, v64
	v_add_f32_e32 v62, v62, v63
	v_lshlrev_b32_e32 v63, 16, v104
	v_add_f32_e32 v63, v58, v63
	v_and_b32_e32 v58, 0xffff0000, v104
	v_add_f32_e32 v64, v59, v58
	v_lshlrev_b32_e32 v58, 16, v105
	v_add_f32_e32 v60, v60, v58
	v_and_b32_e32 v58, 0xffff0000, v105
	v_add_f32_e32 v61, v61, v58
	v_cvt_pk_bf16_f32 v58, v63, v64
	v_cvt_pk_bf16_f32 v59, v60, v61
	global_store_dwordx2 v[98:99], v[58:59], off offset:32
	v_mul_f32_e32 v58, v64, v64
	v_mul_f32_e32 v59, v61, v61
	v_fmac_f32_e32 v58, v63, v63
	v_fmac_f32_e32 v59, v60, v60
	v_add_f32_e32 v58, v58, v59
	v_lshlrev_b32_e32 v59, 16, v100
	v_add_f32_e32 v59, v54, v59
	v_and_b32_e32 v54, 0xffff0000, v100
	v_add_f32_e32 v60, v55, v54
	v_lshlrev_b32_e32 v54, 16, v101
	v_add_f32_e32 v56, v56, v54
	v_and_b32_e32 v54, 0xffff0000, v101
	v_add_f32_e32 v57, v57, v54
	v_cvt_pk_bf16_f32 v54, v59, v60
	v_cvt_pk_bf16_f32 v55, v56, v57
	global_store_dwordx2 v[98:99], v[54:55], off offset:256
	v_mul_f32_e32 v54, v60, v60
	v_mul_f32_e32 v55, v57, v57
	v_fmac_f32_e32 v54, v59, v59
	v_fmac_f32_e32 v55, v56, v56
	v_add_f32_e32 v54, v54, v55
	v_lshlrev_b32_e32 v55, 16, v96
	v_add_f32_e32 v55, v50, v55
	v_and_b32_e32 v50, 0xffff0000, v96
	v_add_f32_e32 v56, v51, v50
	v_lshlrev_b32_e32 v50, 16, v97
	v_add_f32_e32 v52, v52, v50
	v_and_b32_e32 v50, 0xffff0000, v97
	v_add_f32_e32 v53, v53, v50
	v_cvt_pk_bf16_f32 v50, v55, v56
	v_cvt_pk_bf16_f32 v51, v52, v53
	global_store_dwordx2 v[98:99], v[50:51], off offset:288
	v_mul_f32_e32 v50, v56, v56
	v_mul_f32_e32 v51, v53, v53
	v_add_f32_e32 v58, v62, v58
	v_fmac_f32_e32 v50, v55, v55
	v_fmac_f32_e32 v51, v52, v52
	v_add_f32_e32 v54, v58, v54
	v_add_f32_e32 v50, v50, v51
	v_add_f32_e32 v50, v54, v50
	ds_bpermute_b32 v51, v114, v50
	s_waitcnt lgkmcnt(0)
	v_add_f32_e32 v50, v50, v51
	ds_bpermute_b32 v51, v115, v50
	s_and_saveexec_b64 s[70:71], s[40:41]
	s_cbranch_execz .LBB0_408
	s_waitcnt lgkmcnt(0)
	v_add_f32_e32 v50, v50, v51
	ds_write_b32 v172, v50 offset:2048
.LBB0_408:
	s_or_b64 exec, exec, s[70:71]
	v_pk_mul_f32 v[46:47], v[46:47], s[92:93]
	v_lshlrev_b32_e32 v52, 16, v92
	s_mov_b32 s70, s92
	s_mov_b32 s71, s92
	v_add_f32_e32 v52, v46, v52
	v_and_b32_e32 v46, 0xffff0000, v92
	v_pk_mul_f32 v[48:49], v[48:49], s[70:71]
	v_add_f32_e32 v53, v47, v46
	v_lshlrev_b32_e32 v46, 16, v93
	v_add_f32_e32 v48, v48, v46
	v_and_b32_e32 v46, 0xffff0000, v93
	s_waitcnt lgkmcnt(0)
	v_lshl_add_u64 v[50:51], v[118:119], 0, v[94:95]
	v_add_f32_e32 v49, v49, v46
	v_cvt_pk_bf16_f32 v46, v52, v53
	v_cvt_pk_bf16_f32 v47, v48, v49
	global_store_dwordx2 v[50:51], v[46:47], off
	v_mul_f32_e32 v46, v53, v53
	v_mul_f32_e32 v47, v49, v49
	v_fmac_f32_e32 v46, v52, v52
	v_fmac_f32_e32 v47, v48, v48
	v_add_f32_e32 v46, v46, v47
	v_pk_mul_f32 v[42:43], v[42:43], s[92:93]
	v_lshlrev_b32_e32 v47, 16, v90
	v_add_f32_e32 v47, v42, v47
	v_and_b32_e32 v42, 0xffff0000, v90
	v_pk_mul_f32 v[44:45], v[44:45], s[70:71]
	v_add_f32_e32 v43, v43, v42
	v_lshlrev_b32_e32 v42, 16, v91
	v_add_f32_e32 v44, v44, v42
	v_and_b32_e32 v42, 0xffff0000, v91
	v_add_f32_e32 v45, v45, v42
	v_cvt_pk_bf16_f32 v42, v47, v43
	v_mul_f32_e32 v43, v43, v43
	v_fmac_f32_e32 v43, v47, v47
	v_mul_f32_e32 v47, v45, v45
	v_fmac_f32_e32 v47, v44, v44
	v_add_f32_e32 v43, v43, v47
	v_add_f32_e32 v43, v46, v43
	v_pk_mul_f32 v[38:39], v[38:39], s[92:93]
	v_lshlrev_b32_e32 v46, 16, v88
	v_add_f32_e32 v38, v38, v46
	v_and_b32_e32 v46, 0xffff0000, v88
	v_pk_mul_f32 v[40:41], v[40:41], s[70:71]
	v_add_f32_e32 v39, v39, v46
	v_lshlrev_b32_e32 v46, 16, v89
	v_add_f32_e32 v40, v40, v46
	v_and_b32_e32 v46, 0xffff0000, v89
	v_add_f32_e32 v41, v41, v46
	v_mul_f32_e32 v46, v39, v39
	v_mul_f32_e32 v47, v41, v41
	v_fmac_f32_e32 v46, v38, v38
	v_fmac_f32_e32 v47, v40, v40
	v_add_f32_e32 v46, v46, v47
	v_add_f32_e32 v43, v43, v46
	v_pk_mul_f32 v[34:35], v[34:35], s[92:93]
	v_lshlrev_b32_e32 v46, 16, v86
	v_add_f32_e32 v46, v34, v46
	v_and_b32_e32 v34, 0xffff0000, v86
	v_pk_mul_f32 v[36:37], v[36:37], s[70:71]
	v_add_f32_e32 v47, v35, v34
	v_lshlrev_b32_e32 v34, 16, v87
	v_add_f32_e32 v48, v36, v34
	v_and_b32_e32 v34, 0xffff0000, v87
	v_add_f32_e32 v49, v37, v34
	v_mul_f32_e32 v34, v47, v47
	v_mul_f32_e32 v35, v49, v49
	v_fmac_f32_e32 v34, v46, v46
	v_fmac_f32_e32 v35, v48, v48
	v_add_f32_e32 v34, v34, v35
	v_add_f32_e32 v34, v43, v34
	ds_bpermute_b32 v35, v114, v34
	v_cvt_pk_bf16_f32 v43, v44, v45
	global_store_dwordx2 v[50:51], v[42:43], off offset:32
	v_cvt_pk_bf16_f32 v36, v38, v39
	v_cvt_pk_bf16_f32 v37, v40, v41
	s_waitcnt lgkmcnt(0)
	v_add_f32_e32 v34, v34, v35
	ds_bpermute_b32 v35, v115, v34
	global_store_dwordx2 v[50:51], v[36:37], off offset:256
	v_cvt_pk_bf16_f32 v36, v46, v47
	v_cvt_pk_bf16_f32 v37, v48, v49
	global_store_dwordx2 v[50:51], v[36:37], off offset:288
	s_and_saveexec_b64 vcc, s[40:41]
	s_cbranch_execz .LBB0_410
	s_waitcnt lgkmcnt(0)
	v_add_f32_e32 v34, v34, v35
	ds_write_b32 v172, v34 offset:2304
; #define LAS __attribute__((address_space(3)))
; __device__ __forceinline__ float bflo(unsigned w) { return __uint_as_float(w << 16); }
; __device__ __forceinline__ float bfhi(unsigned w) { return __uint_as_float(w & 0xffff0000u); }
; __device__ __forceinline__ unsigned pk2(float lo, float hi) { return pg8::cvt_pk_bf16(lo, hi); }
;     __device__ __forceinline__ void operator()(const f32x4 (&acc)[2][2][4][2], const Unit& u, int wr, int wc, int fr, int fq) const {
;     ...
;             for (int gg = 0; gg < 4; ++gg) {
;                 const int g = hb * 4 + gg, ai = g >> 2, m = g & 3, row = row0 + ai * 128 + m * 16;
;                 const size_t off = (size_t)row * D + col0;
;                 float ss = 0.f;
; #pragma unroll
;                 for (int k = 0; k < 4; ++k) { const int bj = k >> 1, n = k & 1; const size_t o = off + bj * 128 + n * 16; const f32x4 a = acc[ai][bj][m][n] * scale; const u32x2v w0 = rin[gg][k];
;                     f32x4 r; r[0] = bflo(w0.x) + a[0]; r[1] = bfhi(w0.x) + a[1]; r[2] = bflo(w0.y) + a[2]; r[3] = bfhi(w0.y) + a[3];
;                     u32x2v w; w.x = pk2(r[0], r[1]); w.y = pk2(r[2], r[3]); *(u32x2v*)(out + o) = w; ss += (r[0] * r[0] + r[1] * r[1]) + (r[2] * r[2] + r[3] * r[3]); }
;                 ss += __shfl_xor(ss, 16); ss += __shfl_xor(ss, 32);
;                 if (fq == 0) part[(ai * 128 + wr * 64 + m * 16 + fr) * 4 + wc] = ss;
;             }
;         }
;         asm volatile("s_waitcnt lgkmcnt(0)" ::: "memory"); __builtin_amdgcn_s_barrier(); asm volatile("" ::: "memory");
;         { int t = threadIdx.x; asm volatile("" : "+v"(t)); if (t < 256) { const f32x4 p = *(const LAS f32x4*)(part + t * 4); rss[(size_t)(u.pm * 256 + t) * 4 + u.pn] = (p[0] + p[1]) + (p[2] + p[3]); } }
.LBB0_410:
	s_or_b64 exec, exec, vcc
	v_pk_mul_f32 v[30:31], v[30:31], s[92:93]
	v_lshlrev_b32_e32 v36, 16, v82
	v_add_f32_e32 v36, v30, v36
	v_and_b32_e32 v30, 0xffff0000, v82
	v_pk_mul_f32 v[32:33], v[32:33], s[70:71]
	v_add_f32_e32 v37, v31, v30
	v_lshlrev_b32_e32 v30, 16, v83
	v_add_f32_e32 v32, v32, v30
	v_and_b32_e32 v30, 0xffff0000, v83
	s_waitcnt lgkmcnt(0)
	v_lshl_add_u64 v[34:35], v[118:119], 0, v[84:85]
	v_add_f32_e32 v33, v33, v30
	v_cvt_pk_bf16_f32 v30, v36, v37
	v_cvt_pk_bf16_f32 v31, v32, v33
	global_store_dwordx2 v[34:35], v[30:31], off
	v_mul_f32_e32 v30, v37, v37
	v_mul_f32_e32 v31, v33, v33
	v_fmac_f32_e32 v30, v36, v36
	v_fmac_f32_e32 v31, v32, v32
	v_add_f32_e32 v30, v30, v31
	v_pk_mul_f32 v[26:27], v[26:27], s[92:93]
	v_lshlrev_b32_e32 v31, 16, v80
	v_add_f32_e32 v31, v26, v31
	v_and_b32_e32 v26, 0xffff0000, v80
	v_pk_mul_f32 v[28:29], v[28:29], s[70:71]
	v_add_f32_e32 v27, v27, v26
	v_lshlrev_b32_e32 v26, 16, v81
	v_add_f32_e32 v28, v28, v26
	v_and_b32_e32 v26, 0xffff0000, v81
	v_add_f32_e32 v29, v29, v26
	v_cvt_pk_bf16_f32 v26, v31, v27
	v_mul_f32_e32 v27, v27, v27
	v_fmac_f32_e32 v27, v31, v31
	v_mul_f32_e32 v31, v29, v29
	v_fmac_f32_e32 v31, v28, v28
	v_add_f32_e32 v27, v27, v31
	v_add_f32_e32 v27, v30, v27
	v_pk_mul_f32 v[22:23], v[22:23], s[92:93]
	v_lshlrev_b32_e32 v30, 16, v78
	v_add_f32_e32 v22, v22, v30
	v_and_b32_e32 v30, 0xffff0000, v78
	v_pk_mul_f32 v[24:25], v[24:25], s[70:71]
	v_add_f32_e32 v23, v23, v30
	v_lshlrev_b32_e32 v30, 16, v79
	v_add_f32_e32 v24, v24, v30
	v_and_b32_e32 v30, 0xffff0000, v79
	v_add_f32_e32 v25, v25, v30
	v_mul_f32_e32 v30, v23, v23
	v_mul_f32_e32 v31, v25, v25
	v_fmac_f32_e32 v30, v22, v22
	v_fmac_f32_e32 v31, v24, v24
	v_add_f32_e32 v30, v30, v31
	v_add_f32_e32 v27, v27, v30
	v_pk_mul_f32 v[18:19], v[18:19], s[92:93]
	v_lshlrev_b32_e32 v30, 16, v74
	v_add_f32_e32 v30, v18, v30
	v_and_b32_e32 v18, 0xffff0000, v74
	v_pk_mul_f32 v[20:21], v[20:21], s[70:71]
	v_add_f32_e32 v31, v19, v18
	v_lshlrev_b32_e32 v18, 16, v75
	v_add_f32_e32 v32, v20, v18
	v_and_b32_e32 v18, 0xffff0000, v75
	v_add_f32_e32 v33, v21, v18
	v_mul_f32_e32 v18, v31, v31
	v_mul_f32_e32 v19, v33, v33
	v_fmac_f32_e32 v18, v30, v30
	v_fmac_f32_e32 v19, v32, v32
	v_add_f32_e32 v18, v18, v19
	v_add_f32_e32 v18, v27, v18
	ds_bpermute_b32 v19, v114, v18
	v_cvt_pk_bf16_f32 v27, v28, v29
	global_store_dwordx2 v[34:35], v[26:27], off offset:32
	v_cvt_pk_bf16_f32 v20, v22, v23
	v_cvt_pk_bf16_f32 v21, v24, v25
	s_waitcnt lgkmcnt(0)
	v_add_f32_e32 v18, v18, v19
	ds_bpermute_b32 v19, v115, v18
	global_store_dwordx2 v[34:35], v[20:21], off offset:256
	v_cvt_pk_bf16_f32 v20, v30, v31
	v_cvt_pk_bf16_f32 v21, v32, v33
	global_store_dwordx2 v[34:35], v[20:21], off offset:288
	s_and_saveexec_b64 s[70:71], s[40:41]
	s_cbranch_execz .LBB0_412
	s_waitcnt lgkmcnt(0)
	v_add_f32_e32 v18, v18, v19
	ds_write_b32 v172, v18 offset:2560
.LBB0_412:
	s_or_b64 exec, exec, s[70:71]
	v_pk_mul_f32 v[14:15], v[14:15], s[92:93]
	v_lshlrev_b32_e32 v20, 16, v76
	s_mov_b32 s56, s92
	s_mov_b32 s57, s92
	v_add_f32_e32 v20, v14, v20
	v_and_b32_e32 v14, 0xffff0000, v76
	v_pk_mul_f32 v[16:17], v[16:17], s[56:57]
	v_add_f32_e32 v21, v15, v14
	v_lshlrev_b32_e32 v14, 16, v77
	v_add_f32_e32 v16, v16, v14
	v_and_b32_e32 v14, 0xffff0000, v77
	s_waitcnt lgkmcnt(0)
	v_lshl_add_u64 v[18:19], v[118:119], 0, v[70:71]
	v_add_f32_e32 v17, v17, v14
	v_cvt_pk_bf16_f32 v14, v20, v21
	v_cvt_pk_bf16_f32 v15, v16, v17
	global_store_dwordx2 v[18:19], v[14:15], off
	v_mul_f32_e32 v14, v21, v21
	v_mul_f32_e32 v15, v17, v17
	v_fmac_f32_e32 v14, v20, v20
	v_fmac_f32_e32 v15, v16, v16
	v_add_f32_e32 v14, v14, v15
	v_pk_mul_f32 v[10:11], v[10:11], s[92:93]
	v_lshlrev_b32_e32 v15, 16, v72
	v_add_f32_e32 v15, v10, v15
	v_and_b32_e32 v10, 0xffff0000, v72
	v_pk_mul_f32 v[12:13], v[12:13], s[56:57]
	v_add_f32_e32 v11, v11, v10
	v_lshlrev_b32_e32 v10, 16, v73
	v_add_f32_e32 v12, v12, v10
	v_and_b32_e32 v10, 0xffff0000, v73
	v_add_f32_e32 v13, v13, v10
	v_cvt_pk_bf16_f32 v10, v15, v11
	v_mul_f32_e32 v11, v11, v11
	v_fmac_f32_e32 v11, v15, v15
	v_mul_f32_e32 v15, v13, v13
	v_fmac_f32_e32 v15, v12, v12
	v_add_f32_e32 v11, v11, v15
	v_add_f32_e32 v11, v14, v11
	v_pk_mul_f32 v[6:7], v[6:7], s[92:93]
	v_lshlrev_b32_e32 v14, 16, v68
	v_add_f32_e32 v6, v6, v14
	v_and_b32_e32 v14, 0xffff0000, v68
	v_pk_mul_f32 v[8:9], v[8:9], s[56:57]
	v_add_f32_e32 v7, v7, v14
	v_lshlrev_b32_e32 v14, 16, v69
	v_add_f32_e32 v8, v8, v14
	v_and_b32_e32 v14, 0xffff0000, v69
	v_add_f32_e32 v9, v9, v14
	v_mul_f32_e32 v14, v7, v7
	v_mul_f32_e32 v15, v9, v9
	v_fmac_f32_e32 v14, v6, v6
	v_fmac_f32_e32 v15, v8, v8
	v_add_f32_e32 v14, v14, v15
	v_add_f32_e32 v11, v11, v14
	v_pk_mul_f32 v[2:3], v[2:3], s[92:93]
	v_lshlrev_b32_e32 v14, 16, v66
	v_add_f32_e32 v14, v2, v14
	v_and_b32_e32 v2, 0xffff0000, v66
	v_pk_mul_f32 v[4:5], v[4:5], s[56:57]
	v_add_f32_e32 v15, v3, v2
	v_lshlrev_b32_e32 v2, 16, v67
	v_add_f32_e32 v16, v4, v2
	v_and_b32_e32 v2, 0xffff0000, v67
	v_add_f32_e32 v17, v5, v2
	v_mul_f32_e32 v2, v15, v15
	v_mul_f32_e32 v3, v17, v17
	v_fmac_f32_e32 v2, v14, v14
	v_fmac_f32_e32 v3, v16, v16
	v_add_f32_e32 v2, v2, v3
	v_add_f32_e32 v2, v11, v2
	ds_bpermute_b32 v3, v114, v2
	v_cvt_pk_bf16_f32 v11, v12, v13
	global_store_dwordx2 v[18:19], v[10:11], off offset:32
	v_cvt_pk_bf16_f32 v4, v6, v7
	v_cvt_pk_bf16_f32 v5, v8, v9
	s_waitcnt lgkmcnt(0)
	v_add_f32_e32 v2, v2, v3
	ds_bpermute_b32 v3, v115, v2
	global_store_dwordx2 v[18:19], v[4:5], off offset:256
	v_cvt_pk_bf16_f32 v4, v14, v15
	v_cvt_pk_bf16_f32 v5, v16, v17
	global_store_dwordx2 v[18:19], v[4:5], off offset:288
	s_and_saveexec_b64 s[70:71], s[40:41]
	s_cbranch_execz .LBB0_414
	s_waitcnt lgkmcnt(0)
	v_add_f32_e32 v2, v2, v3
	ds_write_b32 v172, v2 offset:2816
.LBB0_414:
	s_or_b64 exec, exec, s[70:71]
	s_waitcnt lgkmcnt(0)
	s_barrier
	v_mov_b32_e32 v2, v158
	s_movk_i32 s56, 0x100
	s_nop 0
	v_cmp_gt_i32_e32 vcc, s56, v2
	s_and_saveexec_b64 s[70:71], vcc
	s_cbranch_execz .LBB0_416
	s_waitcnt lgkmcnt(0)
	v_lshl_add_u32 v3, v2, 4, 0
	v_add_u32_e32 v3, 0x20000, v3
	ds_read_b128 v[4:7], v3
	v_add_u32_e32 v2, s15, v2
	v_ashrrev_i32_e32 v3, 31, v2
	s_ashr_i32 s15, s14, 31
	v_lshl_add_u64 v[2:3], v[2:3], 4, s[90:91]
	s_waitcnt lgkmcnt(0)
	v_mov_b32_e32 v8, v5
	v_mov_b32_e32 v9, v6
	v_mov_b32_e32 v5, v7
	v_pk_add_f32 v[4:5], v[8:9], v[4:5]
	v_lshl_add_u64 v[2:3], s[14:15], 2, v[2:3]
	v_add_f32_e32 v4, v4, v5
	global_store_dword v[2:3], v4, off

; __device__ __forceinline__ unsigned pk2(float lo, float hi) { return pg8::cvt_pk_bf16(lo, hi); }
;     __device__ __forceinline__ void operator()(const f32x4 (&acc)[2][2][4][2], const Unit& u, int wr, int wc, int fr, int fq) const {
;     ...
;         const int row0 = u.pm * 256 + wr * 64 + fr, col0 = u.pn * 256 + wc * 32 + 8 * fq;
;         float rsv[2][4];
;         if (SIDE) { f32x4 pp[2][4];
; #pragma unroll
;           for (int ai = 0; ai < 2; ++ai)
; #pragma unroll
;             for (int m = 0; m < 4; ++m) pp[ai][m] = *(const f32x4*)(rss + (size_t)(row0 + ai * 128 + m * 16) * 4);
; #pragma unroll
;           for (int ai = 0; ai < 2; ++ai)
; #pragma unroll
;             for (int m = 0; m < 4; ++m) rsv[ai][m] = __builtin_amdgcn_rsqf(((pp[ai][m][0] + pp[ai][m][1]) + (pp[ai][m][2] + pp[ai][m][3])) * (1.0f / D) + EPS); }
; #pragma unroll
;         for (int ai = 0; ai < 2; ++ai)
; #pragma unroll
;             for (int m = 0; m < 4; ++m) {
;                 const int row = row0 + ai * 128 + m * 16;
;                 bf16_t* rowp = O + (size_t)row * LD + col0;
;                 const float rs = SIDE ? rsv[ai][m] : 1.0f;
; #pragma unroll
;                 for (int bj = 0; bj < 2; ++bj) {
;                     const f32x4 v0 = acc[ai][bj][m][0] * rs, v1 = acc[ai][bj][m][1] * rs;
;                     u32x4v w; w.x = pk2(v0[0], v0[1]); w.y = pk2(v0[2], v0[3]); w.z = pk2(v1[0], v1[1]); w.w = pk2(v1[2], v1[3]);
;                     *(u32x4v*)(rowp + bj * 128) = w;
;                     if (SIDE) { if (bj == 0 && u.pn == 9 && wc == 0 && fq == 0) { *(f32x4*)(side + (size_t)row * 8) = v0; *(f32x4*)(side + (size_t)row * 8 + 4) = v1; } }
;                 }
;             }
.LBB0_492:
	v_readlane_b32 s78, v251, 10
	v_readlane_b32 s58, v251, 4
	v_readlane_b32 s60, v251, 12
	v_lshl_add_u32 v194, s57, 8, v167
	v_readlane_b32 s79, v251, 11
	v_readlane_b32 s59, v251, 5
	v_readlane_b32 s61, v251, 13
	v_ashrrev_i32_e32 v195, 31, v194
	v_or_b32_e32 v192, 16, v194
	v_ashrrev_i32_e32 v193, 31, v192
	v_lshl_add_u64 v[130:131], v[194:195], 4, s[60:61]
	v_lshl_add_u64 v[132:133], v[192:193], 4, s[60:61]
	global_load_dwordx4 v[196:199], v[130:131], off
	global_load_dwordx4 v[154:157], v[132:133], off
	v_or_b32_e32 v190, 32, v194
	v_or_b32_e32 v188, 48, v194
	v_ashrrev_i32_e32 v191, 31, v190
	v_ashrrev_i32_e32 v189, 31, v188
	v_add_u32_e32 v186, 0x80, v194
	v_add_u32_e32 v184, 0x90, v194
	v_lshl_add_u64 v[130:131], v[190:191], 4, s[60:61]
	v_lshl_add_u64 v[132:133], v[188:189], 4, s[60:61]
	v_ashrrev_i32_e32 v187, 31, v186
	v_ashrrev_i32_e32 v185, 31, v184
	v_add_u32_e32 v182, 0xa0, v194
	v_add_u32_e32 v178, 0xb0, v194
	global_load_dwordx4 v[150:153], v[130:131], off
	global_load_dwordx4 v[146:149], v[132:133], off
	v_lshl_add_u64 v[130:131], v[186:187], 4, s[60:61]
	v_lshl_add_u64 v[132:133], v[184:185], 4, s[60:61]
	v_ashrrev_i32_e32 v183, 31, v182
	v_ashrrev_i32_e32 v179, 31, v178
	global_load_dwordx4 v[142:145], v[130:131], off
	global_load_dwordx4 v[138:141], v[132:133], off
	v_lshl_add_u64 v[130:131], v[182:183], 4, s[60:61]
	v_lshl_add_u64 v[132:133], v[178:179], 4, s[60:61]
	global_load_dwordx4 v[134:137], v[130:131], off
	s_nop 0
	global_load_dwordx4 v[130:133], v[132:133], off
	v_lshl_or_b32 v180, s56, 8, v201
	s_cmp_eq_u32 s56, 9
	v_ashrrev_i32_e32 v181, 31, v180
	s_cselect_b64 s[56:57], -1, 0
	v_lshl_add_u64 v[180:181], v[180:181], 1, s[58:59]
	s_and_b64 s[80:81], s[44:45], s[56:57]
	s_waitcnt vmcnt(0) lgkmcnt(0)
	v_mov_b32_e32 v204, v197
	v_mov_b32_e32 v205, v198
	v_mov_b32_e32 v197, v199
	v_pk_add_f32 v[196:197], v[204:205], v[196:197]
	s_nop 0
	v_add_f32_e32 v196, v196, v197
	v_fmamk_f32 v196, v196, 0x3a800000, v159
	v_rsq_f32_e32 v198, v196
	v_mad_i64_i32 v[196:197], s[56:57], v194, s36, v[180:181]
	v_pk_mul_f32 v[128:129], v[128:129], v[198:199] op_sel_hi:[1,0]
	v_pk_mul_f32 v[126:127], v[126:127], v[198:199] op_sel_hi:[1,0]
	v_pk_mul_f32 v[124:125], v[124:125], v[198:199] op_sel_hi:[1,0]
	v_pk_mul_f32 v[122:123], v[122:123], v[198:199] op_sel_hi:[1,0]
	v_cvt_pk_bf16_f32 v204, v126, v127
	v_cvt_pk_bf16_f32 v205, v128, v129
	s_nop 0
	v_cvt_pk_bf16_f32 v206, v122, v123
	v_cvt_pk_bf16_f32 v207, v124, v125
	global_store_dwordx4 v[196:197], v[204:207], off
	s_and_saveexec_b64 s[70:71], s[80:81]
	s_cbranch_execz .LBB0_494
	v_lshlrev_b64 v[194:195], 5, v[194:195]
	v_lshl_add_u64 v[194:195], s[78:79], 0, v[194:195]
	global_store_dwordx4 v[194:195], v[126:129], off
	global_store_dwordx4 v[194:195], v[122:125], off offset:16
.LBB0_494:
	s_or_b64 exec, exec, s[70:71]
	s_nop 0
	v_add_f32_e32 v122, v154, v155
	v_add_f32_e32 v123, v156, v157
	v_add_f32_e32 v122, v122, v123
	v_fmamk_f32 v122, v122, 0x3a800000, v159
	v_rsq_f32_e32 v122, v122
	v_mov_b32_e32 v199, v198
	v_mov_b32_e32 v124, v198
	v_mov_b32_e32 v125, v198
	v_pk_mul_f32 v[120:121], v[120:121], v[124:125]
	v_pk_mul_f32 v[118:119], v[118:119], v[198:199]
	v_pk_mul_f32 v[124:125], v[116:117], v[124:125]
	v_pk_mul_f32 v[116:117], v[114:115], v[198:199]
	v_cvt_pk_bf16_f32 v114, v118, v119
	v_cvt_pk_bf16_f32 v115, v120, v121
	v_pk_mul_f32 v[112:113], v[112:113], v[122:123] op_sel_hi:[1,0]
	v_cvt_pk_bf16_f32 v116, v116, v117
	v_cvt_pk_bf16_f32 v117, v124, v125
	global_store_dwordx4 v[196:197], v[114:117], off offset:256
	v_pk_mul_f32 v[110:111], v[110:111], v[122:123] op_sel_hi:[1,0]
	v_pk_mul_f32 v[108:109], v[108:109], v[122:123] op_sel_hi:[1,0]
	v_mad_i64_i32 v[114:115], s[56:57], v192, s36, v[180:181]
	v_pk_mul_f32 v[106:107], v[106:107], v[122:123] op_sel_hi:[1,0]
	v_cvt_pk_bf16_f32 v116, v110, v111
	v_cvt_pk_bf16_f32 v117, v112, v113
	s_nop 0
	v_cvt_pk_bf16_f32 v118, v106, v107
	v_cvt_pk_bf16_f32 v119, v108, v109
	global_store_dwordx4 v[114:115], v[116:119], off
	s_and_saveexec_b64 s[70:71], s[80:81]
	s_cbranch_execz .LBB0_496
	v_lshlrev_b64 v[116:117], 5, v[192:193]
	v_lshl_add_u64 v[116:117], s[78:79], 0, v[116:117]
	global_store_dwordx4 v[116:117], v[110:113], off
	global_store_dwordx4 v[116:117], v[106:109], off offset:16
.LBB0_496:
	s_or_b64 exec, exec, s[70:71]
	s_nop 0
	v_add_f32_e32 v106, v150, v151
	v_add_f32_e32 v107, v152, v153
	v_add_f32_e32 v106, v106, v107
	v_fmamk_f32 v106, v106, 0x3a800000, v159
	v_rsq_f32_e32 v106, v106
	v_mov_b32_e32 v123, v122
	v_mov_b32_e32 v108, v122
	v_mov_b32_e32 v109, v122
	v_pk_mul_f32 v[104:105], v[104:105], v[108:109]
	v_pk_mul_f32 v[102:103], v[102:103], v[122:123]
	v_pk_mul_f32 v[108:109], v[100:101], v[108:109]
	v_pk_mul_f32 v[100:101], v[98:99], v[122:123]
	v_cvt_pk_bf16_f32 v98, v102, v103
	v_cvt_pk_bf16_f32 v99, v104, v105
	v_pk_mul_f32 v[96:97], v[96:97], v[106:107] op_sel_hi:[1,0]
	v_cvt_pk_bf16_f32 v100, v100, v101
	v_cvt_pk_bf16_f32 v101, v108, v109
	global_store_dwordx4 v[114:115], v[98:101], off offset:256
	v_pk_mul_f32 v[94:95], v[94:95], v[106:107] op_sel_hi:[1,0]
	v_pk_mul_f32 v[92:93], v[92:93], v[106:107] op_sel_hi:[1,0]
	v_mad_i64_i32 v[98:99], s[56:57], v190, s36, v[180:181]
	v_pk_mul_f32 v[90:91], v[90:91], v[106:107] op_sel_hi:[1,0]
	v_cvt_pk_bf16_f32 v100, v94, v95
	v_cvt_pk_bf16_f32 v101, v96, v97
	s_nop 0
	v_cvt_pk_bf16_f32 v102, v90, v91
	v_cvt_pk_bf16_f32 v103, v92, v93
	global_store_dwordx4 v[98:99], v[100:103], off
	s_and_saveexec_b64 s[70:71], s[80:81]
	s_cbranch_execz .LBB0_498
	v_lshlrev_b64 v[100:101], 5, v[190:191]
	v_lshl_add_u64 v[100:101], s[78:79], 0, v[100:101]
	global_store_dwordx4 v[100:101], v[94:97], off
	global_store_dwordx4 v[100:101], v[90:93], off offset:16
; __device__ __forceinline__ unsigned pk2(float lo, float hi) { return pg8::cvt_pk_bf16(lo, hi); }
;     __device__ __forceinline__ void operator()(const f32x4 (&acc)[2][2][4][2], const Unit& u, int wr, int wc, int fr, int fq) const {
;     ...
;         for (int ai = 0; ai < 2; ++ai)
; #pragma unroll
;             for (int m = 0; m < 4; ++m) {
;                 const int row = row0 + ai * 128 + m * 16;
;                 bf16_t* rowp = O + (size_t)row * LD + col0;
;                 const float rs = SIDE ? rsv[ai][m] : 1.0f;
; #pragma unroll
;                 for (int bj = 0; bj < 2; ++bj) {
;                     const f32x4 v0 = acc[ai][bj][m][0] * rs, v1 = acc[ai][bj][m][1] * rs;
;                     u32x4v w; w.x = pk2(v0[0], v0[1]); w.y = pk2(v0[2], v0[3]); w.z = pk2(v1[0], v1[1]); w.w = pk2(v1[2], v1[3]);
;                     *(u32x4v*)(rowp + bj * 128) = w;
;                     if (SIDE) { if (bj == 0 && u.pn == 9 && wc == 0 && fq == 0) { *(f32x4*)(side + (size_t)row * 8) = v0; *(f32x4*)(side + (size_t)row * 8 + 4) = v1; } }
;                 }
;             }
.LBB0_498:
	s_or_b64 exec, exec, s[70:71]
	s_nop 0
	v_add_f32_e32 v90, v146, v147
	v_add_f32_e32 v91, v148, v149
	v_add_f32_e32 v90, v90, v91
	v_fmamk_f32 v90, v90, 0x3a800000, v159
	v_rsq_f32_e32 v90, v90
	v_mov_b32_e32 v107, v106
	v_mov_b32_e32 v92, v106
	v_mov_b32_e32 v93, v106
	v_pk_mul_f32 v[88:89], v[88:89], v[92:93]
	v_pk_mul_f32 v[86:87], v[86:87], v[106:107]
	v_pk_mul_f32 v[92:93], v[84:85], v[92:93]
	v_pk_mul_f32 v[84:85], v[82:83], v[106:107]
	v_cvt_pk_bf16_f32 v82, v86, v87
	v_cvt_pk_bf16_f32 v83, v88, v89
	v_pk_mul_f32 v[80:81], v[80:81], v[90:91] op_sel_hi:[1,0]
	v_cvt_pk_bf16_f32 v84, v84, v85
	v_cvt_pk_bf16_f32 v85, v92, v93
	global_store_dwordx4 v[98:99], v[82:85], off offset:256
	v_pk_mul_f32 v[78:79], v[78:79], v[90:91] op_sel_hi:[1,0]
	v_pk_mul_f32 v[76:77], v[76:77], v[90:91] op_sel_hi:[1,0]
	v_mad_i64_i32 v[82:83], s[56:57], v188, s36, v[180:181]
	v_pk_mul_f32 v[74:75], v[74:75], v[90:91] op_sel_hi:[1,0]
	v_cvt_pk_bf16_f32 v84, v78, v79
	v_cvt_pk_bf16_f32 v85, v80, v81
	s_nop 0
	v_cvt_pk_bf16_f32 v86, v74, v75
	v_cvt_pk_bf16_f32 v87, v76, v77
	global_store_dwordx4 v[82:83], v[84:87], off
	s_and_saveexec_b64 s[70:71], s[80:81]
	s_cbranch_execz .LBB0_500
	v_lshlrev_b64 v[84:85], 5, v[188:189]
	v_lshl_add_u64 v[84:85], s[78:79], 0, v[84:85]
	global_store_dwordx4 v[84:85], v[78:81], off
	global_store_dwordx4 v[84:85], v[74:77], off offset:16
.LBB0_500:
	s_or_b64 exec, exec, s[70:71]
	s_nop 0
	v_add_f32_e32 v74, v142, v143
	v_add_f32_e32 v75, v144, v145
	v_add_f32_e32 v74, v74, v75
	v_fmamk_f32 v74, v74, 0x3a800000, v159
	v_rsq_f32_e32 v74, v74
	v_mov_b32_e32 v91, v90
	v_mov_b32_e32 v76, v90
	v_mov_b32_e32 v77, v90
	v_pk_mul_f32 v[72:73], v[72:73], v[76:77]
	v_pk_mul_f32 v[70:71], v[70:71], v[90:91]
	v_pk_mul_f32 v[76:77], v[68:69], v[76:77]
	v_pk_mul_f32 v[68:69], v[66:67], v[90:91]
	v_cvt_pk_bf16_f32 v66, v70, v71
	v_cvt_pk_bf16_f32 v67, v72, v73
	v_pk_mul_f32 v[64:65], v[64:65], v[74:75] op_sel_hi:[1,0]
	v_cvt_pk_bf16_f32 v68, v68, v69
	v_cvt_pk_bf16_f32 v69, v76, v77
	global_store_dwordx4 v[82:83], v[66:69], off offset:256
	v_pk_mul_f32 v[62:63], v[62:63], v[74:75] op_sel_hi:[1,0]
	v_pk_mul_f32 v[60:61], v[60:61], v[74:75] op_sel_hi:[1,0]
	v_mad_i64_i32 v[66:67], s[56:57], v186, s36, v[180:181]
	v_pk_mul_f32 v[58:59], v[58:59], v[74:75] op_sel_hi:[1,0]
	v_cvt_pk_bf16_f32 v68, v62, v63
	v_cvt_pk_bf16_f32 v69, v64, v65
	s_nop 0
	v_cvt_pk_bf16_f32 v70, v58, v59
	v_cvt_pk_bf16_f32 v71, v60, v61
	global_store_dwordx4 v[66:67], v[68:71], off
	s_and_saveexec_b64 s[70:71], s[80:81]
	s_cbranch_execz .LBB0_502
	v_lshlrev_b64 v[68:69], 5, v[186:187]
	v_lshl_add_u64 v[68:69], s[78:79], 0, v[68:69]
	global_store_dwordx4 v[68:69], v[62:65], off
	global_store_dwordx4 v[68:69], v[58:61], off offset:16
.LBB0_502:
	s_or_b64 exec, exec, s[70:71]
	s_nop 0
	v_add_f32_e32 v58, v138, v139
	v_add_f32_e32 v59, v140, v141
	v_add_f32_e32 v58, v58, v59
	v_fmamk_f32 v58, v58, 0x3a800000, v159
	v_rsq_f32_e32 v58, v58
	v_mov_b32_e32 v75, v74
	v_mov_b32_e32 v60, v74
	v_mov_b32_e32 v61, v74
	v_pk_mul_f32 v[56:57], v[56:57], v[60:61]
	v_pk_mul_f32 v[54:55], v[54:55], v[74:75]
	v_pk_mul_f32 v[60:61], v[52:53], v[60:61]
	v_pk_mul_f32 v[52:53], v[50:51], v[74:75]
	v_cvt_pk_bf16_f32 v50, v54, v55
	v_cvt_pk_bf16_f32 v51, v56, v57
	v_pk_mul_f32 v[48:49], v[48:49], v[58:59] op_sel_hi:[1,0]
	v_cvt_pk_bf16_f32 v52, v52, v53
	v_cvt_pk_bf16_f32 v53, v60, v61
	global_store_dwordx4 v[66:67], v[50:53], off offset:256
	v_pk_mul_f32 v[46:47], v[46:47], v[58:59] op_sel_hi:[1,0]
	v_pk_mul_f32 v[44:45], v[44:45], v[58:59] op_sel_hi:[1,0]
	v_mad_i64_i32 v[50:51], s[56:57], v184, s36, v[180:181]
	v_pk_mul_f32 v[42:43], v[42:43], v[58:59] op_sel_hi:[1,0]
	v_cvt_pk_bf16_f32 v52, v46, v47
	v_cvt_pk_bf16_f32 v53, v48, v49
	s_nop 0
	v_cvt_pk_bf16_f32 v54, v42, v43
	v_cvt_pk_bf16_f32 v55, v44, v45
	global_store_dwordx4 v[50:51], v[52:55], off
	s_and_saveexec_b64 s[70:71], s[80:81]
	s_cbranch_execz .LBB0_504
	v_lshlrev_b64 v[52:53], 5, v[184:185]
	v_lshl_add_u64 v[52:53], s[78:79], 0, v[52:53]
	global_store_dwordx4 v[52:53], v[46:49], off
	global_store_dwordx4 v[52:53], v[42:45], off offset:16
; #define PG8_BAR __builtin_amdgcn_s_barrier()
; __device__ __forceinline__ unsigned pk2(float lo, float hi) { return pg8::cvt_pk_bf16(lo, hi); }
; template <class Epi, class Sched, bool ALIGN_EPI = false, bool SP2 = false>
; __device__ __forceinline__ void gemm_phase(PG8_LAS unsigned char* lds, const Gemm g, const Sched& S, const Epi& E) {
;     ...
;         if constexpr (ALIGN_EPI) { if (wr == 0) PG8_BAR; }
;         if constexpr (!Epi::AFTER_DRAIN) { E(acc, cur, wr, wc, fr, fq); S.done(cur); }
;         if (!has_next) break;
; #pragma unroll
;         for (int a = 0; a < 2; ++a)
; #pragma unroll
;             for (int b = 0; b < 2; ++b)
; #pragma unroll
;                 for (int m = 0; m < 4; ++m)
; #pragma unroll
;                     for (int n = 0; n < 2; ++n) acc[a][b][m][n] = (f32x4){0.f, 0.f, 0.f, 0.f};
;         cur = nxt; cA = nA; cB = nB; ++ui;
;         if constexpr (ALIGN_EPI) { if (wr == 1) PG8_BAR; }
;     }
;     __device__ __forceinline__ void operator()(const f32x4 (&acc)[2][2][4][2], const Unit& u, int wr, int wc, int fr, int fq) const {
;     ...
;         for (int ai = 0; ai < 2; ++ai)
; #pragma unroll
;             for (int m = 0; m < 4; ++m) {
;                 const int row = row0 + ai * 128 + m * 16;
;                 bf16_t* rowp = O + (size_t)row * LD + col0;
;                 const float rs = SIDE ? rsv[ai][m] : 1.0f;
; #pragma unroll
;                 for (int bj = 0; bj < 2; ++bj) {
;                     const f32x4 v0 = acc[ai][bj][m][0] * rs, v1 = acc[ai][bj][m][1] * rs;
;                     u32x4v w; w.x = pk2(v0[0], v0[1]); w.y = pk2(v0[2], v0[3]); w.z = pk2(v1[0], v1[1]); w.w = pk2(v1[2], v1[3]);
;                     *(u32x4v*)(rowp + bj * 128) = w;
;                     if (SIDE) { if (bj == 0 && u.pn == 9 && wc == 0 && fq == 0) { *(f32x4*)(side + (size_t)row * 8) = v0; *(f32x4*)(side + (size_t)row * 8 + 4) = v1; } }
;                 }
;             }
.LBB0_504:
	s_or_b64 exec, exec, s[70:71]
	s_nop 0
	v_add_f32_e32 v42, v134, v135
	v_add_f32_e32 v43, v136, v137
	v_add_f32_e32 v42, v42, v43
	v_fmamk_f32 v42, v42, 0x3a800000, v159
	v_rsq_f32_e32 v42, v42
	v_mov_b32_e32 v59, v58
	v_mov_b32_e32 v44, v58
	v_mov_b32_e32 v45, v58
	v_pk_mul_f32 v[40:41], v[40:41], v[44:45]
	v_pk_mul_f32 v[38:39], v[38:39], v[58:59]
	v_pk_mul_f32 v[44:45], v[36:37], v[44:45]
	v_pk_mul_f32 v[36:37], v[34:35], v[58:59]
	v_cvt_pk_bf16_f32 v34, v38, v39
	v_cvt_pk_bf16_f32 v35, v40, v41
	v_pk_mul_f32 v[32:33], v[32:33], v[42:43] op_sel_hi:[1,0]
	v_cvt_pk_bf16_f32 v36, v36, v37
	v_cvt_pk_bf16_f32 v37, v44, v45
	global_store_dwordx4 v[50:51], v[34:37], off offset:256
	v_pk_mul_f32 v[30:31], v[30:31], v[42:43] op_sel_hi:[1,0]
	v_pk_mul_f32 v[28:29], v[28:29], v[42:43] op_sel_hi:[1,0]
	v_mad_i64_i32 v[34:35], s[56:57], v182, s36, v[180:181]
	v_pk_mul_f32 v[26:27], v[26:27], v[42:43] op_sel_hi:[1,0]
	v_cvt_pk_bf16_f32 v36, v30, v31
	v_cvt_pk_bf16_f32 v37, v32, v33
	s_nop 0
	v_cvt_pk_bf16_f32 v38, v26, v27
	v_cvt_pk_bf16_f32 v39, v28, v29
	global_store_dwordx4 v[34:35], v[36:39], off
	s_and_saveexec_b64 s[70:71], s[80:81]
	s_cbranch_execz .LBB0_506
	v_lshlrev_b64 v[36:37], 5, v[182:183]
	v_lshl_add_u64 v[36:37], s[78:79], 0, v[36:37]
	global_store_dwordx4 v[36:37], v[30:33], off
	global_store_dwordx4 v[36:37], v[26:29], off offset:16
.LBB0_506:
	s_or_b64 exec, exec, s[70:71]
	s_nop 0
	v_add_f32_e32 v26, v130, v131
	v_add_f32_e32 v27, v132, v133
	v_add_f32_e32 v26, v26, v27
	v_fmamk_f32 v26, v26, 0x3a800000, v159
	v_rsq_f32_e32 v26, v26
	v_mov_b32_e32 v43, v42
	v_mov_b32_e32 v28, v42
	v_mov_b32_e32 v29, v42
	v_pk_mul_f32 v[24:25], v[24:25], v[28:29]
	v_pk_mul_f32 v[22:23], v[22:23], v[42:43]
	v_pk_mul_f32 v[28:29], v[20:21], v[28:29]
	v_pk_mul_f32 v[20:21], v[18:19], v[42:43]
	v_cvt_pk_bf16_f32 v18, v22, v23
	v_cvt_pk_bf16_f32 v19, v24, v25
	v_pk_mul_f32 v[16:17], v[16:17], v[26:27] op_sel_hi:[1,0]
	v_cvt_pk_bf16_f32 v20, v20, v21
	v_cvt_pk_bf16_f32 v21, v28, v29
	global_store_dwordx4 v[34:35], v[18:21], off offset:256
	v_pk_mul_f32 v[14:15], v[14:15], v[26:27] op_sel_hi:[1,0]
	v_pk_mul_f32 v[12:13], v[12:13], v[26:27] op_sel_hi:[1,0]
	v_mad_i64_i32 v[18:19], s[56:57], v178, s36, v[180:181]
	v_pk_mul_f32 v[10:11], v[10:11], v[26:27] op_sel_hi:[1,0]
	v_cvt_pk_bf16_f32 v20, v14, v15
	v_cvt_pk_bf16_f32 v21, v16, v17
	s_nop 0
	v_cvt_pk_bf16_f32 v22, v10, v11
	v_cvt_pk_bf16_f32 v23, v12, v13
	global_store_dwordx4 v[18:19], v[20:23], off
	s_and_saveexec_b64 s[70:71], s[80:81]
	s_cbranch_execz .LBB0_508
	v_lshlrev_b64 v[20:21], 5, v[178:179]
	v_lshl_add_u64 v[20:21], s[78:79], 0, v[20:21]
	global_store_dwordx4 v[20:21], v[14:17], off
	global_store_dwordx4 v[20:21], v[10:13], off offset:16
.LBB0_508:
	s_or_b64 exec, exec, s[70:71]
	v_mov_b32_e32 v27, v26
	v_mov_b32_e32 v10, v26
	v_mov_b32_e32 v11, v26
	v_pk_mul_f32 v[8:9], v[8:9], v[10:11]
	v_pk_mul_f32 v[10:11], v[4:5], v[10:11]
	v_pk_mul_f32 v[4:5], v[2:3], v[26:27]
	s_and_b64 vcc, exec, s[40:41]
	s_mov_b64 s[40:41], -1
	v_pk_mul_f32 v[6:7], v[6:7], v[26:27]
	s_nop 0
	v_cvt_pk_bf16_f32 v2, v6, v7
	v_cvt_pk_bf16_f32 v3, v8, v9
	v_cvt_pk_bf16_f32 v4, v4, v5
	v_cvt_pk_bf16_f32 v5, v10, v11
	global_store_dwordx4 v[18:19], v[2:5], off offset:256
	s_cbranch_vccnz .LBB0_479
	s_andn2_b64 vcc, exec, s[18:19]
	s_cbranch_vccnz .LBB0_478
	s_barrier
	s_branch .LBB0_478

; __device__ __forceinline__ unsigned pk2(float lo, float hi) { return pg8::cvt_pk_bf16(lo, hi); }
;     __device__ __forceinline__ void operator()(const f32x4 (&acc)[2][2][4][2], const Unit& u, int wr, int wc, int fr, int fq) const {
;     ...
;         for (int ai = 0; ai < 2; ++ai)
; #pragma unroll
;             for (int m = 0; m < 4; ++m) {
;                 const int row = row0 + ai * 128 + m * 16;
;                 bf16_t* rowp = O + (size_t)row * LD + col0;
;                 const float rs = SIDE ? rsv[ai][m] : 1.0f;
; #pragma unroll
;                 for (int bj = 0; bj < 2; ++bj) {
;                     const f32x4 v0 = acc[ai][bj][m][0] * rs, v1 = acc[ai][bj][m][1] * rs;
;                     u32x4v w; w.x = pk2(v0[0], v0[1]); w.y = pk2(v0[2], v0[3]); w.z = pk2(v1[0], v1[1]); w.w = pk2(v1[2], v1[3]);
;                     *(u32x4v*)(rowp + bj * 128) = w;
;                     if (SIDE) { if (bj == 0 && u.pn == 9 && wc == 0 && fq == 0) { *(f32x4*)(side + (size_t)row * 8) = v0; *(f32x4*)(side + (size_t)row * 8 + 4) = v1; } }
;                 }
;             }
.LBB0_971:
	v_readlane_b32 s62, v251, 8
	v_lshl_add_u32 v144, s50, 8, v140
	v_lshl_or_b32 v146, s49, 8, v142
	s_mov_b64 s[58:59], 0
	s_mov_b64 s[60:61], 0
	v_readlane_b32 s63, v251, 9
	v_ashrrev_i32_e32 v147, 31, v146
	v_ashrrev_i32_e32 v145, 31, v144
	v_lshlrev_b64 v[148:149], 11, v[144:145]
	v_lshl_add_u64 v[146:147], v[146:147], 1, s[62:63]
	v_lshl_add_u64 v[148:149], v[146:147], 0, v[148:149]
	v_cvt_pk_bf16_f32 v122, v122, v123
	v_cvt_pk_bf16_f32 v123, v124, v125
	v_cvt_pk_bf16_f32 v124, v126, v127
	v_cvt_pk_bf16_f32 v125, v128, v129
	global_store_dwordx4 v[148:149], v[122:125], off
	v_cvt_pk_bf16_f32 v118, v118, v119
	v_cvt_pk_bf16_f32 v119, v120, v121
	v_cvt_pk_bf16_f32 v120, v114, v115
	v_or_b32_e32 v114, 16, v144
	v_ashrrev_i32_e32 v115, 31, v114
	v_lshlrev_b64 v[114:115], 11, v[114:115]
	v_lshl_add_u64 v[114:115], v[146:147], 0, v[114:115]
	v_cvt_pk_bf16_f32 v121, v116, v117
	global_store_dwordx4 v[148:149], v[118:121], off offset:256
	v_cvt_pk_bf16_f32 v110, v110, v111
	v_cvt_pk_bf16_f32 v111, v112, v113
	v_cvt_pk_bf16_f32 v112, v106, v107
	v_cvt_pk_bf16_f32 v113, v108, v109
	global_store_dwordx4 v[114:115], v[110:113], off
	v_cvt_pk_bf16_f32 v102, v102, v103
	v_cvt_pk_bf16_f32 v103, v104, v105
	v_cvt_pk_bf16_f32 v104, v98, v99
	v_or_b32_e32 v98, 32, v144
	v_ashrrev_i32_e32 v99, 31, v98
	v_lshlrev_b64 v[98:99], 11, v[98:99]
	v_lshl_add_u64 v[98:99], v[146:147], 0, v[98:99]
	v_cvt_pk_bf16_f32 v105, v100, v101
	global_store_dwordx4 v[114:115], v[102:105], off offset:256
	v_cvt_pk_bf16_f32 v94, v94, v95
	v_cvt_pk_bf16_f32 v95, v96, v97
	v_cvt_pk_bf16_f32 v96, v90, v91
	v_cvt_pk_bf16_f32 v97, v92, v93
	global_store_dwordx4 v[98:99], v[94:97], off
	v_cvt_pk_bf16_f32 v86, v86, v87
	v_cvt_pk_bf16_f32 v87, v88, v89
	v_cvt_pk_bf16_f32 v88, v82, v83
	v_or_b32_e32 v82, 48, v144
	v_ashrrev_i32_e32 v83, 31, v82
	v_lshlrev_b64 v[82:83], 11, v[82:83]
	v_lshl_add_u64 v[82:83], v[146:147], 0, v[82:83]
	s_mov_b32 s49, 0x40000
	v_cvt_pk_bf16_f32 v89, v84, v85
	global_store_dwordx4 v[98:99], v[86:89], off offset:256
	v_cvt_pk_bf16_f32 v78, v78, v79
	v_cvt_pk_bf16_f32 v79, v80, v81
	v_cvt_pk_bf16_f32 v80, v74, v75
	v_cvt_pk_bf16_f32 v81, v76, v77
	global_store_dwordx4 v[82:83], v[78:81], off
	v_cvt_pk_bf16_f32 v70, v70, v71
	v_cvt_pk_bf16_f32 v71, v72, v73
	v_cvt_pk_bf16_f32 v72, v66, v67
	v_cvt_pk_bf16_f32 v73, v68, v69
	global_store_dwordx4 v[82:83], v[70:73], off offset:256
	v_cvt_pk_bf16_f32 v62, v62, v63
	v_cvt_pk_bf16_f32 v63, v64, v65
	v_cvt_pk_bf16_f32 v64, v58, v59
	v_add_co_u32_e32 v58, vcc, s49, v148
	v_lshl_add_u64 v[66:67], v[148:149], 0, s[88:89]
	s_nop 0
	v_addc_co_u32_e32 v59, vcc, 0, v149, vcc
	s_mov_b32 s49, 0x48000
	v_cvt_pk_bf16_f32 v65, v60, v61
	global_store_dwordx4 v[58:59], v[62:65], off
	v_cvt_pk_bf16_f32 v54, v54, v55
	v_cvt_pk_bf16_f32 v55, v56, v57
	v_cvt_pk_bf16_f32 v56, v50, v51
	v_cvt_pk_bf16_f32 v57, v52, v53
	global_store_dwordx4 v[66:67], v[54:57], off offset:256
	s_mov_b64 s[58:59], 0x48000
	v_cvt_pk_bf16_f32 v46, v46, v47
	v_cvt_pk_bf16_f32 v47, v48, v49
	v_cvt_pk_bf16_f32 v48, v42, v43
	v_add_co_u32_e32 v42, vcc, s49, v148
	v_lshl_add_u64 v[50:51], v[148:149], 0, s[58:59]
	s_nop 0
	v_addc_co_u32_e32 v43, vcc, 0, v149, vcc
	s_mov_b32 s49, 0x50000
	v_cvt_pk_bf16_f32 v49, v44, v45
	global_store_dwordx4 v[42:43], v[46:49], off
	v_cvt_pk_bf16_f32 v38, v38, v39
	v_cvt_pk_bf16_f32 v39, v40, v41
	v_cvt_pk_bf16_f32 v40, v34, v35
	v_cvt_pk_bf16_f32 v41, v36, v37
	global_store_dwordx4 v[50:51], v[38:41], off offset:256
	s_mov_b64 s[58:59], 0x50000
	v_cvt_pk_bf16_f32 v30, v30, v31
	v_cvt_pk_bf16_f32 v31, v32, v33
	v_cvt_pk_bf16_f32 v32, v26, v27
	v_add_co_u32_e32 v26, vcc, s49, v148
	v_lshl_add_u64 v[34:35], v[148:149], 0, s[58:59]
	s_nop 0
	v_addc_co_u32_e32 v27, vcc, 0, v149, vcc
	v_cvt_pk_bf16_f32 v33, v28, v29
	global_store_dwordx4 v[26:27], v[30:33], off
	v_cvt_pk_bf16_f32 v22, v22, v23
	v_cvt_pk_bf16_f32 v23, v24, v25
	v_cvt_pk_bf16_f32 v24, v18, v19
	v_cvt_pk_bf16_f32 v25, v20, v21
	global_store_dwordx4 v[34:35], v[22:25], off offset:256
	v_cvt_pk_bf16_f32 v14, v14, v15
	v_cvt_pk_bf16_f32 v15, v16, v17
	v_cvt_pk_bf16_f32 v16, v10, v11
	v_add_co_u32_e32 v10, vcc, 0x58000, v148
	s_mov_b64 s[58:59], 0x58000
	s_nop 0
	v_addc_co_u32_e32 v11, vcc, 0, v149, vcc
	v_lshl_add_u64 v[18:19], v[148:149], 0, s[58:59]
	s_and_b64 vcc, exec, s[40:41]
	s_mov_b64 s[40:41], -1
	v_cvt_pk_bf16_f32 v17, v12, v13
	global_store_dwordx4 v[10:11], v[14:17], off
	v_cvt_pk_bf16_f32 v6, v6, v7
	v_cvt_pk_bf16_f32 v7, v8, v9
	v_cvt_pk_bf16_f32 v8, v2, v3
	v_cvt_pk_bf16_f32 v9, v4, v5
	global_store_dwordx4 v[18:19], v[6:9], off offset:256
	s_cbranch_vccnz .LBB0_959
	s_andn2_b64 vcc, exec, s[20:21]
	s_cbranch_vccnz .LBB0_958
	s_barrier
	s_branch .LBB0_958

; __device__ __forceinline__ unsigned pk2(float lo, float hi) { return pg8::cvt_pk_bf16(lo, hi); }
;     __device__ __forceinline__ void operator()(const f32x4 (&acc)[2][2][4][2], const Unit& u, int wr, int wc, int fr, int fq) const {
;     ...
;         for (int ai = 0; ai < 2; ++ai)
; #pragma unroll
;             for (int m = 0; m < 4; ++m) {
;                 const int row = row0 + ai * 128 + m * 16;
;                 bf16_t* rowp = O + (size_t)row * LD + col0;
;                 const float rs = SIDE ? rsv[ai][m] : 1.0f;
; #pragma unroll
;                 for (int bj = 0; bj < 2; ++bj) {
;                     const f32x4 v0 = acc[ai][bj][m][0] * rs, v1 = acc[ai][bj][m][1] * rs;
;                     u32x4v w; w.x = pk2(v0[0], v0[1]); w.y = pk2(v0[2], v0[3]); w.z = pk2(v1[0], v1[1]); w.w = pk2(v1[2], v1[3]);
;                     *(u32x4v*)(rowp + bj * 128) = w;
;                     if (SIDE) { if (bj == 0 && u.pn == 9 && wc == 0 && fq == 0) { *(f32x4*)(side + (size_t)row * 8) = v0; *(f32x4*)(side + (size_t)row * 8 + 4) = v1; } }
;                 }
;             }
.LBB0_997:
	v_readlane_b32 s62, v251, 8
	v_lshl_add_u32 v144, s50, 8, v140
	v_lshl_or_b32 v146, s49, 8, v142
	s_mov_b64 s[58:59], 0
	s_mov_b64 s[60:61], 0
	v_readlane_b32 s63, v251, 9
	v_ashrrev_i32_e32 v147, 31, v146
	v_ashrrev_i32_e32 v145, 31, v144
	v_lshlrev_b64 v[148:149], 11, v[144:145]
	v_lshl_add_u64 v[146:147], v[146:147], 1, s[62:63]
	v_lshl_add_u64 v[148:149], v[146:147], 0, v[148:149]
	v_cvt_pk_bf16_f32 v122, v122, v123
	v_cvt_pk_bf16_f32 v123, v124, v125
	v_cvt_pk_bf16_f32 v124, v126, v127
	v_cvt_pk_bf16_f32 v125, v128, v129
	global_store_dwordx4 v[148:149], v[122:125], off
	v_cvt_pk_bf16_f32 v118, v118, v119
	v_cvt_pk_bf16_f32 v119, v120, v121
	v_cvt_pk_bf16_f32 v120, v114, v115
	v_or_b32_e32 v114, 16, v144
	v_ashrrev_i32_e32 v115, 31, v114
	v_lshlrev_b64 v[114:115], 11, v[114:115]
	v_lshl_add_u64 v[114:115], v[146:147], 0, v[114:115]
	v_cvt_pk_bf16_f32 v121, v116, v117
	global_store_dwordx4 v[148:149], v[118:121], off offset:256
	v_cvt_pk_bf16_f32 v110, v110, v111
	v_cvt_pk_bf16_f32 v111, v112, v113
	v_cvt_pk_bf16_f32 v112, v106, v107
	v_cvt_pk_bf16_f32 v113, v108, v109
	global_store_dwordx4 v[114:115], v[110:113], off
	v_cvt_pk_bf16_f32 v102, v102, v103
	v_cvt_pk_bf16_f32 v103, v104, v105
	v_cvt_pk_bf16_f32 v104, v98, v99
	v_or_b32_e32 v98, 32, v144
	v_ashrrev_i32_e32 v99, 31, v98
	v_lshlrev_b64 v[98:99], 11, v[98:99]
	v_lshl_add_u64 v[98:99], v[146:147], 0, v[98:99]
	v_cvt_pk_bf16_f32 v105, v100, v101
	global_store_dwordx4 v[114:115], v[102:105], off offset:256
	v_cvt_pk_bf16_f32 v94, v94, v95
	v_cvt_pk_bf16_f32 v95, v96, v97
	v_cvt_pk_bf16_f32 v96, v90, v91
	v_cvt_pk_bf16_f32 v97, v92, v93
	global_store_dwordx4 v[98:99], v[94:97], off
	v_cvt_pk_bf16_f32 v86, v86, v87
	v_cvt_pk_bf16_f32 v87, v88, v89
	v_cvt_pk_bf16_f32 v88, v82, v83
	v_or_b32_e32 v82, 48, v144
	v_ashrrev_i32_e32 v83, 31, v82
	v_lshlrev_b64 v[82:83], 11, v[82:83]
	v_lshl_add_u64 v[82:83], v[146:147], 0, v[82:83]
	s_mov_b32 s49, 0x40000
	v_cvt_pk_bf16_f32 v89, v84, v85
	global_store_dwordx4 v[98:99], v[86:89], off offset:256
	v_cvt_pk_bf16_f32 v78, v78, v79
	v_cvt_pk_bf16_f32 v79, v80, v81
	v_cvt_pk_bf16_f32 v80, v74, v75
	v_cvt_pk_bf16_f32 v81, v76, v77
	global_store_dwordx4 v[82:83], v[78:81], off
	v_cvt_pk_bf16_f32 v70, v70, v71
	v_cvt_pk_bf16_f32 v71, v72, v73
	v_cvt_pk_bf16_f32 v72, v66, v67
	v_cvt_pk_bf16_f32 v73, v68, v69
	global_store_dwordx4 v[82:83], v[70:73], off offset:256
	v_cvt_pk_bf16_f32 v62, v62, v63
	v_cvt_pk_bf16_f32 v63, v64, v65
	v_cvt_pk_bf16_f32 v64, v58, v59
	v_add_co_u32_e32 v58, vcc, s49, v148
	v_lshl_add_u64 v[66:67], v[148:149], 0, s[88:89]
	s_nop 0
	v_addc_co_u32_e32 v59, vcc, 0, v149, vcc
	s_mov_b32 s49, 0x48000
	v_cvt_pk_bf16_f32 v65, v60, v61
	global_store_dwordx4 v[58:59], v[62:65], off
	v_cvt_pk_bf16_f32 v54, v54, v55
	v_cvt_pk_bf16_f32 v55, v56, v57
	v_cvt_pk_bf16_f32 v56, v50, v51
	v_cvt_pk_bf16_f32 v57, v52, v53
	global_store_dwordx4 v[66:67], v[54:57], off offset:256
	s_mov_b64 s[58:59], 0x48000
	v_cvt_pk_bf16_f32 v46, v46, v47
	v_cvt_pk_bf16_f32 v47, v48, v49
	v_cvt_pk_bf16_f32 v48, v42, v43
	v_add_co_u32_e32 v42, vcc, s49, v148
	v_lshl_add_u64 v[50:51], v[148:149], 0, s[58:59]
	s_nop 0
	v_addc_co_u32_e32 v43, vcc, 0, v149, vcc
	s_mov_b32 s49, 0x50000
	v_cvt_pk_bf16_f32 v49, v44, v45
	global_store_dwordx4 v[42:43], v[46:49], off
	v_cvt_pk_bf16_f32 v38, v38, v39
	v_cvt_pk_bf16_f32 v39, v40, v41
	v_cvt_pk_bf16_f32 v40, v34, v35
	v_cvt_pk_bf16_f32 v41, v36, v37
	global_store_dwordx4 v[50:51], v[38:41], off offset:256
	s_mov_b64 s[58:59], 0x50000
	v_cvt_pk_bf16_f32 v30, v30, v31
	v_cvt_pk_bf16_f32 v31, v32, v33
	v_cvt_pk_bf16_f32 v32, v26, v27
	v_add_co_u32_e32 v26, vcc, s49, v148
	v_lshl_add_u64 v[34:35], v[148:149], 0, s[58:59]
	s_nop 0
	v_addc_co_u32_e32 v27, vcc, 0, v149, vcc
	v_cvt_pk_bf16_f32 v33, v28, v29
	global_store_dwordx4 v[26:27], v[30:33], off
	v_cvt_pk_bf16_f32 v22, v22, v23
	v_cvt_pk_bf16_f32 v23, v24, v25
	v_cvt_pk_bf16_f32 v24, v18, v19
	v_cvt_pk_bf16_f32 v25, v20, v21
	global_store_dwordx4 v[34:35], v[22:25], off offset:256
	v_cvt_pk_bf16_f32 v14, v14, v15
	v_cvt_pk_bf16_f32 v15, v16, v17
	v_cvt_pk_bf16_f32 v16, v10, v11
	v_add_co_u32_e32 v10, vcc, 0x58000, v148
	s_mov_b64 s[58:59], 0x58000
	s_nop 0
	v_addc_co_u32_e32 v11, vcc, 0, v149, vcc
	v_lshl_add_u64 v[18:19], v[148:149], 0, s[58:59]
	s_and_b64 vcc, exec, s[40:41]
	s_mov_b64 s[40:41], -1
	v_cvt_pk_bf16_f32 v17, v12, v13
	global_store_dwordx4 v[10:11], v[14:17], off
	v_cvt_pk_bf16_f32 v6, v6, v7
	v_cvt_pk_bf16_f32 v7, v8, v9
	v_cvt_pk_bf16_f32 v8, v2, v3
	v_cvt_pk_bf16_f32 v9, v4, v5
	global_store_dwordx4 v[18:19], v[6:9], off offset:256
	s_cbranch_vccnz .LBB0_985
	s_andn2_b64 vcc, exec, s[18:19]
	s_cbranch_vccnz .LBB0_984
	s_barrier
	s_branch .LBB0_984

; __device__ __forceinline__ float bflo(unsigned w) { return __uint_as_float(w << 16); }
; __device__ __forceinline__ float bfhi(unsigned w) { return __uint_as_float(w & 0xffff0000u); }
; __device__ __forceinline__ unsigned pk2(float lo, float hi) { return pg8::cvt_pk_bf16(lo, hi); }
;     __device__ __forceinline__ void operator()(const f32x4 (&acc)[2][2][4][2], const Unit& u, int wr, int wc, int fr, int fq) const {
;     ...
;         const int row0 = u.pm * 256 + wr * 64 + fr, col0 = u.pn * 256 + wc * 32 + 4 * fq;
; #pragma unroll
;         for (int hb = 0; hb < 2; ++hb) {
;             u32x2v rin[4][4];
; #pragma unroll
;             for (int gg = 0; gg < 4; ++gg) { const int g = hb * 4 + gg; const size_t offn = (size_t)(row0 + (g >> 2) * 128 + (g & 3) * 16) * D + col0;
; #pragma unroll
;                 for (int k = 0; k < 4; ++k) rin[gg][k] = *(const u32x2v*)(in + offn + (k >> 1) * 128 + (k & 1) * 16); }
; #pragma unroll
;             for (int gg = 0; gg < 4; ++gg) {
;                 const int g = hb * 4 + gg, ai = g >> 2, m = g & 3, row = row0 + ai * 128 + m * 16;
;                 const size_t off = (size_t)row * D + col0;
;                 float ss = 0.f;
; #pragma unroll
;                 for (int k = 0; k < 4; ++k) { const int bj = k >> 1, n = k & 1; const size_t o = off + bj * 128 + n * 16; const f32x4 a = acc[ai][bj][m][n] * scale; const u32x2v w0 = rin[gg][k];
;                     f32x4 r; r[0] = bflo(w0.x) + a[0]; r[1] = bfhi(w0.x) + a[1]; r[2] = bflo(w0.y) + a[2]; r[3] = bfhi(w0.y) + a[3];
;                     u32x2v w; w.x = pk2(r[0], r[1]); w.y = pk2(r[2], r[3]); *(u32x2v*)(out + o) = w; ss += (r[0] * r[0] + r[1] * r[1]) + (r[2] * r[2] + r[3] * r[3]); }
;                 ss += __shfl_xor(ss, 16); ss += __shfl_xor(ss, 32);
;                 if (fq == 0) part[(ai * 128 + wr * 64 + m * 16 + fr) * 4 + wc] = ss;
.LBB0_1103:
	s_lshl_b32 s13, s13, 8
	v_lshl_or_b32 v136, s12, 8, v170
	v_readlane_b32 s80, v250, 28
	v_add_u32_e32 v138, s13, v168
	v_ashrrev_i32_e32 v137, 31, v136
	v_readlane_b32 s81, v250, 29
	s_mov_b64 s[56:57], s[46:47]
	s_mov_b64 s[70:71], s[46:47]
	s_mov_b32 s90, 1.0
	v_lshlrev_b64 v[140:141], 1, v[136:137]
	v_ashrrev_i32_e32 v139, 31, v138
	v_lshlrev_b64 v[142:143], 11, v[138:139]
	v_lshl_add_u64 v[136:137], s[56:57], 0, v[140:141]
	v_lshl_add_u64 v[144:145], v[136:137], 0, v[142:143]
	global_load_dwordx2 v[174:175], v[144:145], off
	global_load_dwordx2 v[176:177], v[144:145], off offset:32
	global_load_dwordx2 v[178:179], v[144:145], off offset:256
	global_load_dwordx2 v[180:181], v[144:145], off offset:288
	v_or_b32_e32 v144, 16, v138
	v_or_b32_e32 v146, 32, v138
	v_or_b32_e32 v150, 48, v138
	v_ashrrev_i32_e32 v145, 31, v144
	v_ashrrev_i32_e32 v147, 31, v146
	v_ashrrev_i32_e32 v151, 31, v150
	v_lshlrev_b64 v[166:167], 11, v[144:145]
	v_lshlrev_b64 v[148:149], 11, v[146:147]
	v_pk_mul_f32 v[182:183], v[128:129], s[90:91] op_sel_hi:[1,0]
	v_pk_mul_f32 v[188:189], v[122:123], s[90:91] op_sel_hi:[1,0]
	v_pk_mul_f32 v[190:191], v[120:121], s[90:91] op_sel_hi:[1,0]
	v_pk_mul_f32 v[192:193], v[118:119], s[90:91] op_sel_hi:[1,0]
	v_lshl_add_u64 v[118:119], s[70:71], 0, v[140:141]
	v_lshlrev_b64 v[128:129], 11, v[150:151]
	v_lshl_add_u64 v[120:121], v[136:137], 0, v[166:167]
	v_lshl_add_u64 v[122:123], v[136:137], 0, v[148:149]
	v_pk_mul_f32 v[184:185], v[126:127], s[90:91] op_sel_hi:[1,0]
	v_pk_mul_f32 v[186:187], v[124:125], s[90:91] op_sel_hi:[1,0]
	v_lshl_add_u64 v[194:195], v[118:119], 0, v[142:143]
	v_lshl_add_u64 v[196:197], v[136:137], 0, v[128:129]
	global_load_dwordx2 v[156:157], v[120:121], off
	global_load_dwordx2 v[154:155], v[120:121], off offset:32
	global_load_dwordx2 v[152:153], v[120:121], off offset:256
	global_load_dwordx2 v[150:151], v[120:121], off offset:288
	global_load_dwordx2 v[146:147], v[122:123], off
	global_load_dwordx2 v[144:145], v[122:123], off offset:32
	global_load_dwordx2 v[142:143], v[122:123], off offset:256
	global_load_dwordx2 v[140:141], v[122:123], off offset:288
	global_load_dwordx2 v[126:127], v[196:197], off
	global_load_dwordx2 v[124:125], v[196:197], off offset:32
	s_nop 0
	global_load_dwordx2 v[122:123], v[196:197], off offset:256
	global_load_dwordx2 v[120:121], v[196:197], off offset:288
	v_pk_mul_f32 v[114:115], v[114:115], s[90:91] op_sel_hi:[1,0]
	v_pk_mul_f32 v[116:117], v[116:117], s[90:91] op_sel_hi:[1,0]
	s_waitcnt vmcnt(0) lgkmcnt(0)
	v_lshlrev_b32_e32 v173, 16, v174
	v_and_b32_e32 v174, 0xffff0000, v174
	v_lshlrev_b32_e32 v196, 16, v175
	v_and_b32_e32 v175, 0xffff0000, v175
	v_lshlrev_b32_e32 v197, 16, v176
	v_and_b32_e32 v176, 0xffff0000, v176
	v_lshlrev_b32_e32 v198, 16, v177
	v_and_b32_e32 v177, 0xffff0000, v177
	v_lshlrev_b32_e32 v200, 16, v179
	v_add_f32_e32 v173, v184, v173
	v_add_f32_e32 v184, v185, v174
	v_add_f32_e32 v183, v183, v175
	v_add_f32_e32 v176, v189, v176
	v_add_f32_e32 v177, v187, v177
	v_add_f32_e32 v182, v182, v196
	v_add_f32_e32 v185, v188, v197
	v_add_f32_e32 v186, v186, v198
	v_add_f32_e32 v188, v190, v200
	v_cvt_pk_bf16_f32 v174, v173, v184
	v_cvt_pk_bf16_f32 v175, v182, v183
	v_mul_f32_e32 v184, v184, v184
	v_mul_f32_e32 v183, v183, v183
	v_mul_f32_e32 v189, v176, v176
	v_mul_f32_e32 v190, v177, v177
	v_lshlrev_b32_e32 v199, 16, v178
	v_and_b32_e32 v178, 0xffff0000, v178
	v_and_b32_e32 v179, 0xffff0000, v179
	v_fmac_f32_e32 v184, v173, v173
	v_fmac_f32_e32 v183, v182, v182
	v_fmac_f32_e32 v189, v185, v185
	v_fmac_f32_e32 v190, v186, v186
	v_add_f32_e32 v178, v193, v178
	v_add_f32_e32 v179, v191, v179
	global_store_dwordx2 v[194:195], v[174:175], off
	v_add_f32_e32 v173, v184, v183
	v_add_f32_e32 v175, v189, v190
	v_add_f32_e32 v187, v192, v199
	v_mul_f32_e32 v191, v178, v178
	v_add_f32_e32 v173, v173, v175
	v_mul_f32_e32 v175, v179, v179
	v_fmac_f32_e32 v191, v187, v187
	v_fmac_f32_e32 v175, v188, v188
	v_add_f32_e32 v175, v191, v175
	v_add_f32_e32 v173, v173, v175
	v_lshlrev_b32_e32 v175, 16, v180
	v_cvt_pk_bf16_f32 v174, v185, v176
	v_add_f32_e32 v176, v114, v175
	v_and_b32_e32 v114, 0xffff0000, v180
	v_add_f32_e32 v180, v115, v114
	v_lshlrev_b32_e32 v114, 16, v181
	v_add_f32_e32 v182, v116, v114
	v_and_b32_e32 v114, 0xffff0000, v181
	v_add_f32_e32 v181, v117, v114
	v_mul_f32_e32 v114, v180, v180
	v_mul_f32_e32 v115, v181, v181
	v_fmac_f32_e32 v114, v176, v176
	v_fmac_f32_e32 v115, v182, v182
	v_add_f32_e32 v114, v114, v115
	v_and_b32_e32 v116, 64, v209
	v_add_f32_e32 v115, v173, v114
	v_xor_b32_e32 v114, 16, v209
	v_add_u32_e32 v117, 64, v116
	v_cmp_lt_i32_e32 vcc, v114, v117
	v_cvt_pk_bf16_f32 v175, v186, v177
	global_store_dwordx2 v[194:195], v[174:175], off offset:32
	v_cvt_pk_bf16_f32 v174, v187, v178
	v_cvt_pk_bf16_f32 v175, v188, v179
	global_store_dwordx2 v[194:195], v[174:175], off offset:256
	v_cndmask_b32_e32 v114, v209, v114, vcc
	v_lshlrev_b32_e32 v114, 2, v114
	ds_bpermute_b32 v116, v114, v115
	v_cvt_pk_bf16_f32 v174, v176, v180
	v_cvt_pk_bf16_f32 v175, v182, v181
	global_store_dwordx2 v[194:195], v[174:175], off offset:288
	s_waitcnt lgkmcnt(0)
	v_add_f32_e32 v116, v115, v116
	v_xor_b32_e32 v115, 32, v209
	v_cmp_lt_i32_e32 vcc, v115, v117
	s_nop 1
	v_cndmask_b32_e32 v115, v209, v115, vcc
	v_lshlrev_b32_e32 v115, 2, v115
	ds_bpermute_b32 v117, v115, v116
	s_and_saveexec_b64 s[70:71], s[40:41]
	s_cbranch_execz .LBB0_1105
	s_waitcnt lgkmcnt(0)
	v_add_f32_e32 v116, v116, v117
	ds_write_b32 v171, v116
; __device__ __forceinline__ float bflo(unsigned w) { return __uint_as_float(w << 16); }
; __device__ __forceinline__ float bfhi(unsigned w) { return __uint_as_float(w & 0xffff0000u); }
; __device__ __forceinline__ unsigned pk2(float lo, float hi) { return pg8::cvt_pk_bf16(lo, hi); }
;     __device__ __forceinline__ void operator()(const f32x4 (&acc)[2][2][4][2], const Unit& u, int wr, int wc, int fr, int fq) const {
;     ...
;             for (int gg = 0; gg < 4; ++gg) {
;                 const int g = hb * 4 + gg, ai = g >> 2, m = g & 3, row = row0 + ai * 128 + m * 16;
;                 const size_t off = (size_t)row * D + col0;
;                 float ss = 0.f;
; #pragma unroll
;                 for (int k = 0; k < 4; ++k) { const int bj = k >> 1, n = k & 1; const size_t o = off + bj * 128 + n * 16; const f32x4 a = acc[ai][bj][m][n] * scale; const u32x2v w0 = rin[gg][k];
;                     f32x4 r; r[0] = bflo(w0.x) + a[0]; r[1] = bfhi(w0.x) + a[1]; r[2] = bflo(w0.y) + a[2]; r[3] = bfhi(w0.y) + a[3];
;                     u32x2v w; w.x = pk2(r[0], r[1]); w.y = pk2(r[2], r[3]); *(u32x2v*)(out + o) = w; ss += (r[0] * r[0] + r[1] * r[1]) + (r[2] * r[2] + r[3] * r[3]); }
;                 ss += __shfl_xor(ss, 16); ss += __shfl_xor(ss, 32);
;                 if (fq == 0) part[(ai * 128 + wr * 64 + m * 16 + fr) * 4 + wc] = ss;
.LBB0_1105:
	s_or_b64 exec, exec, s[70:71]
	s_mov_b32 s91, s90
	s_waitcnt lgkmcnt(0)
	v_lshl_add_u64 v[116:117], v[118:119], 0, v[166:167]
	v_pk_mul_f32 v[110:111], v[110:111], s[90:91]
	v_lshlrev_b32_e32 v166, 16, v156
	s_mov_b32 s70, s90
	s_mov_b32 s71, s90
	v_add_f32_e32 v166, v110, v166
	v_and_b32_e32 v110, 0xffff0000, v156
	v_pk_mul_f32 v[112:113], v[112:113], s[70:71]
	v_add_f32_e32 v156, v111, v110
	v_lshlrev_b32_e32 v110, 16, v157
	v_add_f32_e32 v112, v112, v110
	v_and_b32_e32 v110, 0xffff0000, v157
	v_add_f32_e32 v113, v113, v110
	v_cvt_pk_bf16_f32 v110, v166, v156
	v_cvt_pk_bf16_f32 v111, v112, v113
	global_store_dwordx2 v[116:117], v[110:111], off
	v_mul_f32_e32 v110, v156, v156
	v_mul_f32_e32 v111, v113, v113
	v_fmac_f32_e32 v110, v166, v166
	v_fmac_f32_e32 v111, v112, v112
	v_add_f32_e32 v110, v110, v111
	v_pk_mul_f32 v[106:107], v[106:107], s[90:91]
	v_lshlrev_b32_e32 v111, 16, v154
	v_add_f32_e32 v111, v106, v111
	v_and_b32_e32 v106, 0xffff0000, v154
	v_pk_mul_f32 v[108:109], v[108:109], s[70:71]
	v_add_f32_e32 v107, v107, v106
	v_lshlrev_b32_e32 v106, 16, v155
	v_add_f32_e32 v108, v108, v106
	v_and_b32_e32 v106, 0xffff0000, v155
	v_add_f32_e32 v109, v109, v106
	v_cvt_pk_bf16_f32 v106, v111, v107
	v_mul_f32_e32 v107, v107, v107
	v_fmac_f32_e32 v107, v111, v111
	v_mul_f32_e32 v111, v109, v109
	v_fmac_f32_e32 v111, v108, v108
	v_add_f32_e32 v107, v107, v111
	v_add_f32_e32 v107, v110, v107
	v_pk_mul_f32 v[102:103], v[102:103], s[90:91]
	v_lshlrev_b32_e32 v110, 16, v152
	v_add_f32_e32 v102, v102, v110
	v_and_b32_e32 v110, 0xffff0000, v152
	v_pk_mul_f32 v[104:105], v[104:105], s[70:71]
	v_add_f32_e32 v103, v103, v110
	v_lshlrev_b32_e32 v110, 16, v153
	v_add_f32_e32 v104, v104, v110
	v_and_b32_e32 v110, 0xffff0000, v153
	v_add_f32_e32 v105, v105, v110
	v_mul_f32_e32 v110, v103, v103
	v_mul_f32_e32 v111, v105, v105
	v_fmac_f32_e32 v110, v102, v102
	v_fmac_f32_e32 v111, v104, v104
	v_add_f32_e32 v110, v110, v111
	v_add_f32_e32 v107, v107, v110
	v_pk_mul_f32 v[98:99], v[98:99], s[90:91]
	v_lshlrev_b32_e32 v110, 16, v150
	v_add_f32_e32 v110, v98, v110
	v_and_b32_e32 v98, 0xffff0000, v150
	v_pk_mul_f32 v[100:101], v[100:101], s[70:71]
	v_add_f32_e32 v111, v99, v98
	v_lshlrev_b32_e32 v98, 16, v151
	v_add_f32_e32 v112, v100, v98
	v_and_b32_e32 v98, 0xffff0000, v151
	v_add_f32_e32 v113, v101, v98
	v_mul_f32_e32 v98, v111, v111
	v_mul_f32_e32 v99, v113, v113
	v_fmac_f32_e32 v98, v110, v110
	v_fmac_f32_e32 v99, v112, v112
	v_add_f32_e32 v98, v98, v99
	v_add_f32_e32 v98, v107, v98
	ds_bpermute_b32 v99, v114, v98
	v_cvt_pk_bf16_f32 v107, v108, v109
	global_store_dwordx2 v[116:117], v[106:107], off offset:32
	v_cvt_pk_bf16_f32 v100, v102, v103
	v_cvt_pk_bf16_f32 v101, v104, v105
	s_waitcnt lgkmcnt(0)
	v_add_f32_e32 v98, v98, v99
	ds_bpermute_b32 v99, v115, v98
	global_store_dwordx2 v[116:117], v[100:101], off offset:256
	v_cvt_pk_bf16_f32 v100, v110, v111
	v_cvt_pk_bf16_f32 v101, v112, v113
	global_store_dwordx2 v[116:117], v[100:101], off offset:288
	s_and_saveexec_b64 s[92:93], s[40:41]
	s_cbranch_execz .LBB0_1107
	s_waitcnt lgkmcnt(0)
	v_add_f32_e32 v98, v98, v99
	ds_write_b32 v171, v98 offset:256
.LBB0_1107:
	s_or_b64 exec, exec, s[92:93]
	v_pk_mul_f32 v[94:95], v[94:95], s[90:91]
	v_lshlrev_b32_e32 v100, 16, v146
	v_add_f32_e32 v100, v94, v100
	v_and_b32_e32 v94, 0xffff0000, v146
	v_pk_mul_f32 v[96:97], v[96:97], s[70:71]
	v_add_f32_e32 v101, v95, v94
	v_lshlrev_b32_e32 v94, 16, v147
	v_add_f32_e32 v96, v96, v94
	v_and_b32_e32 v94, 0xffff0000, v147
	s_waitcnt lgkmcnt(0)
	v_lshl_add_u64 v[98:99], v[118:119], 0, v[148:149]
	v_add_f32_e32 v97, v97, v94
	v_cvt_pk_bf16_f32 v94, v100, v101
	v_cvt_pk_bf16_f32 v95, v96, v97
	global_store_dwordx2 v[98:99], v[94:95], off
	v_mul_f32_e32 v94, v101, v101
	v_mul_f32_e32 v95, v97, v97
	v_fmac_f32_e32 v94, v100, v100
	v_fmac_f32_e32 v95, v96, v96
	v_add_f32_e32 v94, v94, v95
	v_pk_mul_f32 v[90:91], v[90:91], s[90:91]
	v_lshlrev_b32_e32 v95, 16, v144
	v_add_f32_e32 v95, v90, v95
	v_and_b32_e32 v90, 0xffff0000, v144
	v_pk_mul_f32 v[92:93], v[92:93], s[70:71]
	v_add_f32_e32 v91, v91, v90
	v_lshlrev_b32_e32 v90, 16, v145
	v_add_f32_e32 v92, v92, v90
	v_and_b32_e32 v90, 0xffff0000, v145
	v_add_f32_e32 v93, v93, v90
	v_cvt_pk_bf16_f32 v90, v95, v91
	v_mul_f32_e32 v91, v91, v91
	v_fmac_f32_e32 v91, v95, v95
	v_mul_f32_e32 v95, v93, v93
	v_fmac_f32_e32 v95, v92, v92
	v_add_f32_e32 v91, v91, v95
	v_add_f32_e32 v91, v94, v91
	v_pk_mul_f32 v[86:87], v[86:87], s[90:91]
	v_lshlrev_b32_e32 v94, 16, v142
	v_add_f32_e32 v86, v86, v94
	v_and_b32_e32 v94, 0xffff0000, v142
	v_pk_mul_f32 v[88:89], v[88:89], s[70:71]
	v_add_f32_e32 v87, v87, v94
	v_lshlrev_b32_e32 v94, 16, v143
	v_add_f32_e32 v88, v88, v94
	v_and_b32_e32 v94, 0xffff0000, v143
	v_add_f32_e32 v89, v89, v94
	v_mul_f32_e32 v94, v87, v87
	v_mul_f32_e32 v95, v89, v89
	v_fmac_f32_e32 v94, v86, v86
	v_fmac_f32_e32 v95, v88, v88
	v_add_f32_e32 v94, v94, v95
	v_add_f32_e32 v91, v91, v94
	v_pk_mul_f32 v[82:83], v[82:83], s[90:91]
	v_lshlrev_b32_e32 v94, 16, v140
	v_add_f32_e32 v94, v82, v94
	v_and_b32_e32 v82, 0xffff0000, v140
	v_pk_mul_f32 v[84:85], v[84:85], s[70:71]
	v_add_f32_e32 v95, v83, v82
	v_lshlrev_b32_e32 v82, 16, v141
	v_add_f32_e32 v96, v84, v82
	v_and_b32_e32 v82, 0xffff0000, v141
	v_add_f32_e32 v97, v85, v82
	v_mul_f32_e32 v82, v95, v95
	v_mul_f32_e32 v83, v97, v97
	v_fmac_f32_e32 v82, v94, v94
	v_fmac_f32_e32 v83, v96, v96
	v_add_f32_e32 v82, v82, v83
	v_add_f32_e32 v82, v91, v82
	ds_bpermute_b32 v83, v114, v82
	v_cvt_pk_bf16_f32 v91, v92, v93
	global_store_dwordx2 v[98:99], v[90:91], off offset:32
	v_cvt_pk_bf16_f32 v84, v86, v87
	v_cvt_pk_bf16_f32 v85, v88, v89
	s_waitcnt lgkmcnt(0)
	v_add_f32_e32 v82, v82, v83
	ds_bpermute_b32 v83, v115, v82
	global_store_dwordx2 v[98:99], v[84:85], off offset:256
	v_cvt_pk_bf16_f32 v84, v94, v95
	v_cvt_pk_bf16_f32 v85, v96, v97
	global_store_dwordx2 v[98:99], v[84:85], off offset:288
	s_and_saveexec_b64 s[70:71], s[40:41]
	s_cbranch_execz .LBB0_1109
	s_waitcnt lgkmcnt(0)
	v_add_f32_e32 v82, v82, v83
	ds_write_b32 v171, v82 offset:512
; __device__ __forceinline__ float bflo(unsigned w) { return __uint_as_float(w << 16); }
; __device__ __forceinline__ float bfhi(unsigned w) { return __uint_as_float(w & 0xffff0000u); }
; __device__ __forceinline__ unsigned pk2(float lo, float hi) { return pg8::cvt_pk_bf16(lo, hi); }
;     __device__ __forceinline__ void operator()(const f32x4 (&acc)[2][2][4][2], const Unit& u, int wr, int wc, int fr, int fq) const {
;     ...
;             for (int gg = 0; gg < 4; ++gg) { const int g = hb * 4 + gg; const size_t offn = (size_t)(row0 + (g >> 2) * 128 + (g & 3) * 16) * D + col0;
; #pragma unroll
;                 for (int k = 0; k < 4; ++k) rin[gg][k] = *(const u32x2v*)(in + offn + (k >> 1) * 128 + (k & 1) * 16); }
; #pragma unroll
;             for (int gg = 0; gg < 4; ++gg) {
;                 const int g = hb * 4 + gg, ai = g >> 2, m = g & 3, row = row0 + ai * 128 + m * 16;
;                 const size_t off = (size_t)row * D + col0;
;                 float ss = 0.f;
; #pragma unroll
;                 for (int k = 0; k < 4; ++k) { const int bj = k >> 1, n = k & 1; const size_t o = off + bj * 128 + n * 16; const f32x4 a = acc[ai][bj][m][n] * scale; const u32x2v w0 = rin[gg][k];
;                     f32x4 r; r[0] = bflo(w0.x) + a[0]; r[1] = bfhi(w0.x) + a[1]; r[2] = bflo(w0.y) + a[2]; r[3] = bfhi(w0.y) + a[3];
;                     u32x2v w; w.x = pk2(r[0], r[1]); w.y = pk2(r[2], r[3]); *(u32x2v*)(out + o) = w; ss += (r[0] * r[0] + r[1] * r[1]) + (r[2] * r[2] + r[3] * r[3]); }
;                 ss += __shfl_xor(ss, 16); ss += __shfl_xor(ss, 32);
;                 if (fq == 0) part[(ai * 128 + wr * 64 + m * 16 + fr) * 4 + wc] = ss;
.LBB0_1109:
	s_or_b64 exec, exec, s[70:71]
	v_pk_mul_f32 v[78:79], v[78:79], s[90:91]
	v_lshlrev_b32_e32 v84, 16, v126
	s_mov_b32 s70, s90
	s_mov_b32 s71, s90
	v_add_f32_e32 v84, v78, v84
	v_and_b32_e32 v78, 0xffff0000, v126
	v_pk_mul_f32 v[80:81], v[80:81], s[70:71]
	v_add_f32_e32 v85, v79, v78
	v_lshlrev_b32_e32 v78, 16, v127
	v_add_f32_e32 v80, v80, v78
	v_and_b32_e32 v78, 0xffff0000, v127
	s_waitcnt lgkmcnt(0)
	v_lshl_add_u64 v[82:83], v[118:119], 0, v[128:129]
	v_add_f32_e32 v81, v81, v78
	v_cvt_pk_bf16_f32 v78, v84, v85
	v_cvt_pk_bf16_f32 v79, v80, v81
	global_store_dwordx2 v[82:83], v[78:79], off
	v_mul_f32_e32 v78, v85, v85
	v_mul_f32_e32 v79, v81, v81
	v_fmac_f32_e32 v78, v84, v84
	v_fmac_f32_e32 v79, v80, v80
	v_add_f32_e32 v78, v78, v79
	v_pk_mul_f32 v[74:75], v[74:75], s[90:91]
	v_lshlrev_b32_e32 v79, 16, v124
	v_add_f32_e32 v79, v74, v79
	v_and_b32_e32 v74, 0xffff0000, v124
	v_pk_mul_f32 v[76:77], v[76:77], s[70:71]
	v_add_f32_e32 v75, v75, v74
	v_lshlrev_b32_e32 v74, 16, v125
	v_add_f32_e32 v76, v76, v74
	v_and_b32_e32 v74, 0xffff0000, v125
	v_add_f32_e32 v77, v77, v74
	v_cvt_pk_bf16_f32 v74, v79, v75
	v_mul_f32_e32 v75, v75, v75
	v_fmac_f32_e32 v75, v79, v79
	v_mul_f32_e32 v79, v77, v77
	v_fmac_f32_e32 v79, v76, v76
	v_add_f32_e32 v75, v75, v79
	v_add_f32_e32 v75, v78, v75
	v_pk_mul_f32 v[70:71], v[70:71], s[90:91]
	v_lshlrev_b32_e32 v78, 16, v122
	v_add_f32_e32 v70, v70, v78
	v_and_b32_e32 v78, 0xffff0000, v122
	v_pk_mul_f32 v[72:73], v[72:73], s[70:71]
	v_add_f32_e32 v71, v71, v78
	v_lshlrev_b32_e32 v78, 16, v123
	v_add_f32_e32 v72, v72, v78
	v_and_b32_e32 v78, 0xffff0000, v123
	v_add_f32_e32 v73, v73, v78
	v_mul_f32_e32 v78, v71, v71
	v_mul_f32_e32 v79, v73, v73
	v_fmac_f32_e32 v78, v70, v70
	v_fmac_f32_e32 v79, v72, v72
	v_add_f32_e32 v78, v78, v79
	v_add_f32_e32 v75, v75, v78
	v_pk_mul_f32 v[66:67], v[66:67], s[90:91]
	v_lshlrev_b32_e32 v78, 16, v120
	v_add_f32_e32 v78, v66, v78
	v_and_b32_e32 v66, 0xffff0000, v120
	v_pk_mul_f32 v[68:69], v[68:69], s[70:71]
	v_add_f32_e32 v79, v67, v66
	v_lshlrev_b32_e32 v66, 16, v121
	v_add_f32_e32 v80, v68, v66
	v_and_b32_e32 v66, 0xffff0000, v121
	v_add_f32_e32 v81, v69, v66
	v_mul_f32_e32 v66, v79, v79
	v_mul_f32_e32 v67, v81, v81
	v_fmac_f32_e32 v66, v78, v78
	v_fmac_f32_e32 v67, v80, v80
	v_add_f32_e32 v66, v66, v67
	v_add_f32_e32 v66, v75, v66
	ds_bpermute_b32 v67, v114, v66
	v_cvt_pk_bf16_f32 v75, v76, v77
	global_store_dwordx2 v[82:83], v[74:75], off offset:32
	v_cvt_pk_bf16_f32 v68, v70, v71
	v_cvt_pk_bf16_f32 v69, v72, v73
	s_waitcnt lgkmcnt(0)
	v_add_f32_e32 v66, v66, v67
	ds_bpermute_b32 v67, v115, v66
	global_store_dwordx2 v[82:83], v[68:69], off offset:256
	v_cvt_pk_bf16_f32 v68, v78, v79
	v_cvt_pk_bf16_f32 v69, v80, v81
	global_store_dwordx2 v[82:83], v[68:69], off offset:288
	s_and_saveexec_b64 s[92:93], s[40:41]
	s_cbranch_execz .LBB0_1111
	s_waitcnt lgkmcnt(0)
	v_add_f32_e32 v66, v66, v67
	ds_write_b32 v171, v66 offset:768
.LBB0_1111:
	s_or_b64 exec, exec, s[92:93]
	s_waitcnt lgkmcnt(0)
	v_lshlrev_b64 v[66:67], 11, v[138:139]
	v_lshl_add_u64 v[98:99], v[66:67], 0, s[88:89]
	v_lshl_add_u64 v[68:69], v[136:137], 0, v[98:99]
	global_load_dwordx2 v[102:103], v[68:69], off
	global_load_dwordx2 v[104:105], v[68:69], off offset:32
	global_load_dwordx2 v[100:101], v[68:69], off offset:256
	global_load_dwordx2 v[96:97], v[68:69], off offset:288
	s_mov_b64 s[56:57], 0x48000
	v_lshl_add_u64 v[94:95], v[66:67], 0, s[56:57]
	s_mov_b64 s[56:57], 0x50000
	v_lshl_add_u64 v[84:85], v[66:67], 0, s[56:57]
	s_mov_b64 s[56:57], 0x58000
	v_lshl_add_u64 v[68:69], v[136:137], 0, v[94:95]
	v_lshl_add_u64 v[70:71], v[66:67], 0, s[56:57]
	global_load_dwordx2 v[92:93], v[68:69], off
	global_load_dwordx2 v[90:91], v[68:69], off offset:32
	global_load_dwordx2 v[88:89], v[68:69], off offset:256
	global_load_dwordx2 v[86:87], v[68:69], off offset:288
	v_lshl_add_u64 v[68:69], v[136:137], 0, v[84:85]
	v_lshl_add_u64 v[66:67], v[136:137], 0, v[70:71]
	global_load_dwordx2 v[82:83], v[68:69], off
	global_load_dwordx2 v[80:81], v[68:69], off offset:32
	global_load_dwordx2 v[78:79], v[68:69], off offset:256
	global_load_dwordx2 v[74:75], v[68:69], off offset:288
	global_load_dwordx2 v[76:77], v[66:67], off
	global_load_dwordx2 v[72:73], v[66:67], off offset:32
	s_nop 0
	global_load_dwordx2 v[68:69], v[66:67], off offset:256
	s_nop 0
	global_load_dwordx2 v[66:67], v[66:67], off offset:288
	v_pk_mul_f32 v[62:63], v[62:63], s[90:91]
	v_pk_mul_f32 v[64:65], v[64:65], s[70:71]
	v_lshl_add_u64 v[98:99], v[118:119], 0, v[98:99]
	v_pk_mul_f32 v[58:59], v[58:59], s[90:91]
	v_pk_mul_f32 v[60:61], v[60:61], s[70:71]
	v_pk_mul_f32 v[54:55], v[54:55], s[90:91]
	v_pk_mul_f32 v[56:57], v[56:57], s[70:71]
	v_pk_mul_f32 v[50:51], v[50:51], s[90:91]
	v_pk_mul_f32 v[52:53], v[52:53], s[70:71]
	s_waitcnt vmcnt(0) lgkmcnt(0)
; __device__ __forceinline__ float bflo(unsigned w) { return __uint_as_float(w << 16); }
; __device__ __forceinline__ float bfhi(unsigned w) { return __uint_as_float(w & 0xffff0000u); }
; __device__ __forceinline__ unsigned pk2(float lo, float hi) { return pg8::cvt_pk_bf16(lo, hi); }
;     __device__ __forceinline__ void operator()(const f32x4 (&acc)[2][2][4][2], const Unit& u, int wr, int wc, int fr, int fq) const {
;     ...
;             for (int gg = 0; gg < 4; ++gg) {
;                 const int g = hb * 4 + gg, ai = g >> 2, m = g & 3, row = row0 + ai * 128 + m * 16;
;                 const size_t off = (size_t)row * D + col0;
;                 float ss = 0.f;
; #pragma unroll
;                 for (int k = 0; k < 4; ++k) { const int bj = k >> 1, n = k & 1; const size_t o = off + bj * 128 + n * 16; const f32x4 a = acc[ai][bj][m][n] * scale; const u32x2v w0 = rin[gg][k];
;                     f32x4 r; r[0] = bflo(w0.x) + a[0]; r[1] = bfhi(w0.x) + a[1]; r[2] = bflo(w0.y) + a[2]; r[3] = bfhi(w0.y) + a[3];
;                     u32x2v w; w.x = pk2(r[0], r[1]); w.y = pk2(r[2], r[3]); *(u32x2v*)(out + o) = w; ss += (r[0] * r[0] + r[1] * r[1]) + (r[2] * r[2] + r[3] * r[3]); }
;                 ss += __shfl_xor(ss, 16); ss += __shfl_xor(ss, 32);
;                 if (fq == 0) part[(ai * 128 + wr * 64 + m * 16 + fr) * 4 + wc] = ss;
	v_lshlrev_b32_e32 v106, 16, v102
	v_add_f32_e32 v106, v62, v106
	v_and_b32_e32 v62, 0xffff0000, v102
	v_add_f32_e32 v102, v63, v62
	v_lshlrev_b32_e32 v62, 16, v103
	v_add_f32_e32 v64, v64, v62
	v_and_b32_e32 v62, 0xffff0000, v103
	v_add_f32_e32 v65, v65, v62
	v_cvt_pk_bf16_f32 v62, v106, v102
	v_cvt_pk_bf16_f32 v63, v64, v65
	global_store_dwordx2 v[98:99], v[62:63], off
	v_mul_f32_e32 v62, v102, v102
	v_mul_f32_e32 v63, v65, v65
	v_fmac_f32_e32 v62, v106, v106
	v_fmac_f32_e32 v63, v64, v64
	v_add_f32_e32 v62, v62, v63
	v_lshlrev_b32_e32 v63, 16, v104
	v_add_f32_e32 v63, v58, v63
	v_and_b32_e32 v58, 0xffff0000, v104
	v_add_f32_e32 v64, v59, v58
	v_lshlrev_b32_e32 v58, 16, v105
	v_add_f32_e32 v60, v60, v58
	v_and_b32_e32 v58, 0xffff0000, v105
	v_add_f32_e32 v61, v61, v58
	v_cvt_pk_bf16_f32 v58, v63, v64
	v_cvt_pk_bf16_f32 v59, v60, v61
	global_store_dwordx2 v[98:99], v[58:59], off offset:32
	v_mul_f32_e32 v58, v64, v64
	v_mul_f32_e32 v59, v61, v61
	v_fmac_f32_e32 v58, v63, v63
	v_fmac_f32_e32 v59, v60, v60
	v_add_f32_e32 v58, v58, v59
	v_lshlrev_b32_e32 v59, 16, v100
	v_add_f32_e32 v59, v54, v59
	v_and_b32_e32 v54, 0xffff0000, v100
	v_add_f32_e32 v60, v55, v54
	v_lshlrev_b32_e32 v54, 16, v101
	v_add_f32_e32 v56, v56, v54
	v_and_b32_e32 v54, 0xffff0000, v101
	v_add_f32_e32 v57, v57, v54
	v_cvt_pk_bf16_f32 v54, v59, v60
	v_cvt_pk_bf16_f32 v55, v56, v57
	global_store_dwordx2 v[98:99], v[54:55], off offset:256
	v_mul_f32_e32 v54, v60, v60
	v_mul_f32_e32 v55, v57, v57
	v_fmac_f32_e32 v54, v59, v59
	v_fmac_f32_e32 v55, v56, v56
	v_add_f32_e32 v54, v54, v55
	v_lshlrev_b32_e32 v55, 16, v96
	v_add_f32_e32 v55, v50, v55
	v_and_b32_e32 v50, 0xffff0000, v96
	v_add_f32_e32 v56, v51, v50
	v_lshlrev_b32_e32 v50, 16, v97
	v_add_f32_e32 v52, v52, v50
	v_and_b32_e32 v50, 0xffff0000, v97
	v_add_f32_e32 v53, v53, v50
	v_cvt_pk_bf16_f32 v50, v55, v56
	v_cvt_pk_bf16_f32 v51, v52, v53
	global_store_dwordx2 v[98:99], v[50:51], off offset:288
	v_mul_f32_e32 v50, v56, v56
	v_mul_f32_e32 v51, v53, v53
	v_add_f32_e32 v58, v62, v58
	v_fmac_f32_e32 v50, v55, v55
	v_fmac_f32_e32 v51, v52, v52
	v_add_f32_e32 v54, v58, v54
	v_add_f32_e32 v50, v50, v51
	v_add_f32_e32 v50, v54, v50
	ds_bpermute_b32 v51, v114, v50
	s_waitcnt lgkmcnt(0)
	v_add_f32_e32 v50, v50, v51
	ds_bpermute_b32 v51, v115, v50
	s_and_saveexec_b64 s[70:71], s[40:41]
	s_cbranch_execz .LBB0_1113
	s_waitcnt lgkmcnt(0)
	v_add_f32_e32 v50, v50, v51
	ds_write_b32 v171, v50 offset:2048
.LBB0_1113:
	s_or_b64 exec, exec, s[70:71]
	v_pk_mul_f32 v[46:47], v[46:47], s[90:91]
	v_lshlrev_b32_e32 v52, 16, v92
	s_mov_b32 s70, s90
	s_mov_b32 s71, s90
	v_add_f32_e32 v52, v46, v52
	v_and_b32_e32 v46, 0xffff0000, v92
	v_pk_mul_f32 v[48:49], v[48:49], s[70:71]
	v_add_f32_e32 v53, v47, v46
	v_lshlrev_b32_e32 v46, 16, v93
	v_add_f32_e32 v48, v48, v46
	v_and_b32_e32 v46, 0xffff0000, v93
	s_waitcnt lgkmcnt(0)
	v_lshl_add_u64 v[50:51], v[118:119], 0, v[94:95]
	v_add_f32_e32 v49, v49, v46
	v_cvt_pk_bf16_f32 v46, v52, v53
	v_cvt_pk_bf16_f32 v47, v48, v49
	global_store_dwordx2 v[50:51], v[46:47], off
	v_mul_f32_e32 v46, v53, v53
	v_mul_f32_e32 v47, v49, v49
	v_fmac_f32_e32 v46, v52, v52
	v_fmac_f32_e32 v47, v48, v48
	v_add_f32_e32 v46, v46, v47
	v_pk_mul_f32 v[42:43], v[42:43], s[90:91]
	v_lshlrev_b32_e32 v47, 16, v90
	v_add_f32_e32 v47, v42, v47
	v_and_b32_e32 v42, 0xffff0000, v90
	v_pk_mul_f32 v[44:45], v[44:45], s[70:71]
	v_add_f32_e32 v43, v43, v42
	v_lshlrev_b32_e32 v42, 16, v91
	v_add_f32_e32 v44, v44, v42
	v_and_b32_e32 v42, 0xffff0000, v91
	v_add_f32_e32 v45, v45, v42
	v_cvt_pk_bf16_f32 v42, v47, v43
	v_mul_f32_e32 v43, v43, v43
	v_fmac_f32_e32 v43, v47, v47
	v_mul_f32_e32 v47, v45, v45
	v_fmac_f32_e32 v47, v44, v44
	v_add_f32_e32 v43, v43, v47
	v_add_f32_e32 v43, v46, v43
	v_pk_mul_f32 v[38:39], v[38:39], s[90:91]
	v_lshlrev_b32_e32 v46, 16, v88
	v_add_f32_e32 v38, v38, v46
	v_and_b32_e32 v46, 0xffff0000, v88
	v_pk_mul_f32 v[40:41], v[40:41], s[70:71]
	v_add_f32_e32 v39, v39, v46
	v_lshlrev_b32_e32 v46, 16, v89
	v_add_f32_e32 v40, v40, v46
	v_and_b32_e32 v46, 0xffff0000, v89
	v_add_f32_e32 v41, v41, v46
	v_mul_f32_e32 v46, v39, v39
	v_mul_f32_e32 v47, v41, v41
	v_fmac_f32_e32 v46, v38, v38
	v_fmac_f32_e32 v47, v40, v40
	v_add_f32_e32 v46, v46, v47
	v_add_f32_e32 v43, v43, v46
	v_pk_mul_f32 v[34:35], v[34:35], s[90:91]
	v_lshlrev_b32_e32 v46, 16, v86
	v_add_f32_e32 v46, v34, v46
	v_and_b32_e32 v34, 0xffff0000, v86
	v_pk_mul_f32 v[36:37], v[36:37], s[70:71]
	v_add_f32_e32 v47, v35, v34
	v_lshlrev_b32_e32 v34, 16, v87
	v_add_f32_e32 v48, v36, v34
	v_and_b32_e32 v34, 0xffff0000, v87
	v_add_f32_e32 v49, v37, v34
	v_mul_f32_e32 v34, v47, v47
	v_mul_f32_e32 v35, v49, v49
	v_fmac_f32_e32 v34, v46, v46
	v_fmac_f32_e32 v35, v48, v48
	v_add_f32_e32 v34, v34, v35
	v_add_f32_e32 v34, v43, v34
	ds_bpermute_b32 v35, v114, v34
	v_cvt_pk_bf16_f32 v43, v44, v45
	global_store_dwordx2 v[50:51], v[42:43], off offset:32
	v_cvt_pk_bf16_f32 v36, v38, v39
	v_cvt_pk_bf16_f32 v37, v40, v41
	s_waitcnt lgkmcnt(0)
	v_add_f32_e32 v34, v34, v35
	ds_bpermute_b32 v35, v115, v34
	global_store_dwordx2 v[50:51], v[36:37], off offset:256
	v_cvt_pk_bf16_f32 v36, v46, v47
	v_cvt_pk_bf16_f32 v37, v48, v49
	global_store_dwordx2 v[50:51], v[36:37], off offset:288
	s_and_saveexec_b64 s[92:93], s[40:41]
	s_cbranch_execz .LBB0_1115
	s_waitcnt lgkmcnt(0)
	v_add_f32_e32 v34, v34, v35
	ds_write_b32 v171, v34 offset:2304
; #define LAS __attribute__((address_space(3)))
; __device__ __forceinline__ float bflo(unsigned w) { return __uint_as_float(w << 16); }
; __device__ __forceinline__ float bfhi(unsigned w) { return __uint_as_float(w & 0xffff0000u); }
; __device__ __forceinline__ unsigned pk2(float lo, float hi) { return pg8::cvt_pk_bf16(lo, hi); }
;     __device__ __forceinline__ void operator()(const f32x4 (&acc)[2][2][4][2], const Unit& u, int wr, int wc, int fr, int fq) const {
;     ...
;             for (int gg = 0; gg < 4; ++gg) {
;                 const int g = hb * 4 + gg, ai = g >> 2, m = g & 3, row = row0 + ai * 128 + m * 16;
;                 const size_t off = (size_t)row * D + col0;
;                 float ss = 0.f;
; #pragma unroll
;                 for (int k = 0; k < 4; ++k) { const int bj = k >> 1, n = k & 1; const size_t o = off + bj * 128 + n * 16; const f32x4 a = acc[ai][bj][m][n] * scale; const u32x2v w0 = rin[gg][k];
;                     f32x4 r; r[0] = bflo(w0.x) + a[0]; r[1] = bfhi(w0.x) + a[1]; r[2] = bflo(w0.y) + a[2]; r[3] = bfhi(w0.y) + a[3];
;                     u32x2v w; w.x = pk2(r[0], r[1]); w.y = pk2(r[2], r[3]); *(u32x2v*)(out + o) = w; ss += (r[0] * r[0] + r[1] * r[1]) + (r[2] * r[2] + r[3] * r[3]); }
;                 ss += __shfl_xor(ss, 16); ss += __shfl_xor(ss, 32);
;                 if (fq == 0) part[(ai * 128 + wr * 64 + m * 16 + fr) * 4 + wc] = ss;
;             }
;         }
;         asm volatile("s_waitcnt lgkmcnt(0)" ::: "memory"); __builtin_amdgcn_s_barrier(); asm volatile("" ::: "memory");
;         { int t = threadIdx.x; asm volatile("" : "+v"(t)); if (t < 256) { const f32x4 p = *(const LAS f32x4*)(part + t * 4); rss[(size_t)(u.pm * 256 + t) * 4 + u.pn] = (p[0] + p[1]) + (p[2] + p[3]); } }
.LBB0_1115:
	s_or_b64 exec, exec, s[92:93]
	v_pk_mul_f32 v[30:31], v[30:31], s[90:91]
	v_lshlrev_b32_e32 v36, 16, v82
	v_add_f32_e32 v36, v30, v36
	v_and_b32_e32 v30, 0xffff0000, v82
	v_pk_mul_f32 v[32:33], v[32:33], s[70:71]
	v_add_f32_e32 v37, v31, v30
	v_lshlrev_b32_e32 v30, 16, v83
	v_add_f32_e32 v32, v32, v30
	v_and_b32_e32 v30, 0xffff0000, v83
	s_waitcnt lgkmcnt(0)
	v_lshl_add_u64 v[34:35], v[118:119], 0, v[84:85]
	v_add_f32_e32 v33, v33, v30
	v_cvt_pk_bf16_f32 v30, v36, v37
	v_cvt_pk_bf16_f32 v31, v32, v33
	global_store_dwordx2 v[34:35], v[30:31], off
	v_mul_f32_e32 v30, v37, v37
	v_mul_f32_e32 v31, v33, v33
	v_fmac_f32_e32 v30, v36, v36
	v_fmac_f32_e32 v31, v32, v32
	v_add_f32_e32 v30, v30, v31
	v_pk_mul_f32 v[26:27], v[26:27], s[90:91]
	v_lshlrev_b32_e32 v31, 16, v80
	v_add_f32_e32 v31, v26, v31
	v_and_b32_e32 v26, 0xffff0000, v80
	v_pk_mul_f32 v[28:29], v[28:29], s[70:71]
	v_add_f32_e32 v27, v27, v26
	v_lshlrev_b32_e32 v26, 16, v81
	v_add_f32_e32 v28, v28, v26
	v_and_b32_e32 v26, 0xffff0000, v81
	v_add_f32_e32 v29, v29, v26
	v_cvt_pk_bf16_f32 v26, v31, v27
	v_mul_f32_e32 v27, v27, v27
	v_fmac_f32_e32 v27, v31, v31
	v_mul_f32_e32 v31, v29, v29
	v_fmac_f32_e32 v31, v28, v28
	v_add_f32_e32 v27, v27, v31
	v_add_f32_e32 v27, v30, v27
	v_pk_mul_f32 v[22:23], v[22:23], s[90:91]
	v_lshlrev_b32_e32 v30, 16, v78
	v_add_f32_e32 v22, v22, v30
	v_and_b32_e32 v30, 0xffff0000, v78
	v_pk_mul_f32 v[24:25], v[24:25], s[70:71]
	v_add_f32_e32 v23, v23, v30
	v_lshlrev_b32_e32 v30, 16, v79
	v_add_f32_e32 v24, v24, v30
	v_and_b32_e32 v30, 0xffff0000, v79
	v_add_f32_e32 v25, v25, v30
	v_mul_f32_e32 v30, v23, v23
	v_mul_f32_e32 v31, v25, v25
	v_fmac_f32_e32 v30, v22, v22
	v_fmac_f32_e32 v31, v24, v24
	v_add_f32_e32 v30, v30, v31
	v_add_f32_e32 v27, v27, v30
	v_pk_mul_f32 v[18:19], v[18:19], s[90:91]
	v_lshlrev_b32_e32 v30, 16, v74
	v_add_f32_e32 v30, v18, v30
	v_and_b32_e32 v18, 0xffff0000, v74
	v_pk_mul_f32 v[20:21], v[20:21], s[70:71]
	v_add_f32_e32 v31, v19, v18
	v_lshlrev_b32_e32 v18, 16, v75
	v_add_f32_e32 v32, v20, v18
	v_and_b32_e32 v18, 0xffff0000, v75
	v_add_f32_e32 v33, v21, v18
	v_mul_f32_e32 v18, v31, v31
	v_mul_f32_e32 v19, v33, v33
	v_fmac_f32_e32 v18, v30, v30
	v_fmac_f32_e32 v19, v32, v32
	v_add_f32_e32 v18, v18, v19
	v_add_f32_e32 v18, v27, v18
	ds_bpermute_b32 v19, v114, v18
	v_cvt_pk_bf16_f32 v27, v28, v29
	global_store_dwordx2 v[34:35], v[26:27], off offset:32
	v_cvt_pk_bf16_f32 v20, v22, v23
	v_cvt_pk_bf16_f32 v21, v24, v25
	s_waitcnt lgkmcnt(0)
	v_add_f32_e32 v18, v18, v19
	ds_bpermute_b32 v19, v115, v18
	global_store_dwordx2 v[34:35], v[20:21], off offset:256
	v_cvt_pk_bf16_f32 v20, v30, v31
	v_cvt_pk_bf16_f32 v21, v32, v33
	global_store_dwordx2 v[34:35], v[20:21], off offset:288
	s_and_saveexec_b64 s[70:71], s[40:41]
	s_cbranch_execz .LBB0_1117
	s_waitcnt lgkmcnt(0)
	v_add_f32_e32 v18, v18, v19
	ds_write_b32 v171, v18 offset:2560
.LBB0_1117:
	s_or_b64 exec, exec, s[70:71]
	v_pk_mul_f32 v[14:15], v[14:15], s[90:91]
	v_lshlrev_b32_e32 v20, 16, v76
	s_mov_b32 s56, s90
	s_mov_b32 s57, s90
	v_add_f32_e32 v20, v14, v20
	v_and_b32_e32 v14, 0xffff0000, v76
	v_pk_mul_f32 v[16:17], v[16:17], s[56:57]
	v_add_f32_e32 v21, v15, v14
	v_lshlrev_b32_e32 v14, 16, v77
	v_add_f32_e32 v16, v16, v14
	v_and_b32_e32 v14, 0xffff0000, v77
	s_waitcnt lgkmcnt(0)
	v_lshl_add_u64 v[18:19], v[118:119], 0, v[70:71]
	v_add_f32_e32 v17, v17, v14
	v_cvt_pk_bf16_f32 v14, v20, v21
	v_cvt_pk_bf16_f32 v15, v16, v17
	global_store_dwordx2 v[18:19], v[14:15], off
	v_mul_f32_e32 v14, v21, v21
	v_mul_f32_e32 v15, v17, v17
	v_fmac_f32_e32 v14, v20, v20
	v_fmac_f32_e32 v15, v16, v16
	v_add_f32_e32 v14, v14, v15
	v_pk_mul_f32 v[10:11], v[10:11], s[90:91]
	v_lshlrev_b32_e32 v15, 16, v72
	v_add_f32_e32 v15, v10, v15
	v_and_b32_e32 v10, 0xffff0000, v72
	v_pk_mul_f32 v[12:13], v[12:13], s[56:57]
	v_add_f32_e32 v11, v11, v10
	v_lshlrev_b32_e32 v10, 16, v73
	v_add_f32_e32 v12, v12, v10
	v_and_b32_e32 v10, 0xffff0000, v73
	v_add_f32_e32 v13, v13, v10
	v_cvt_pk_bf16_f32 v10, v15, v11
	v_mul_f32_e32 v11, v11, v11
	v_fmac_f32_e32 v11, v15, v15
	v_mul_f32_e32 v15, v13, v13
	v_fmac_f32_e32 v15, v12, v12
	v_add_f32_e32 v11, v11, v15
	v_add_f32_e32 v11, v14, v11
	v_pk_mul_f32 v[6:7], v[6:7], s[90:91]
	v_lshlrev_b32_e32 v14, 16, v68
	v_add_f32_e32 v6, v6, v14
	v_and_b32_e32 v14, 0xffff0000, v68
	v_pk_mul_f32 v[8:9], v[8:9], s[56:57]
	v_add_f32_e32 v7, v7, v14
	v_lshlrev_b32_e32 v14, 16, v69
	v_add_f32_e32 v8, v8, v14
	v_and_b32_e32 v14, 0xffff0000, v69
	v_add_f32_e32 v9, v9, v14
	v_mul_f32_e32 v14, v7, v7
	v_mul_f32_e32 v15, v9, v9
	v_fmac_f32_e32 v14, v6, v6
	v_fmac_f32_e32 v15, v8, v8
	v_add_f32_e32 v14, v14, v15
	v_add_f32_e32 v11, v11, v14
	v_pk_mul_f32 v[2:3], v[2:3], s[90:91]
	v_lshlrev_b32_e32 v14, 16, v66
	v_add_f32_e32 v14, v2, v14
	v_and_b32_e32 v2, 0xffff0000, v66
	v_pk_mul_f32 v[4:5], v[4:5], s[56:57]
	v_add_f32_e32 v15, v3, v2
	v_lshlrev_b32_e32 v2, 16, v67
	v_add_f32_e32 v16, v4, v2
	v_and_b32_e32 v2, 0xffff0000, v67
	v_add_f32_e32 v17, v5, v2
	v_mul_f32_e32 v2, v15, v15
	v_mul_f32_e32 v3, v17, v17
	v_fmac_f32_e32 v2, v14, v14
	v_fmac_f32_e32 v3, v16, v16
	v_add_f32_e32 v2, v2, v3
	v_add_f32_e32 v2, v11, v2
	ds_bpermute_b32 v3, v114, v2
	v_cvt_pk_bf16_f32 v11, v12, v13
	global_store_dwordx2 v[18:19], v[10:11], off offset:32
	v_cvt_pk_bf16_f32 v4, v6, v7
	v_cvt_pk_bf16_f32 v5, v8, v9
	s_waitcnt lgkmcnt(0)
	v_add_f32_e32 v2, v2, v3
	ds_bpermute_b32 v3, v115, v2
	global_store_dwordx2 v[18:19], v[4:5], off offset:256
	v_cvt_pk_bf16_f32 v4, v14, v15
	v_cvt_pk_bf16_f32 v5, v16, v17
	global_store_dwordx2 v[18:19], v[4:5], off offset:288
	s_and_saveexec_b64 s[70:71], s[40:41]
	s_cbranch_execz .LBB0_1119
	s_waitcnt lgkmcnt(0)
	v_add_f32_e32 v2, v2, v3
	ds_write_b32 v171, v2 offset:2816
.LBB0_1119:
	s_or_b64 exec, exec, s[70:71]
	s_waitcnt lgkmcnt(0)
	s_barrier
	v_mov_b32_e32 v2, v158
	s_movk_i32 s56, 0x100
	s_nop 0
	v_cmp_gt_i32_e32 vcc, s56, v2
	s_and_saveexec_b64 s[70:71], vcc
	s_cbranch_execz .LBB0_1121
	s_waitcnt lgkmcnt(0)
	v_lshl_add_u32 v3, v2, 4, 0
	v_add_u32_e32 v3, 0x20000, v3
	ds_read_b128 v[4:7], v3
	v_add_u32_e32 v2, s13, v2
	v_ashrrev_i32_e32 v3, 31, v2
	s_ashr_i32 s13, s12, 31
	v_lshl_add_u64 v[2:3], v[2:3], 4, s[80:81]
	s_waitcnt lgkmcnt(0)
	v_mov_b32_e32 v8, v5
	v_mov_b32_e32 v9, v6
	v_mov_b32_e32 v5, v7
	v_pk_add_f32 v[4:5], v[8:9], v[4:5]
	v_lshl_add_u64 v[2:3], s[12:13], 2, v[2:3]
	v_add_f32_e32 v4, v4, v5
	global_store_dword v[2:3], v4, off

; __device__ __forceinline__ unsigned pk2(float lo, float hi) { return pg8::cvt_pk_bf16(lo, hi); }
;     __device__ __forceinline__ void operator()(const f32x4 (&acc)[2][2][4][2], const Unit& u, int wr, int wc, int fr, int fq) const {
;         bf16_t* O = O_; const float* rss = rss_; asm volatile("" : "+s"(O), "+s"(rss));
;         const int row0 = u.pm * 256 + wr * 64 + fr, col0 = u.pn * 128 + wc * 32 + 8 * fq;
;         float rsv[2][4];
;         { f32x4 pp[2][4];
; #pragma unroll
;           for (int ai = 0; ai < 2; ++ai)
; #pragma unroll
;             for (int m = 0; m < 4; ++m) pp[ai][m] = *(const f32x4*)(rss + (size_t)(row0 + ai * 128 + m * 16) * 4);
; #pragma unroll
;           for (int ai = 0; ai < 2; ++ai)
; #pragma unroll
;             for (int m = 0; m < 4; ++m) rsv[ai][m] = __builtin_amdgcn_rsqf(((pp[ai][m][0] + pp[ai][m][1]) + (pp[ai][m][2] + pp[ai][m][3])) * (1.0f / D) + EPS); }
; #pragma unroll
;         for (int ai = 0; ai < 2; ++ai)
; #pragma unroll
;             for (int m = 0; m < 4; ++m) {
;                 bf16_t* rowp = O + (size_t)(row0 + ai * 128 + m * 16) * FF + col0;
;                 const float rs = rsv[ai][m];
;                 float v[8];
; #pragma unroll
;                 for (int n = 0; n < 2; ++n)
; #pragma unroll
;                     for (int j = 0; j < 4; ++j) { const float g = acc[ai][0][m][n][j] * rs, up = acc[ai][1][m][n][j] * rs; v[n * 4 + j] = g * __builtin_amdgcn_rcpf(1.0f + __expf(-g)) * up; }
;                 u32x4v w; w.x = pk2(v[0], v[1]); w.y = pk2(v[2], v[3]); w.z = pk2(v[4], v[5]); w.w = pk2(v[6], v[7]);
;                 *(u32x4v*)rowp = w;
.LBB0_1195:
	v_readlane_b32 s68, v251, 4
	v_readlane_b32 s60, v250, 28
	v_lshl_add_u32 v178, s58, 8, v147
	v_readlane_b32 s69, v251, 5
	v_readlane_b32 s61, v250, 29
	v_ashrrev_i32_e32 v179, 31, v178
	v_or_b32_e32 v174, 16, v178
	v_lshl_add_u64 v[140:141], v[178:179], 4, s[60:61]
	global_load_dwordx4 v[180:183], v[140:141], off
	v_ashrrev_i32_e32 v175, 31, v174
	v_or_b32_e32 v170, 32, v178
	v_lshl_add_u64 v[140:141], v[174:175], 4, s[60:61]
	v_ashrrev_i32_e32 v171, 31, v170
	v_or_b32_e32 v166, 48, v178
	global_load_dwordx4 v[184:187], v[140:141], off
	v_lshl_add_u64 v[140:141], v[170:171], 4, s[60:61]
	v_ashrrev_i32_e32 v167, 31, v166
	v_add_u32_e32 v154, 0x80, v178
	global_load_dwordx4 v[188:191], v[140:141], off
	v_lshl_add_u64 v[140:141], v[166:167], 4, s[60:61]
	v_ashrrev_i32_e32 v155, 31, v154
	v_add_u32_e32 v150, 0x90, v178
	global_load_dwordx4 v[192:195], v[140:141], off
	v_lshl_add_u64 v[140:141], v[154:155], 4, s[60:61]
	v_ashrrev_i32_e32 v151, 31, v150
	v_add_u32_e32 v142, 0xa0, v178
	global_load_dwordx4 v[196:199], v[140:141], off
	v_lshl_add_u64 v[140:141], v[150:151], 4, s[60:61]
	v_ashrrev_i32_e32 v143, 31, v142
	global_load_dwordx4 v[200:203], v[140:141], off
	v_lshl_add_u64 v[140:141], v[142:143], 4, s[60:61]
	global_load_dwordx4 v[204:207], v[140:141], off
	v_add_u32_e32 v140, 0xb0, v178
	v_ashrrev_i32_e32 v141, 31, v140
	v_lshl_add_u64 v[144:145], v[140:141], 4, s[60:61]
	global_load_dwordx4 v[210:213], v[144:145], off
	s_and_b64 vcc, exec, s[40:41]
	s_waitcnt vmcnt(0) lgkmcnt(0)
	v_mov_b32_e32 v144, v181
	v_mov_b32_e32 v145, v182
	v_mov_b32_e32 v181, v183
	v_pk_add_f32 v[144:145], v[144:145], v[180:181]
	v_mov_b32_e32 v182, v126
	v_add_f32_e32 v141, v144, v145
	v_fmamk_f32 v141, v141, 0x3a800000, v159
	v_rsq_f32_e32 v180, v141
	v_mov_b32_e32 v183, v122
	v_mov_b32_e32 v144, v185
	v_mov_b32_e32 v145, v186
	v_pk_mul_f32 v[182:183], v[182:183], v[180:181] op_sel_hi:[1,0]
	v_mov_b32_e32 v185, v187
	v_mul_f32_e32 v122, 0xbfb8aa3b, v183
	v_exp_f32_e32 v122, v122
	v_pk_add_f32 v[144:145], v[144:145], v[184:185]
	v_add_f32_e32 v122, 1.0, v122
	v_rcp_f32_e32 v122, v122
	v_add_f32_e32 v141, v144, v145
	v_mov_b32_e32 v144, v189
	v_mov_b32_e32 v145, v190
	v_mul_f32_e32 v122, v183, v122
	v_mul_f32_e32 v126, v182, v122
	v_mov_b32_e32 v122, v127
	v_pk_mul_f32 v[122:123], v[122:123], v[180:181] op_sel_hi:[1,0]
	v_mov_b32_e32 v189, v191
	v_mul_f32_e32 v127, 0xbfb8aa3b, v123
	v_exp_f32_e32 v127, v127
	v_fmamk_f32 v141, v141, 0x3a800000, v159
	v_pk_add_f32 v[144:145], v[144:145], v[188:189]
	v_rsq_f32_e32 v176, v141
	v_add_f32_e32 v127, 1.0, v127
	v_rcp_f32_e32 v127, v127
	v_add_f32_e32 v141, v144, v145
	v_mov_b32_e32 v144, v193
	v_mov_b32_e32 v145, v194
	v_mul_f32_e32 v123, v123, v127
	v_mul_f32_e32 v127, v122, v123
	v_mov_b32_e32 v122, v128
	v_mov_b32_e32 v123, v124
	v_pk_mul_f32 v[122:123], v[122:123], v[180:181] op_sel_hi:[1,0]
	v_mov_b32_e32 v193, v195
	v_mul_f32_e32 v124, 0xbfb8aa3b, v123
	v_exp_f32_e32 v124, v124
	v_fmamk_f32 v141, v141, 0x3a800000, v159
	v_pk_add_f32 v[144:145], v[144:145], v[192:193]
	v_rsq_f32_e32 v172, v141
	v_add_f32_e32 v124, 1.0, v124
	v_rcp_f32_e32 v124, v124
	v_add_f32_e32 v141, v144, v145
	v_mov_b32_e32 v144, v197
	v_mov_b32_e32 v145, v198
	v_mul_f32_e32 v123, v123, v124
	v_mov_b32_e32 v124, v129
	v_mul_f32_e32 v128, v122, v123
	v_pk_mul_f32 v[122:123], v[124:125], v[180:181] op_sel_hi:[1,0]
	v_mov_b32_e32 v197, v199
	v_mul_f32_e32 v124, 0xbfb8aa3b, v123
	v_exp_f32_e32 v124, v124
	v_fmamk_f32 v141, v141, 0x3a800000, v159
	v_pk_add_f32 v[144:145], v[144:145], v[196:197]
	v_rsq_f32_e32 v168, v141
	v_add_f32_e32 v124, 1.0, v124
	v_rcp_f32_e32 v124, v124
	v_add_f32_e32 v141, v144, v145
	v_mov_b32_e32 v144, v201
	v_mov_b32_e32 v145, v202
	v_mul_f32_e32 v123, v123, v124
	v_mul_f32_e32 v124, v122, v123
	v_mov_b32_e32 v122, v118
	v_mov_b32_e32 v123, v114
	v_pk_mul_f32 v[122:123], v[122:123], v[180:181] op_sel_hi:[1,0]
	v_mov_b32_e32 v201, v203
	v_mul_f32_e32 v114, 0xbfb8aa3b, v123
	v_exp_f32_e32 v114, v114
	v_fmamk_f32 v141, v141, 0x3a800000, v159
	v_pk_add_f32 v[144:145], v[144:145], v[200:201]
	v_rsq_f32_e32 v156, v141
	v_add_f32_e32 v114, 1.0, v114
	v_rcp_f32_e32 v114, v114
	v_add_f32_e32 v141, v144, v145
	v_mov_b32_e32 v144, v205
	v_mov_b32_e32 v145, v206
	v_mul_f32_e32 v114, v123, v114
	v_mul_f32_e32 v122, v122, v114
	v_mov_b32_e32 v114, v119
	v_pk_mul_f32 v[114:115], v[114:115], v[180:181] op_sel_hi:[1,0]
	v_mov_b32_e32 v205, v207
	v_mul_f32_e32 v118, 0xbfb8aa3b, v115
	v_exp_f32_e32 v118, v118
	v_fmamk_f32 v141, v141, 0x3a800000, v159
	v_pk_add_f32 v[144:145], v[144:145], v[204:205]
	v_rsq_f32_e32 v152, v141
	v_add_f32_e32 v118, 1.0, v118
	v_rcp_f32_e32 v118, v118
	v_add_f32_e32 v141, v144, v145
	v_mov_b32_e32 v144, v211
	v_mov_b32_e32 v145, v212
	v_mul_f32_e32 v115, v115, v118
	v_mul_f32_e32 v123, v114, v115
	v_mov_b32_e32 v114, v120
	v_mov_b32_e32 v115, v116
	v_pk_mul_f32 v[114:115], v[114:115], v[180:181] op_sel_hi:[1,0]
	v_mov_b32_e32 v211, v213
	v_mul_f32_e32 v116, 0xbfb8aa3b, v115
	v_exp_f32_e32 v116, v116
	v_fmamk_f32 v141, v141, 0x3a800000, v159
	v_pk_add_f32 v[144:145], v[144:145], v[210:211]
	v_rsq_f32_e32 v148, v141
	v_add_f32_e32 v116, 1.0, v116
	v_rcp_f32_e32 v116, v116
	v_add_f32_e32 v141, v144, v145
	v_lshl_or_b32 v144, s57, 7, v153
	v_ashrrev_i32_e32 v145, 31, v144
	v_mul_f32_e32 v115, v115, v116
	v_mov_b32_e32 v116, v121
	v_mul_f32_e32 v120, v114, v115
	v_pk_mul_f32 v[114:115], v[116:117], v[180:181] op_sel_hi:[1,0]
	v_lshl_add_u64 v[144:145], v[144:145], 1, s[68:69]
	v_mul_f32_e32 v116, 0xbfb8aa3b, v115
	v_exp_f32_e32 v116, v116
	v_mad_i64_i32 v[118:119], s[58:59], v178, s85, v[144:145]
; __device__ __forceinline__ unsigned pk2(float lo, float hi) { return pg8::cvt_pk_bf16(lo, hi); }
;     __device__ __forceinline__ void operator()(const f32x4 (&acc)[2][2][4][2], const Unit& u, int wr, int wc, int fr, int fq) const {
;     ...
; #pragma unroll
;         for (int ai = 0; ai < 2; ++ai)
; #pragma unroll
;             for (int m = 0; m < 4; ++m) {
;                 bf16_t* rowp = O + (size_t)(row0 + ai * 128 + m * 16) * FF + col0;
;                 const float rs = rsv[ai][m];
;                 float v[8];
; #pragma unroll
;                 for (int n = 0; n < 2; ++n)
; #pragma unroll
;                     for (int j = 0; j < 4; ++j) { const float g = acc[ai][0][m][n][j] * rs, up = acc[ai][1][m][n][j] * rs; v[n * 4 + j] = g * __builtin_amdgcn_rcpf(1.0f + __expf(-g)) * up; }
;                 u32x4v w; w.x = pk2(v[0], v[1]); w.y = pk2(v[2], v[3]); w.z = pk2(v[4], v[5]); w.w = pk2(v[6], v[7]);
;                 *(u32x4v*)rowp = w;
	v_fmamk_f32 v141, v141, 0x3a800000, v159
	v_add_f32_e32 v116, 1.0, v116
	v_rcp_f32_e32 v116, v116
	v_rsq_f32_e32 v146, v141
	s_mov_b64 s[68:69], -1
	v_mul_f32_e32 v115, v115, v116
	v_mul_f32_e32 v117, v114, v115
	v_cvt_pk_bf16_f32 v114, v126, v127
	v_cvt_pk_bf16_f32 v115, v128, v124
	v_cvt_pk_bf16_f32 v116, v122, v123
	v_cvt_pk_bf16_f32 v117, v120, v117
	global_store_dwordx4 v[118:119], v[114:117], off
	s_nop 1
	v_mov_b32_e32 v114, v110
	v_mov_b32_e32 v115, v106
	v_pk_mul_f32 v[114:115], v[114:115], v[176:177] op_sel_hi:[1,0]
	s_nop 0
	v_mul_f32_e32 v106, 0xbfb8aa3b, v115
	v_exp_f32_e32 v106, v106
	s_nop 0
	v_add_f32_e32 v106, 1.0, v106
	v_rcp_f32_e32 v106, v106
	s_nop 0
	v_mul_f32_e32 v106, v115, v106
	v_mul_f32_e32 v110, v114, v106
	v_mov_b32_e32 v106, v111
	v_pk_mul_f32 v[106:107], v[106:107], v[176:177] op_sel_hi:[1,0]
	s_nop 0
	v_mul_f32_e32 v111, 0xbfb8aa3b, v107
	v_exp_f32_e32 v111, v111
	s_nop 0
	v_add_f32_e32 v111, 1.0, v111
	v_rcp_f32_e32 v111, v111
	s_nop 0
	v_mul_f32_e32 v107, v107, v111
	v_mul_f32_e32 v111, v106, v107
	v_mov_b32_e32 v106, v112
	v_mov_b32_e32 v107, v108
	v_pk_mul_f32 v[106:107], v[106:107], v[176:177] op_sel_hi:[1,0]
	s_nop 0
	v_mul_f32_e32 v108, 0xbfb8aa3b, v107
	v_exp_f32_e32 v108, v108
	s_nop 0
	v_add_f32_e32 v108, 1.0, v108
	v_rcp_f32_e32 v108, v108
	s_nop 0
	v_mul_f32_e32 v107, v107, v108
	v_mov_b32_e32 v108, v113
	v_mul_f32_e32 v112, v106, v107
	v_pk_mul_f32 v[106:107], v[108:109], v[176:177] op_sel_hi:[1,0]
	s_nop 0
	v_mul_f32_e32 v108, 0xbfb8aa3b, v107
	v_exp_f32_e32 v108, v108
	s_nop 0
	v_add_f32_e32 v108, 1.0, v108
	v_rcp_f32_e32 v108, v108
	s_nop 0
	v_mul_f32_e32 v107, v107, v108
	v_mul_f32_e32 v108, v106, v107
	v_mov_b32_e32 v106, v102
	v_mov_b32_e32 v107, v98
	v_pk_mul_f32 v[106:107], v[106:107], v[176:177] op_sel_hi:[1,0]
	s_nop 0
	v_mul_f32_e32 v98, 0xbfb8aa3b, v107
	v_exp_f32_e32 v98, v98
	s_nop 0
	v_add_f32_e32 v98, 1.0, v98
	v_rcp_f32_e32 v98, v98
	s_nop 0
	v_mul_f32_e32 v98, v107, v98
	v_mul_f32_e32 v106, v106, v98
	v_mov_b32_e32 v98, v103
	v_pk_mul_f32 v[98:99], v[98:99], v[176:177] op_sel_hi:[1,0]
	s_nop 0
	v_mul_f32_e32 v102, 0xbfb8aa3b, v99
	v_exp_f32_e32 v102, v102
	s_nop 0
	v_add_f32_e32 v102, 1.0, v102
	v_rcp_f32_e32 v102, v102
	s_nop 0
	v_mul_f32_e32 v99, v99, v102
	v_mul_f32_e32 v107, v98, v99
	v_mov_b32_e32 v98, v104
	v_mov_b32_e32 v99, v100
	v_pk_mul_f32 v[98:99], v[98:99], v[176:177] op_sel_hi:[1,0]
	v_mad_i64_i32 v[102:103], s[58:59], v174, s85, v[144:145]
	v_mul_f32_e32 v100, 0xbfb8aa3b, v99
	v_exp_f32_e32 v100, v100
	s_nop 0
	v_add_f32_e32 v100, 1.0, v100
	v_rcp_f32_e32 v100, v100
	s_nop 0
	v_mul_f32_e32 v99, v99, v100
	v_mov_b32_e32 v100, v105
	v_mul_f32_e32 v104, v98, v99
	v_pk_mul_f32 v[98:99], v[100:101], v[176:177] op_sel_hi:[1,0]
	s_nop 0
	v_mul_f32_e32 v100, 0xbfb8aa3b, v99
	v_exp_f32_e32 v100, v100
	s_nop 0
	v_add_f32_e32 v100, 1.0, v100
	v_rcp_f32_e32 v100, v100
	s_nop 0
	v_mul_f32_e32 v99, v99, v100
	v_mul_f32_e32 v101, v98, v99
	v_cvt_pk_bf16_f32 v98, v110, v111
	v_cvt_pk_bf16_f32 v99, v112, v108
	v_cvt_pk_bf16_f32 v100, v106, v107
	v_cvt_pk_bf16_f32 v101, v104, v101
	global_store_dwordx4 v[102:103], v[98:101], off
	s_nop 1
	v_mov_b32_e32 v98, v94
	v_mov_b32_e32 v99, v90
	v_pk_mul_f32 v[98:99], v[98:99], v[172:173] op_sel_hi:[1,0]
	s_nop 0
	v_mul_f32_e32 v90, 0xbfb8aa3b, v99
	v_exp_f32_e32 v90, v90
	s_nop 0
	v_add_f32_e32 v90, 1.0, v90
	v_rcp_f32_e32 v90, v90
	s_nop 0
	v_mul_f32_e32 v90, v99, v90
	v_mul_f32_e32 v94, v98, v90
	v_mov_b32_e32 v90, v95
	v_pk_mul_f32 v[90:91], v[90:91], v[172:173] op_sel_hi:[1,0]
	s_nop 0
	v_mul_f32_e32 v95, 0xbfb8aa3b, v91
	v_exp_f32_e32 v95, v95
	s_nop 0
	v_add_f32_e32 v95, 1.0, v95
	v_rcp_f32_e32 v95, v95
	s_nop 0
	v_mul_f32_e32 v91, v91, v95
	v_mul_f32_e32 v95, v90, v91
	v_mov_b32_e32 v90, v96
	v_mov_b32_e32 v91, v92
	v_pk_mul_f32 v[90:91], v[90:91], v[172:173] op_sel_hi:[1,0]
	s_nop 0
	v_mul_f32_e32 v92, 0xbfb8aa3b, v91
	v_exp_f32_e32 v92, v92
	s_nop 0
	v_add_f32_e32 v92, 1.0, v92
	v_rcp_f32_e32 v92, v92
	s_nop 0
	v_mul_f32_e32 v91, v91, v92
	v_mov_b32_e32 v92, v97
	v_mul_f32_e32 v96, v90, v91
	v_pk_mul_f32 v[90:91], v[92:93], v[172:173] op_sel_hi:[1,0]
	s_nop 0
	v_mul_f32_e32 v92, 0xbfb8aa3b, v91
	v_exp_f32_e32 v92, v92
	s_nop 0
	v_add_f32_e32 v92, 1.0, v92
	v_rcp_f32_e32 v92, v92
	s_nop 0
	v_mul_f32_e32 v91, v91, v92
	v_mul_f32_e32 v92, v90, v91
	v_mov_b32_e32 v90, v86
	v_mov_b32_e32 v91, v82
	v_pk_mul_f32 v[90:91], v[90:91], v[172:173] op_sel_hi:[1,0]
	s_nop 0
	v_mul_f32_e32 v82, 0xbfb8aa3b, v91
	v_exp_f32_e32 v82, v82
	s_nop 0
	v_add_f32_e32 v82, 1.0, v82
	v_rcp_f32_e32 v82, v82
	s_nop 0
	v_mul_f32_e32 v82, v91, v82
	v_mul_f32_e32 v90, v90, v82
	v_mov_b32_e32 v82, v87
	v_pk_mul_f32 v[82:83], v[82:83], v[172:173] op_sel_hi:[1,0]
	s_nop 0
	v_mul_f32_e32 v86, 0xbfb8aa3b, v83
	v_exp_f32_e32 v86, v86
	s_nop 0
	v_add_f32_e32 v86, 1.0, v86
	v_rcp_f32_e32 v86, v86
	s_nop 0
	v_mul_f32_e32 v83, v83, v86
	v_mul_f32_e32 v91, v82, v83
	v_mov_b32_e32 v82, v88
	v_mov_b32_e32 v83, v84
	v_pk_mul_f32 v[82:83], v[82:83], v[172:173] op_sel_hi:[1,0]
	v_mad_i64_i32 v[86:87], s[58:59], v170, s85, v[144:145]
	v_mul_f32_e32 v84, 0xbfb8aa3b, v83
	v_exp_f32_e32 v84, v84
	s_nop 0
	v_add_f32_e32 v84, 1.0, v84
	v_rcp_f32_e32 v84, v84
	s_nop 0
	v_mul_f32_e32 v83, v83, v84
	v_mov_b32_e32 v84, v89
	v_mul_f32_e32 v88, v82, v83
	v_pk_mul_f32 v[82:83], v[84:85], v[172:173] op_sel_hi:[1,0]
	s_nop 0
	v_mul_f32_e32 v84, 0xbfb8aa3b, v83
	v_exp_f32_e32 v84, v84
	s_nop 0
	v_add_f32_e32 v84, 1.0, v84
	v_rcp_f32_e32 v84, v84
	s_nop 0
	v_mul_f32_e32 v83, v83, v84
	v_mul_f32_e32 v85, v82, v83
	v_cvt_pk_bf16_f32 v82, v94, v95
	v_cvt_pk_bf16_f32 v83, v96, v92
; __device__ __forceinline__ unsigned pk2(float lo, float hi) { return pg8::cvt_pk_bf16(lo, hi); }
;     __device__ __forceinline__ void operator()(const f32x4 (&acc)[2][2][4][2], const Unit& u, int wr, int wc, int fr, int fq) const {
;     ...
; #pragma unroll
;         for (int ai = 0; ai < 2; ++ai)
; #pragma unroll
;             for (int m = 0; m < 4; ++m) {
;                 bf16_t* rowp = O + (size_t)(row0 + ai * 128 + m * 16) * FF + col0;
;                 const float rs = rsv[ai][m];
;                 float v[8];
; #pragma unroll
;                 for (int n = 0; n < 2; ++n)
; #pragma unroll
;                     for (int j = 0; j < 4; ++j) { const float g = acc[ai][0][m][n][j] * rs, up = acc[ai][1][m][n][j] * rs; v[n * 4 + j] = g * __builtin_amdgcn_rcpf(1.0f + __expf(-g)) * up; }
;                 u32x4v w; w.x = pk2(v[0], v[1]); w.y = pk2(v[2], v[3]); w.z = pk2(v[4], v[5]); w.w = pk2(v[6], v[7]);
;                 *(u32x4v*)rowp = w;
	v_cvt_pk_bf16_f32 v84, v90, v91
	v_cvt_pk_bf16_f32 v85, v88, v85
	global_store_dwordx4 v[86:87], v[82:85], off
	s_nop 1
	v_mov_b32_e32 v82, v78
	v_mov_b32_e32 v83, v74
	v_pk_mul_f32 v[82:83], v[82:83], v[168:169] op_sel_hi:[1,0]
	s_nop 0
	v_mul_f32_e32 v74, 0xbfb8aa3b, v83
	v_exp_f32_e32 v74, v74
	s_nop 0
	v_add_f32_e32 v74, 1.0, v74
	v_rcp_f32_e32 v74, v74
	s_nop 0
	v_mul_f32_e32 v74, v83, v74
	v_mul_f32_e32 v78, v82, v74
	v_mov_b32_e32 v74, v79
	v_pk_mul_f32 v[74:75], v[74:75], v[168:169] op_sel_hi:[1,0]
	s_nop 0
	v_mul_f32_e32 v79, 0xbfb8aa3b, v75
	v_exp_f32_e32 v79, v79
	s_nop 0
	v_add_f32_e32 v79, 1.0, v79
	v_rcp_f32_e32 v79, v79
	s_nop 0
	v_mul_f32_e32 v75, v75, v79
	v_mul_f32_e32 v79, v74, v75
	v_mov_b32_e32 v74, v80
	v_mov_b32_e32 v75, v76
	v_pk_mul_f32 v[74:75], v[74:75], v[168:169] op_sel_hi:[1,0]
	s_nop 0
	v_mul_f32_e32 v76, 0xbfb8aa3b, v75
	v_exp_f32_e32 v76, v76
	s_nop 0
	v_add_f32_e32 v76, 1.0, v76
	v_rcp_f32_e32 v76, v76
	s_nop 0
	v_mul_f32_e32 v75, v75, v76
	v_mov_b32_e32 v76, v81
	v_mul_f32_e32 v80, v74, v75
	v_pk_mul_f32 v[74:75], v[76:77], v[168:169] op_sel_hi:[1,0]
	s_nop 0
	v_mul_f32_e32 v76, 0xbfb8aa3b, v75
	v_exp_f32_e32 v76, v76
	s_nop 0
	v_add_f32_e32 v76, 1.0, v76
	v_rcp_f32_e32 v76, v76
	s_nop 0
	v_mul_f32_e32 v75, v75, v76
	v_mul_f32_e32 v76, v74, v75
	v_mov_b32_e32 v74, v70
	v_mov_b32_e32 v75, v66
	v_pk_mul_f32 v[74:75], v[74:75], v[168:169] op_sel_hi:[1,0]
	s_nop 0
	v_mul_f32_e32 v66, 0xbfb8aa3b, v75
	v_exp_f32_e32 v66, v66
	s_nop 0
	v_add_f32_e32 v66, 1.0, v66
	v_rcp_f32_e32 v66, v66
	s_nop 0
	v_mul_f32_e32 v66, v75, v66
	v_mul_f32_e32 v74, v74, v66
	v_mov_b32_e32 v66, v71
	v_pk_mul_f32 v[66:67], v[66:67], v[168:169] op_sel_hi:[1,0]
	s_nop 0
	v_mul_f32_e32 v70, 0xbfb8aa3b, v67
	v_exp_f32_e32 v70, v70
	s_nop 0
	v_add_f32_e32 v70, 1.0, v70
	v_rcp_f32_e32 v70, v70
	s_nop 0
	v_mul_f32_e32 v67, v67, v70
	v_mul_f32_e32 v75, v66, v67
	v_mov_b32_e32 v66, v72
	v_mov_b32_e32 v67, v68
	v_pk_mul_f32 v[66:67], v[66:67], v[168:169] op_sel_hi:[1,0]
	v_mad_i64_i32 v[70:71], s[58:59], v166, s85, v[144:145]
	v_mul_f32_e32 v68, 0xbfb8aa3b, v67
	v_exp_f32_e32 v68, v68
	s_nop 0
	v_add_f32_e32 v68, 1.0, v68
	v_rcp_f32_e32 v68, v68
	s_nop 0
	v_mul_f32_e32 v67, v67, v68
	v_mov_b32_e32 v68, v73
	v_mul_f32_e32 v72, v66, v67
	v_pk_mul_f32 v[66:67], v[68:69], v[168:169] op_sel_hi:[1,0]
	s_nop 0
	v_mul_f32_e32 v68, 0xbfb8aa3b, v67
	v_exp_f32_e32 v68, v68
	s_nop 0
	v_add_f32_e32 v68, 1.0, v68
	v_rcp_f32_e32 v68, v68
	s_nop 0
	v_mul_f32_e32 v67, v67, v68
	v_mul_f32_e32 v69, v66, v67
	v_cvt_pk_bf16_f32 v66, v78, v79
	v_cvt_pk_bf16_f32 v67, v80, v76
	v_cvt_pk_bf16_f32 v68, v74, v75
	v_cvt_pk_bf16_f32 v69, v72, v69
	global_store_dwordx4 v[70:71], v[66:69], off
	s_nop 1
	v_mov_b32_e32 v66, v62
	v_mov_b32_e32 v67, v58
	v_pk_mul_f32 v[66:67], v[66:67], v[156:157] op_sel_hi:[1,0]
	s_nop 0
	v_mul_f32_e32 v58, 0xbfb8aa3b, v67
	v_exp_f32_e32 v58, v58
	s_nop 0
	v_add_f32_e32 v58, 1.0, v58
	v_rcp_f32_e32 v58, v58
	s_nop 0
	v_mul_f32_e32 v58, v67, v58
	v_mul_f32_e32 v62, v66, v58
	v_mov_b32_e32 v58, v63
	v_pk_mul_f32 v[58:59], v[58:59], v[156:157] op_sel_hi:[1,0]
	s_nop 0
	v_mul_f32_e32 v63, 0xbfb8aa3b, v59
	v_exp_f32_e32 v63, v63
	s_nop 0
	v_add_f32_e32 v63, 1.0, v63
	v_rcp_f32_e32 v63, v63
	s_nop 0
	v_mul_f32_e32 v59, v59, v63
	v_mul_f32_e32 v63, v58, v59
	v_mov_b32_e32 v58, v64
	v_mov_b32_e32 v59, v60
	v_pk_mul_f32 v[58:59], v[58:59], v[156:157] op_sel_hi:[1,0]
	s_nop 0
	v_mul_f32_e32 v60, 0xbfb8aa3b, v59
	v_exp_f32_e32 v60, v60
	s_nop 0
	v_add_f32_e32 v60, 1.0, v60
	v_rcp_f32_e32 v60, v60
	s_nop 0
	v_mul_f32_e32 v59, v59, v60
	v_mov_b32_e32 v60, v65
	v_mul_f32_e32 v64, v58, v59
	v_pk_mul_f32 v[58:59], v[60:61], v[156:157] op_sel_hi:[1,0]
	s_nop 0
	v_mul_f32_e32 v60, 0xbfb8aa3b, v59
	v_exp_f32_e32 v60, v60
	s_nop 0
	v_add_f32_e32 v60, 1.0, v60
	v_rcp_f32_e32 v60, v60
	s_nop 0
	v_mul_f32_e32 v59, v59, v60
	v_mul_f32_e32 v60, v58, v59
	v_mov_b32_e32 v58, v54
	v_mov_b32_e32 v59, v50
	v_pk_mul_f32 v[58:59], v[58:59], v[156:157] op_sel_hi:[1,0]
	s_nop 0
	v_mul_f32_e32 v50, 0xbfb8aa3b, v59
	v_exp_f32_e32 v50, v50
	s_nop 0
	v_add_f32_e32 v50, 1.0, v50
	v_rcp_f32_e32 v50, v50
	s_nop 0
	v_mul_f32_e32 v50, v59, v50
	v_mul_f32_e32 v58, v58, v50
	v_mov_b32_e32 v50, v55
	v_pk_mul_f32 v[50:51], v[50:51], v[156:157] op_sel_hi:[1,0]
	s_nop 0
	v_mul_f32_e32 v54, 0xbfb8aa3b, v51
	v_exp_f32_e32 v54, v54
	s_nop 0
	v_add_f32_e32 v54, 1.0, v54
	v_rcp_f32_e32 v54, v54
	s_nop 0
	v_mul_f32_e32 v51, v51, v54
	v_mul_f32_e32 v59, v50, v51
	v_mov_b32_e32 v50, v56
	v_mov_b32_e32 v51, v52
	v_pk_mul_f32 v[50:51], v[50:51], v[156:157] op_sel_hi:[1,0]
	v_mad_i64_i32 v[54:55], s[58:59], v154, s85, v[144:145]
	v_mul_f32_e32 v52, 0xbfb8aa3b, v51
	v_exp_f32_e32 v52, v52
	s_nop 0
	v_add_f32_e32 v52, 1.0, v52
	v_rcp_f32_e32 v52, v52
	s_nop 0
	v_mul_f32_e32 v51, v51, v52
	v_mov_b32_e32 v52, v57
	v_mul_f32_e32 v56, v50, v51
	v_pk_mul_f32 v[50:51], v[52:53], v[156:157] op_sel_hi:[1,0]
	s_nop 0
	v_mul_f32_e32 v52, 0xbfb8aa3b, v51
	v_exp_f32_e32 v52, v52
	s_nop 0
	v_add_f32_e32 v52, 1.0, v52
	v_rcp_f32_e32 v52, v52
	s_nop 0
	v_mul_f32_e32 v51, v51, v52
	v_mul_f32_e32 v53, v50, v51
	v_cvt_pk_bf16_f32 v50, v62, v63
	v_cvt_pk_bf16_f32 v51, v64, v60
	v_cvt_pk_bf16_f32 v52, v58, v59
	v_cvt_pk_bf16_f32 v53, v56, v53
	global_store_dwordx4 v[54:55], v[50:53], off
	s_nop 1
	v_mov_b32_e32 v50, v46
	v_mov_b32_e32 v51, v42
	v_pk_mul_f32 v[50:51], v[50:51], v[152:153] op_sel_hi:[1,0]
	s_nop 0
	v_mul_f32_e32 v42, 0xbfb8aa3b, v51
	v_exp_f32_e32 v42, v42
	s_nop 0
	v_add_f32_e32 v42, 1.0, v42
	v_rcp_f32_e32 v42, v42
	s_nop 0
	v_mul_f32_e32 v42, v51, v42
	v_mul_f32_e32 v46, v50, v42
	v_mov_b32_e32 v42, v47
; __device__ __forceinline__ unsigned pk2(float lo, float hi) { return pg8::cvt_pk_bf16(lo, hi); }
;     __device__ __forceinline__ void operator()(const f32x4 (&acc)[2][2][4][2], const Unit& u, int wr, int wc, int fr, int fq) const {
;     ...
; #pragma unroll
;         for (int ai = 0; ai < 2; ++ai)
; #pragma unroll
;             for (int m = 0; m < 4; ++m) {
;                 bf16_t* rowp = O + (size_t)(row0 + ai * 128 + m * 16) * FF + col0;
;                 const float rs = rsv[ai][m];
;                 float v[8];
; #pragma unroll
;                 for (int n = 0; n < 2; ++n)
; #pragma unroll
;                     for (int j = 0; j < 4; ++j) { const float g = acc[ai][0][m][n][j] * rs, up = acc[ai][1][m][n][j] * rs; v[n * 4 + j] = g * __builtin_amdgcn_rcpf(1.0f + __expf(-g)) * up; }
;                 u32x4v w; w.x = pk2(v[0], v[1]); w.y = pk2(v[2], v[3]); w.z = pk2(v[4], v[5]); w.w = pk2(v[6], v[7]);
;                 *(u32x4v*)rowp = w;
	v_pk_mul_f32 v[42:43], v[42:43], v[152:153] op_sel_hi:[1,0]
	s_nop 0
	v_mul_f32_e32 v47, 0xbfb8aa3b, v43
	v_exp_f32_e32 v47, v47
	s_nop 0
	v_add_f32_e32 v47, 1.0, v47
	v_rcp_f32_e32 v47, v47
	s_nop 0
	v_mul_f32_e32 v43, v43, v47
	v_mul_f32_e32 v47, v42, v43
	v_mov_b32_e32 v42, v48
	v_mov_b32_e32 v43, v44
	v_pk_mul_f32 v[42:43], v[42:43], v[152:153] op_sel_hi:[1,0]
	s_nop 0
	v_mul_f32_e32 v44, 0xbfb8aa3b, v43
	v_exp_f32_e32 v44, v44
	s_nop 0
	v_add_f32_e32 v44, 1.0, v44
	v_rcp_f32_e32 v44, v44
	s_nop 0
	v_mul_f32_e32 v43, v43, v44
	v_mov_b32_e32 v44, v49
	v_mul_f32_e32 v48, v42, v43
	v_pk_mul_f32 v[42:43], v[44:45], v[152:153] op_sel_hi:[1,0]
	s_nop 0
	v_mul_f32_e32 v44, 0xbfb8aa3b, v43
	v_exp_f32_e32 v44, v44
	s_nop 0
	v_add_f32_e32 v44, 1.0, v44
	v_rcp_f32_e32 v44, v44
	s_nop 0
	v_mul_f32_e32 v43, v43, v44
	v_mul_f32_e32 v44, v42, v43
	v_mov_b32_e32 v42, v38
	v_mov_b32_e32 v43, v34
	v_pk_mul_f32 v[42:43], v[42:43], v[152:153] op_sel_hi:[1,0]
	s_nop 0
	v_mul_f32_e32 v34, 0xbfb8aa3b, v43
	v_exp_f32_e32 v34, v34
	s_nop 0
	v_add_f32_e32 v34, 1.0, v34
	v_rcp_f32_e32 v34, v34
	s_nop 0
	v_mul_f32_e32 v34, v43, v34
	v_mul_f32_e32 v42, v42, v34
	v_mov_b32_e32 v34, v39
	v_pk_mul_f32 v[34:35], v[34:35], v[152:153] op_sel_hi:[1,0]
	s_nop 0
	v_mul_f32_e32 v38, 0xbfb8aa3b, v35
	v_exp_f32_e32 v38, v38
	s_nop 0
	v_add_f32_e32 v38, 1.0, v38
	v_rcp_f32_e32 v38, v38
	s_nop 0
	v_mul_f32_e32 v35, v35, v38
	v_mul_f32_e32 v43, v34, v35
	v_mov_b32_e32 v34, v40
	v_mov_b32_e32 v35, v36
	v_pk_mul_f32 v[34:35], v[34:35], v[152:153] op_sel_hi:[1,0]
	v_mad_i64_i32 v[38:39], s[58:59], v150, s85, v[144:145]
	v_mul_f32_e32 v36, 0xbfb8aa3b, v35
	v_exp_f32_e32 v36, v36
	s_nop 0
	v_add_f32_e32 v36, 1.0, v36
	v_rcp_f32_e32 v36, v36
	s_nop 0
	v_mul_f32_e32 v35, v35, v36
	v_mov_b32_e32 v36, v41
	v_mul_f32_e32 v40, v34, v35
	v_pk_mul_f32 v[34:35], v[36:37], v[152:153] op_sel_hi:[1,0]
	s_nop 0
	v_mul_f32_e32 v36, 0xbfb8aa3b, v35
	v_exp_f32_e32 v36, v36
	s_nop 0
	v_add_f32_e32 v36, 1.0, v36
	v_rcp_f32_e32 v36, v36
	s_nop 0
	v_mul_f32_e32 v35, v35, v36
	v_mul_f32_e32 v37, v34, v35
	v_cvt_pk_bf16_f32 v34, v46, v47
	v_cvt_pk_bf16_f32 v35, v48, v44
	v_cvt_pk_bf16_f32 v36, v42, v43
	v_cvt_pk_bf16_f32 v37, v40, v37
	global_store_dwordx4 v[38:39], v[34:37], off
	s_nop 1
	v_mov_b32_e32 v34, v30
	v_mov_b32_e32 v35, v26
	v_pk_mul_f32 v[34:35], v[34:35], v[148:149] op_sel_hi:[1,0]
	s_nop 0
	v_mul_f32_e32 v26, 0xbfb8aa3b, v35
	v_exp_f32_e32 v26, v26
	s_nop 0
	v_add_f32_e32 v26, 1.0, v26
	v_rcp_f32_e32 v26, v26
	s_nop 0
	v_mul_f32_e32 v26, v35, v26
	v_mul_f32_e32 v30, v34, v26
	v_mov_b32_e32 v26, v31
	v_pk_mul_f32 v[26:27], v[26:27], v[148:149] op_sel_hi:[1,0]
	s_nop 0
	v_mul_f32_e32 v31, 0xbfb8aa3b, v27
	v_exp_f32_e32 v31, v31
	s_nop 0
	v_add_f32_e32 v31, 1.0, v31
	v_rcp_f32_e32 v31, v31
	s_nop 0
	v_mul_f32_e32 v27, v27, v31
	v_mul_f32_e32 v31, v26, v27
	v_mov_b32_e32 v26, v32
	v_mov_b32_e32 v27, v28
	v_pk_mul_f32 v[26:27], v[26:27], v[148:149] op_sel_hi:[1,0]
	s_nop 0
	v_mul_f32_e32 v28, 0xbfb8aa3b, v27
	v_exp_f32_e32 v28, v28
	s_nop 0
	v_add_f32_e32 v28, 1.0, v28
	v_rcp_f32_e32 v28, v28
	s_nop 0
	v_mul_f32_e32 v27, v27, v28
	v_mov_b32_e32 v28, v33
	v_mul_f32_e32 v32, v26, v27
	v_pk_mul_f32 v[26:27], v[28:29], v[148:149] op_sel_hi:[1,0]
	s_nop 0
	v_mul_f32_e32 v28, 0xbfb8aa3b, v27
	v_exp_f32_e32 v28, v28
	s_nop 0
	v_add_f32_e32 v28, 1.0, v28
	v_rcp_f32_e32 v28, v28
	s_nop 0
	v_mul_f32_e32 v27, v27, v28
	v_mul_f32_e32 v28, v26, v27
	v_mov_b32_e32 v26, v22
	v_mov_b32_e32 v27, v18
	v_pk_mul_f32 v[26:27], v[26:27], v[148:149] op_sel_hi:[1,0]
	s_nop 0
	v_mul_f32_e32 v18, 0xbfb8aa3b, v27
	v_exp_f32_e32 v18, v18
	s_nop 0
	v_add_f32_e32 v18, 1.0, v18
	v_rcp_f32_e32 v18, v18
	s_nop 0
	v_mul_f32_e32 v18, v27, v18
; #define PG8_BAR __builtin_amdgcn_s_barrier()
; __device__ __forceinline__ unsigned pk2(float lo, float hi) { return pg8::cvt_pk_bf16(lo, hi); }
; template <class Epi, class Sched, bool ALIGN_EPI = false, bool SP2 = false>
; __device__ __forceinline__ void gemm_phase(PG8_LAS unsigned char* lds, const Gemm g, const Sched& S, const Epi& E) {
;     ...
;         if constexpr (ALIGN_EPI) { if (wr == 0) PG8_BAR; }
;         if constexpr (!Epi::AFTER_DRAIN) { E(acc, cur, wr, wc, fr, fq); S.done(cur); }
;         if (!has_next) break;
; #pragma unroll
;         for (int a = 0; a < 2; ++a)
; #pragma unroll
;             for (int b = 0; b < 2; ++b)
; #pragma unroll
;                 for (int m = 0; m < 4; ++m)
; #pragma unroll
;                     for (int n = 0; n < 2; ++n) acc[a][b][m][n] = (f32x4){0.f, 0.f, 0.f, 0.f};
;         cur = nxt; cA = nA; cB = nB; ++ui;
;         if constexpr (ALIGN_EPI) { if (wr == 1) PG8_BAR; }
;     __device__ __forceinline__ void operator()(const f32x4 (&acc)[2][2][4][2], const Unit& u, int wr, int wc, int fr, int fq) const {
;     ...
; #pragma unroll
;         for (int ai = 0; ai < 2; ++ai)
; #pragma unroll
;             for (int m = 0; m < 4; ++m) {
;                 bf16_t* rowp = O + (size_t)(row0 + ai * 128 + m * 16) * FF + col0;
;                 const float rs = rsv[ai][m];
;                 float v[8];
; #pragma unroll
;                 for (int n = 0; n < 2; ++n)
; #pragma unroll
;                     for (int j = 0; j < 4; ++j) { const float g = acc[ai][0][m][n][j] * rs, up = acc[ai][1][m][n][j] * rs; v[n * 4 + j] = g * __builtin_amdgcn_rcpf(1.0f + __expf(-g)) * up; }
;                 u32x4v w; w.x = pk2(v[0], v[1]); w.y = pk2(v[2], v[3]); w.z = pk2(v[4], v[5]); w.w = pk2(v[6], v[7]);
;                 *(u32x4v*)rowp = w;
	v_mul_f32_e32 v26, v26, v18
	v_mov_b32_e32 v18, v23
	v_pk_mul_f32 v[18:19], v[18:19], v[148:149] op_sel_hi:[1,0]
	s_nop 0
	v_mul_f32_e32 v22, 0xbfb8aa3b, v19
	v_exp_f32_e32 v22, v22
	s_nop 0
	v_add_f32_e32 v22, 1.0, v22
	v_rcp_f32_e32 v22, v22
	s_nop 0
	v_mul_f32_e32 v19, v19, v22
	v_mul_f32_e32 v27, v18, v19
	v_mov_b32_e32 v18, v24
	v_mov_b32_e32 v19, v20
	v_pk_mul_f32 v[18:19], v[18:19], v[148:149] op_sel_hi:[1,0]
	v_mad_i64_i32 v[22:23], s[58:59], v142, s85, v[144:145]
	v_mul_f32_e32 v20, 0xbfb8aa3b, v19
	v_exp_f32_e32 v20, v20
	s_nop 0
	v_add_f32_e32 v20, 1.0, v20
	v_rcp_f32_e32 v20, v20
	s_nop 0
	v_mul_f32_e32 v19, v19, v20
	v_mov_b32_e32 v20, v25
	v_mul_f32_e32 v24, v18, v19
	v_pk_mul_f32 v[18:19], v[20:21], v[148:149] op_sel_hi:[1,0]
	s_nop 0
	v_mul_f32_e32 v20, 0xbfb8aa3b, v19
	v_exp_f32_e32 v20, v20
	s_nop 0
	v_add_f32_e32 v20, 1.0, v20
	v_rcp_f32_e32 v20, v20
	s_nop 0
	v_mul_f32_e32 v19, v19, v20
	v_mul_f32_e32 v21, v18, v19
	v_cvt_pk_bf16_f32 v18, v30, v31
	v_cvt_pk_bf16_f32 v19, v32, v28
	v_cvt_pk_bf16_f32 v20, v26, v27
	v_cvt_pk_bf16_f32 v21, v24, v21
	global_store_dwordx4 v[22:23], v[18:21], off
	s_nop 1
	v_mov_b32_e32 v18, v14
	v_mov_b32_e32 v19, v10
	v_pk_mul_f32 v[18:19], v[18:19], v[146:147] op_sel_hi:[1,0]
	s_nop 0
	v_mul_f32_e32 v10, 0xbfb8aa3b, v19
	v_exp_f32_e32 v10, v10
	s_nop 0
	v_add_f32_e32 v10, 1.0, v10
	v_rcp_f32_e32 v10, v10
	s_nop 0
	v_mul_f32_e32 v10, v19, v10
	v_mul_f32_e32 v14, v18, v10
	v_mov_b32_e32 v10, v15
	v_pk_mul_f32 v[10:11], v[10:11], v[146:147] op_sel_hi:[1,0]
	s_nop 0
	v_mul_f32_e32 v15, 0xbfb8aa3b, v11
	v_exp_f32_e32 v15, v15
	s_nop 0
	v_add_f32_e32 v15, 1.0, v15
	v_rcp_f32_e32 v15, v15
	s_nop 0
	v_mul_f32_e32 v11, v11, v15
	v_mul_f32_e32 v15, v10, v11
	v_mov_b32_e32 v10, v16
	v_mov_b32_e32 v11, v12
	v_pk_mul_f32 v[10:11], v[10:11], v[146:147] op_sel_hi:[1,0]
	s_nop 0
	v_mul_f32_e32 v12, 0xbfb8aa3b, v11
	v_exp_f32_e32 v12, v12
	s_nop 0
	v_add_f32_e32 v12, 1.0, v12
	v_rcp_f32_e32 v12, v12
	s_nop 0
	v_mul_f32_e32 v11, v11, v12
	v_mov_b32_e32 v12, v17
	v_mul_f32_e32 v16, v10, v11
	v_pk_mul_f32 v[10:11], v[12:13], v[146:147] op_sel_hi:[1,0]
	s_nop 0
	v_mul_f32_e32 v12, 0xbfb8aa3b, v11
	v_exp_f32_e32 v12, v12
	s_nop 0
	v_add_f32_e32 v12, 1.0, v12
	v_rcp_f32_e32 v12, v12
	s_nop 0
	v_mul_f32_e32 v11, v11, v12
	v_mul_f32_e32 v12, v10, v11
	v_mov_b32_e32 v10, v2
	v_mov_b32_e32 v11, v6
	v_pk_mul_f32 v[10:11], v[10:11], v[146:147] op_sel_hi:[1,0]
	v_mov_b32_e32 v6, v3
	v_mul_f32_e32 v2, 0xbfb8aa3b, v11
	v_exp_f32_e32 v2, v2
	s_nop 0
	v_add_f32_e32 v2, 1.0, v2
	v_rcp_f32_e32 v2, v2
	s_nop 0
	v_mul_f32_e32 v2, v11, v2
	v_mul_f32_e32 v10, v10, v2
	v_pk_mul_f32 v[2:3], v[6:7], v[146:147] op_sel_hi:[1,0]
	s_nop 0
	v_mul_f32_e32 v6, 0xbfb8aa3b, v3
	v_exp_f32_e32 v6, v6
	s_nop 0
	v_add_f32_e32 v6, 1.0, v6
	v_rcp_f32_e32 v6, v6
	s_nop 0
	v_mul_f32_e32 v3, v3, v6
	v_mul_f32_e32 v11, v2, v3
	v_mov_b32_e32 v2, v4
	v_mov_b32_e32 v3, v8
	v_pk_mul_f32 v[2:3], v[2:3], v[146:147] op_sel_hi:[1,0]
	v_mov_b32_e32 v8, v5
	v_mul_f32_e32 v4, 0xbfb8aa3b, v3
	v_exp_f32_e32 v4, v4
	v_mad_i64_i32 v[6:7], s[58:59], v140, s85, v[144:145]
	v_add_f32_e32 v4, 1.0, v4
	v_rcp_f32_e32 v4, v4
	s_nop 0
	v_mul_f32_e32 v3, v3, v4
	v_mul_f32_e32 v13, v2, v3
	v_pk_mul_f32 v[2:3], v[8:9], v[146:147] op_sel_hi:[1,0]
	s_nop 0
	v_mul_f32_e32 v4, 0xbfb8aa3b, v3
	v_exp_f32_e32 v4, v4
	s_nop 0
	v_add_f32_e32 v4, 1.0, v4
	v_rcp_f32_e32 v4, v4
	s_nop 0
	v_mul_f32_e32 v3, v3, v4
	v_mul_f32_e32 v5, v2, v3
	v_cvt_pk_bf16_f32 v2, v14, v15
	v_cvt_pk_bf16_f32 v3, v16, v12
	v_cvt_pk_bf16_f32 v4, v10, v11
	v_cvt_pk_bf16_f32 v5, v13, v5
	global_store_dwordx4 v[6:7], v[2:5], off
	s_cbranch_vccnz .LBB0_1182
	s_andn2_b64 vcc, exec, s[18:19]
	s_cbranch_vccnz .LBB0_1181
	s_barrier
	s_branch .LBB0_1181

; __device__ __forceinline__ float bflo(unsigned w) { return __uint_as_float(w << 16); }
; __device__ __forceinline__ float bfhi(unsigned w) { return __uint_as_float(w & 0xffff0000u); }
; __device__ __forceinline__ unsigned pk2(float lo, float hi) { return pg8::cvt_pk_bf16(lo, hi); }
;     __device__ __forceinline__ void operator()(const f32x4 (&acc)[2][2][4][2], const Unit& u, int wr, int wc, int fr, int fq) const {
;     ...
;         const int row0 = u.pm * 256 + wr * 64 + fr, col0 = u.pn * 256 + wc * 32 + 4 * fq;
; #pragma unroll
;         for (int hb = 0; hb < 2; ++hb) {
;             u32x2v rin[4][4];
; #pragma unroll
;             for (int gg = 0; gg < 4; ++gg) { const int g = hb * 4 + gg; const size_t offn = (size_t)(row0 + (g >> 2) * 128 + (g & 3) * 16) * D + col0;
; #pragma unroll
;                 for (int k = 0; k < 4; ++k) rin[gg][k] = *(const u32x2v*)(in + offn + (k >> 1) * 128 + (k & 1) * 16); }
; #pragma unroll
;             for (int gg = 0; gg < 4; ++gg) {
;                 const int g = hb * 4 + gg, ai = g >> 2, m = g & 3, row = row0 + ai * 128 + m * 16;
;                 const size_t off = (size_t)row * D + col0;
;                 float ss = 0.f;
; #pragma unroll
;                 for (int k = 0; k < 4; ++k) { const int bj = k >> 1, n = k & 1; const size_t o = off + bj * 128 + n * 16; const f32x4 a = acc[ai][bj][m][n] * scale; const u32x2v w0 = rin[gg][k];
;                     f32x4 r; r[0] = bflo(w0.x) + a[0]; r[1] = bfhi(w0.x) + a[1]; r[2] = bflo(w0.y) + a[2]; r[3] = bfhi(w0.y) + a[3];
;                     u32x2v w; w.x = pk2(r[0], r[1]); w.y = pk2(r[2], r[3]); *(u32x2v*)(out + o) = w; ss += (r[0] * r[0] + r[1] * r[1]) + (r[2] * r[2] + r[3] * r[3]); }
;                 ss += __shfl_xor(ss, 16); ss += __shfl_xor(ss, 32);
;                 if (fq == 0) part[(ai * 128 + wr * 64 + m * 16 + fr) * 4 + wc] = ss;
.LBB0_1271:
	s_lshl_b32 s13, s13, 8
	v_lshl_or_b32 v136, s12, 8, v170
	v_readlane_b32 s80, v251, 12
	v_add_u32_e32 v138, s13, v168
	v_ashrrev_i32_e32 v137, 31, v136
	s_mov_b64 s[56:57], s[46:47]
	s_mov_b64 s[70:71], s[46:47]
	s_mov_b32 s90, 0.5
	v_readlane_b32 s81, v251, 13
	v_lshlrev_b64 v[140:141], 1, v[136:137]
	v_ashrrev_i32_e32 v139, 31, v138
	v_lshlrev_b64 v[142:143], 11, v[138:139]
	v_lshl_add_u64 v[136:137], s[56:57], 0, v[140:141]
	v_lshl_add_u64 v[144:145], v[136:137], 0, v[142:143]
	global_load_dwordx2 v[174:175], v[144:145], off
	global_load_dwordx2 v[176:177], v[144:145], off offset:32
	global_load_dwordx2 v[178:179], v[144:145], off offset:256
	global_load_dwordx2 v[180:181], v[144:145], off offset:288
	v_or_b32_e32 v144, 16, v138
	v_or_b32_e32 v146, 32, v138
	v_or_b32_e32 v150, 48, v138
	v_ashrrev_i32_e32 v145, 31, v144
	v_ashrrev_i32_e32 v147, 31, v146
	v_ashrrev_i32_e32 v151, 31, v150
	v_lshlrev_b64 v[166:167], 11, v[144:145]
	v_lshlrev_b64 v[148:149], 11, v[146:147]
	v_pk_mul_f32 v[182:183], v[128:129], s[90:91] op_sel_hi:[1,0]
	v_pk_mul_f32 v[188:189], v[122:123], s[90:91] op_sel_hi:[1,0]
	v_pk_mul_f32 v[190:191], v[120:121], s[90:91] op_sel_hi:[1,0]
	v_pk_mul_f32 v[192:193], v[118:119], s[90:91] op_sel_hi:[1,0]
	v_lshl_add_u64 v[118:119], s[70:71], 0, v[140:141]
	v_lshlrev_b64 v[128:129], 11, v[150:151]
	v_lshl_add_u64 v[120:121], v[136:137], 0, v[166:167]
	v_lshl_add_u64 v[122:123], v[136:137], 0, v[148:149]
	v_pk_mul_f32 v[184:185], v[126:127], s[90:91] op_sel_hi:[1,0]
	v_pk_mul_f32 v[186:187], v[124:125], s[90:91] op_sel_hi:[1,0]
	v_lshl_add_u64 v[194:195], v[118:119], 0, v[142:143]
	v_lshl_add_u64 v[196:197], v[136:137], 0, v[128:129]
	global_load_dwordx2 v[156:157], v[120:121], off
	global_load_dwordx2 v[154:155], v[120:121], off offset:32
	global_load_dwordx2 v[152:153], v[120:121], off offset:256
	global_load_dwordx2 v[150:151], v[120:121], off offset:288
	global_load_dwordx2 v[146:147], v[122:123], off
	global_load_dwordx2 v[144:145], v[122:123], off offset:32
	global_load_dwordx2 v[142:143], v[122:123], off offset:256
	global_load_dwordx2 v[140:141], v[122:123], off offset:288
	global_load_dwordx2 v[126:127], v[196:197], off
	global_load_dwordx2 v[124:125], v[196:197], off offset:32
	s_nop 0
	global_load_dwordx2 v[122:123], v[196:197], off offset:256
	global_load_dwordx2 v[120:121], v[196:197], off offset:288
	v_pk_mul_f32 v[114:115], v[114:115], s[90:91] op_sel_hi:[1,0]
	v_pk_mul_f32 v[116:117], v[116:117], s[90:91] op_sel_hi:[1,0]
	s_waitcnt vmcnt(0) lgkmcnt(0)
	v_lshlrev_b32_e32 v173, 16, v174
	v_and_b32_e32 v174, 0xffff0000, v174
	v_lshlrev_b32_e32 v196, 16, v175
	v_and_b32_e32 v175, 0xffff0000, v175
	v_lshlrev_b32_e32 v197, 16, v176
	v_and_b32_e32 v176, 0xffff0000, v176
	v_lshlrev_b32_e32 v198, 16, v177
	v_and_b32_e32 v177, 0xffff0000, v177
	v_lshlrev_b32_e32 v200, 16, v179
	v_add_f32_e32 v173, v184, v173
	v_add_f32_e32 v184, v185, v174
	v_add_f32_e32 v183, v183, v175
	v_add_f32_e32 v176, v189, v176
	v_add_f32_e32 v177, v187, v177
	v_add_f32_e32 v182, v182, v196
	v_add_f32_e32 v185, v188, v197
	v_add_f32_e32 v186, v186, v198
	v_add_f32_e32 v188, v190, v200
	v_cvt_pk_bf16_f32 v174, v173, v184
	v_cvt_pk_bf16_f32 v175, v182, v183
	v_mul_f32_e32 v184, v184, v184
	v_mul_f32_e32 v183, v183, v183
	v_mul_f32_e32 v189, v176, v176
	v_mul_f32_e32 v190, v177, v177
	v_lshlrev_b32_e32 v199, 16, v178
	v_and_b32_e32 v178, 0xffff0000, v178
	v_and_b32_e32 v179, 0xffff0000, v179
	v_fmac_f32_e32 v184, v173, v173
	v_fmac_f32_e32 v183, v182, v182
	v_fmac_f32_e32 v189, v185, v185
	v_fmac_f32_e32 v190, v186, v186
	v_add_f32_e32 v178, v193, v178
	v_add_f32_e32 v179, v191, v179
	global_store_dwordx2 v[194:195], v[174:175], off
	v_add_f32_e32 v173, v184, v183
	v_add_f32_e32 v175, v189, v190
	v_add_f32_e32 v187, v192, v199
	v_mul_f32_e32 v191, v178, v178
	v_add_f32_e32 v173, v173, v175
	v_mul_f32_e32 v175, v179, v179
	v_fmac_f32_e32 v191, v187, v187
	v_fmac_f32_e32 v175, v188, v188
	v_add_f32_e32 v175, v191, v175
	v_add_f32_e32 v173, v173, v175
	v_lshlrev_b32_e32 v175, 16, v180
	v_cvt_pk_bf16_f32 v174, v185, v176
	v_add_f32_e32 v176, v114, v175
	v_and_b32_e32 v114, 0xffff0000, v180
	v_add_f32_e32 v180, v115, v114
	v_lshlrev_b32_e32 v114, 16, v181
	v_add_f32_e32 v182, v116, v114
	v_and_b32_e32 v114, 0xffff0000, v181
	v_add_f32_e32 v181, v117, v114
	v_mul_f32_e32 v114, v180, v180
	v_mul_f32_e32 v115, v181, v181
	v_fmac_f32_e32 v114, v176, v176
	v_fmac_f32_e32 v115, v182, v182
	v_add_f32_e32 v114, v114, v115
	v_and_b32_e32 v116, 64, v209
	v_add_f32_e32 v115, v173, v114
	v_xor_b32_e32 v114, 16, v209
	v_add_u32_e32 v117, 64, v116
	v_cmp_lt_i32_e32 vcc, v114, v117
	v_cvt_pk_bf16_f32 v175, v186, v177
	global_store_dwordx2 v[194:195], v[174:175], off offset:32
	v_cvt_pk_bf16_f32 v174, v187, v178
	v_cvt_pk_bf16_f32 v175, v188, v179
	global_store_dwordx2 v[194:195], v[174:175], off offset:256
	v_cndmask_b32_e32 v114, v209, v114, vcc
	v_lshlrev_b32_e32 v114, 2, v114
	ds_bpermute_b32 v116, v114, v115
	v_cvt_pk_bf16_f32 v174, v176, v180
	v_cvt_pk_bf16_f32 v175, v182, v181
	global_store_dwordx2 v[194:195], v[174:175], off offset:288
	s_waitcnt lgkmcnt(0)
	v_add_f32_e32 v116, v115, v116
	v_xor_b32_e32 v115, 32, v209
	v_cmp_lt_i32_e32 vcc, v115, v117
	s_nop 1
	v_cndmask_b32_e32 v115, v209, v115, vcc
	v_lshlrev_b32_e32 v115, 2, v115
	ds_bpermute_b32 v117, v115, v116
	s_and_saveexec_b64 s[70:71], s[40:41]
	s_cbranch_execz .LBB0_1273
	s_waitcnt lgkmcnt(0)
	v_add_f32_e32 v116, v116, v117
	ds_write_b32 v171, v116

;     __device__ __forceinline__ void operator()(const f32x4 (&acc)[2][2][4][2], const Unit& u, int wr, int wc, int fr, int fq) const {
;     ...
;         const int row0 = u.pm * 256 + wr * 64 + fr, col0 = u.pn * 256 + wc * 32 + 4 * fq;
;         float rsv[8];
;         { f32x4 pp[8];
; #pragma unroll
;           for (int g = 0; g < 8; ++g) pp[g] = *(const f32x4*)(rss + (size_t)(row0 + (g >> 2) * 128 + (g & 3) * 16) * 4);
; #pragma unroll
;           for (int g = 0; g < 8; ++g) rsv[g] = __builtin_amdgcn_rsqf(((pp[g][0] + pp[g][1]) + (pp[g][2] + pp[g][3])) * (1.0f / D) + EPS); }
; #pragma unroll
;         for (int hb = 0; hb < 4; ++hb) {
;             u32x2v rin[2][4], pin[2][4];
; #pragma unroll
;             for (int gg = 0; gg < 2; ++gg) { const int g = hb * 2 + gg; const size_t offn = (size_t)(row0 + (g >> 2) * 128 + (g & 3) * 16) * D + col0;
; #pragma unroll
;                 for (int k = 0; k < 4; ++k) { const size_t o = offn + (k >> 1) * 128 + (k & 1) * 16; rin[gg][k] = *(const u32x2v*)(in + o); pin[gg][k] = *(const u32x2v*)(P + o); } }
.LBB0_1364:
	s_lshl_b32 s19, s19, 8
	v_readlane_b32 s70, v250, 7
	v_readlane_b32 s50, v251, 12
	v_readlane_b32 s90, v251, 8
	v_readlane_b32 s80, v250, 28
	v_add_u32_e32 v178, s19, v237
	v_readlane_b32 s71, v250, 8
	v_readlane_b32 s51, v251, 13
	s_mov_b64 s[78:79], s[46:47]
	v_readlane_b32 s91, v251, 9
	v_readlane_b32 s81, v250, 29
	v_ashrrev_i32_e32 v179, 31, v178
	v_lshl_or_b32 v180, s18, 8, v239
	v_lshl_add_u64 v[34:35], v[178:179], 4, s[50:51]
	global_load_dwordx4 v[190:193], v[34:35], off
	v_ashrrev_i32_e32 v181, 31, v180
	v_or_b32_e32 v194, 16, v178
	v_ashrrev_i32_e32 v195, 31, v194
	v_or_b32_e32 v188, 32, v178
	v_lshl_add_u64 v[34:35], v[194:195], 4, s[50:51]
	v_ashrrev_i32_e32 v189, 31, v188
	v_or_b32_e32 v186, 48, v178
	global_load_dwordx4 v[154:157], v[34:35], off
	v_lshl_add_u64 v[34:35], v[188:189], 4, s[50:51]
	v_ashrrev_i32_e32 v187, 31, v186
	v_add_u32_e32 v184, 0x80, v178
	global_load_dwordx4 v[146:149], v[34:35], off
	v_lshl_add_u64 v[34:35], v[186:187], 4, s[50:51]
	v_ashrrev_i32_e32 v185, 31, v184
	v_add_u32_e32 v182, 0x90, v178
	global_load_dwordx4 v[114:117], v[34:35], off
	v_lshl_add_u64 v[34:35], v[184:185], 4, s[50:51]
	v_ashrrev_i32_e32 v183, 31, v182
	v_add_u32_e32 v176, 0xa0, v178
	global_load_dwordx4 v[106:109], v[34:35], off
	v_lshl_add_u64 v[34:35], v[182:183], 4, s[50:51]
	v_ashrrev_i32_e32 v177, 31, v176
	v_add_u32_e32 v172, 0xb0, v178
	global_load_dwordx4 v[74:77], v[34:35], off
	v_lshl_add_u64 v[34:35], v[176:177], 4, s[50:51]
	v_ashrrev_i32_e32 v173, 31, v172
	global_load_dwordx4 v[66:69], v[34:35], off
	v_lshl_add_u64 v[34:35], v[172:173], 4, s[50:51]
	global_load_dwordx4 v[34:37], v[34:35], off
	s_waitcnt vmcnt(0) lgkmcnt(0)
	v_mov_b32_e32 v174, v191
	v_mov_b32_e32 v175, v192
	v_mov_b32_e32 v191, v193
	v_pk_add_f32 v[174:175], v[174:175], v[190:191]
	v_lshlrev_b64 v[190:191], 10, v[178:179]
	v_lshl_add_u64 v[190:191], v[190:191], 0, v[180:181]
	v_lshlrev_b64 v[190:191], 1, v[190:191]
	v_lshl_add_u64 v[192:193], s[78:79], 0, v[190:191]
	global_load_dwordx2 v[226:227], v[192:193], off
	v_lshl_add_u64 v[190:191], s[90:91], 0, v[190:191]
	global_load_dwordx2 v[224:225], v[190:191], off
	global_load_dwordx2 v[222:223], v[192:193], off offset:32
	global_load_dwordx2 v[220:221], v[190:191], off offset:32
	global_load_dwordx2 v[218:219], v[192:193], off offset:256
	global_load_dwordx2 v[214:215], v[190:191], off offset:256
	global_load_dwordx2 v[212:213], v[192:193], off offset:288
	global_load_dwordx2 v[210:211], v[190:191], off offset:288
	v_add_f32_e32 v174, v174, v175
	v_fmamk_f32 v174, v174, 0x3a800000, v159
	v_rsq_f32_e32 v208, v174
	v_lshlrev_b64 v[190:191], 10, v[194:195]
	v_lshl_add_u64 v[190:191], v[190:191], 0, v[180:181]
	v_lshlrev_b64 v[190:191], 1, v[190:191]
	v_pk_mul_f32 v[150:151], v[150:151], v[208:209] op_sel_hi:[1,0]
	v_pk_mul_f32 v[152:153], v[152:153], v[208:209] op_sel_hi:[1,0]
	v_mul_f32_e32 v150, 0xbfb8aa3b, v150
	v_exp_f32_e32 v150, v150
	v_pk_mul_f32 v[142:143], v[142:143], v[208:209] op_sel_hi:[1,0]
	v_lshl_add_u64 v[192:193], s[78:79], 0, v[190:191]
	v_mul_f32_e32 v142, 0xbfb8aa3b, v142
	v_add_f32_e32 v150, 1.0, v150
	v_rcp_f32_e32 v150, v150
	v_exp_f32_e32 v142, v142
	v_lshl_add_u64 v[216:217], s[90:91], 0, v[190:191]
	v_lshl_add_u64 v[174:175], v[180:181], 1, s[70:71]
	global_load_dwordx2 v[204:205], v[192:193], off
	global_load_dwordx2 v[206:207], v[216:217], off
	global_load_dwordx2 v[200:201], v[192:193], off offset:32
	global_load_dwordx2 v[202:203], v[216:217], off offset:32
	global_load_dwordx2 v[196:197], v[192:193], off offset:256
	global_load_dwordx2 v[198:199], v[216:217], off offset:256
	global_load_dwordx2 v[190:191], v[192:193], off offset:288
	s_nop 0
	global_load_dwordx2 v[192:193], v[216:217], off offset:288
	v_lshlrev_b64 v[216:217], 11, v[178:179]
	v_add_f32_e32 v142, 1.0, v142
	v_lshl_add_u64 v[216:217], v[174:175], 0, v[216:217]
	v_rcp_f32_e32 v142, v142
	v_pk_mul_f32 v[144:145], v[144:145], v[208:209] op_sel_hi:[1,0]
	v_pk_mul_f32 v[138:139], v[138:139], v[208:209] op_sel_hi:[1,0]
	v_pk_mul_f32 v[140:141], v[140:141], v[208:209] op_sel_hi:[1,0]
	v_mul_f32_e32 v138, 0xbfb8aa3b, v138
	v_exp_f32_e32 v138, v138
	v_pk_mul_f32 v[134:135], v[134:135], v[208:209] op_sel_hi:[1,0]
	v_pk_mul_f32 v[136:137], v[136:137], v[208:209] op_sel_hi:[1,0]
	v_mul_f32_e32 v134, 0xbfb8aa3b, v134
	v_add_f32_e32 v138, 1.0, v138
	v_rcp_f32_e32 v138, v138
	v_exp_f32_e32 v134, v134
	s_waitcnt vmcnt(0) lgkmcnt(0)
; __device__ __forceinline__ float bflo(unsigned w) { return __uint_as_float(w << 16); }
; __device__ __forceinline__ float bfhi(unsigned w) { return __uint_as_float(w & 0xffff0000u); }
; __device__ __forceinline__ unsigned pk2(float lo, float hi) { return pg8::cvt_pk_bf16(lo, hi); }
; __device__ __forceinline__ float sigmoidf_(float x) { return __builtin_amdgcn_rcpf(1.0f + __expf(-x)); }
;     __device__ __forceinline__ void operator()(const f32x4 (&acc)[2][2][4][2], const Unit& u, int wr, int wc, int fr, int fq) const {
;     ...
;             for (int gg = 0; gg < 2; ++gg) {
;                 const int g = hb * 2 + gg, ai = g >> 2, m = g & 3, row = row0 + ai * 128 + m * 16;
;                 const size_t off = (size_t)row * D + col0;
;                 const float rs = rsv[g];
;                 float ss = 0.f;
; #pragma unroll
;                 for (int k = 0; k < 4; ++k) { const int bj = k >> 1, n = k & 1; const size_t o = off + bj * 128 + n * 16;
;                     const u32x2v rw = rin[gg][k], pw = pin[gg][k]; const f32x4 a = acc[ai][bj][m][n] * rs;
;                     f32x4 res; res[0] = bflo(rw.x) + sigmoidf_(a[0]) * bflo(pw.x); res[1] = bfhi(rw.x) + sigmoidf_(a[1]) * bfhi(pw.x); res[2] = bflo(rw.y) + sigmoidf_(a[2]) * bflo(pw.y); res[3] = bfhi(rw.y) + sigmoidf_(a[3]) * bfhi(pw.y);
;                     u32x2v w; w.x = pk2(res[0], res[1]); w.y = pk2(res[2], res[3]); *(u32x2v*)(out + o) = w; ss += (res[0] * res[0] + res[1] * res[1]) + (res[2] * res[2] + res[3] * res[3]); }
;                 ss += __shfl_xor(ss, 16); ss += __shfl_xor(ss, 32); if (fq == 0) part[(ai * 128 + wr * 64 + m * 16 + fr) * 4 + wc] = ss;
	v_lshlrev_b32_e32 v243, 16, v224
	v_add_f32_e32 v134, 1.0, v134
	v_rcp_f32_e32 v134, v134
	v_lshlrev_b32_e32 v242, 16, v226
	v_fmac_f32_e32 v242, v150, v243
	v_mul_f32_e32 v150, 0xbfb8aa3b, v151
	v_exp_f32_e32 v150, v150
	v_and_b32_e32 v226, 0xffff0000, v226
	v_and_b32_e32 v151, 0xffff0000, v224
	v_lshlrev_b32_e32 v224, 16, v227
	v_add_f32_e32 v150, 1.0, v150
	v_rcp_f32_e32 v150, v150
	s_nop 0
	v_fmac_f32_e32 v226, v150, v151
	v_mul_f32_e32 v150, 0xbfb8aa3b, v152
	v_exp_f32_e32 v150, v150
	v_lshlrev_b32_e32 v151, 16, v225
	v_and_b32_e32 v152, 0xffff0000, v227
	v_add_f32_e32 v150, 1.0, v150
	v_rcp_f32_e32 v150, v150
	s_nop 0
	v_fmac_f32_e32 v224, v150, v151
	v_mul_f32_e32 v150, 0xbfb8aa3b, v153
	v_exp_f32_e32 v150, v150
	v_and_b32_e32 v151, 0xffff0000, v225
	v_lshlrev_b32_e32 v153, 16, v223
	v_add_f32_e32 v150, 1.0, v150
	v_rcp_f32_e32 v150, v150
	s_nop 0
	v_fmac_f32_e32 v152, v150, v151
	v_cvt_pk_bf16_f32 v150, v242, v226
	v_cvt_pk_bf16_f32 v151, v224, v152
	global_store_dwordx2 v[216:217], v[150:151], off
	v_mul_f32_e32 v150, v226, v226
	v_mul_f32_e32 v151, v152, v152
	v_fmac_f32_e32 v150, v242, v242
	v_fmac_f32_e32 v151, v224, v224
	v_add_f32_e32 v150, v150, v151
	v_lshlrev_b32_e32 v151, 16, v222
	v_lshlrev_b32_e32 v152, 16, v220
	v_fmac_f32_e32 v151, v142, v152
	v_mul_f32_e32 v142, 0xbfb8aa3b, v143
	v_exp_f32_e32 v142, v142
	v_and_b32_e32 v152, 0xffff0000, v222
	v_and_b32_e32 v143, 0xffff0000, v220
	v_add_f32_e32 v142, 1.0, v142
	v_rcp_f32_e32 v142, v142
	s_nop 0
	v_fmac_f32_e32 v152, v142, v143
	v_mul_f32_e32 v142, 0xbfb8aa3b, v144
	v_exp_f32_e32 v142, v142
	v_lshlrev_b32_e32 v143, 16, v221
	v_and_b32_e32 v144, 0xffff0000, v223
	v_add_f32_e32 v142, 1.0, v142
	v_rcp_f32_e32 v142, v142
	s_nop 0
	v_fmac_f32_e32 v153, v142, v143
	v_mul_f32_e32 v142, 0xbfb8aa3b, v145
	v_exp_f32_e32 v142, v142
	v_and_b32_e32 v143, 0xffff0000, v221
	v_lshlrev_b32_e32 v145, 16, v219
	v_add_f32_e32 v142, 1.0, v142
	v_rcp_f32_e32 v142, v142
	s_nop 0
	v_fmac_f32_e32 v144, v142, v143
	v_cvt_pk_bf16_f32 v142, v151, v152
	v_cvt_pk_bf16_f32 v143, v153, v144
	global_store_dwordx2 v[216:217], v[142:143], off offset:32
	v_mul_f32_e32 v142, v152, v152
	v_mul_f32_e32 v143, v144, v144
	v_fmac_f32_e32 v142, v151, v151
	v_fmac_f32_e32 v143, v153, v153
	v_add_f32_e32 v142, v142, v143
	v_lshlrev_b32_e32 v143, 16, v218
	v_lshlrev_b32_e32 v144, 16, v214
	v_fmac_f32_e32 v143, v138, v144
	v_mul_f32_e32 v138, 0xbfb8aa3b, v139
	v_exp_f32_e32 v138, v138
	v_and_b32_e32 v144, 0xffff0000, v218
	v_and_b32_e32 v139, 0xffff0000, v214
	v_add_f32_e32 v142, v150, v142
	v_add_f32_e32 v138, 1.0, v138
	v_rcp_f32_e32 v138, v138
	s_nop 0
	v_fmac_f32_e32 v144, v138, v139
	v_mul_f32_e32 v138, 0xbfb8aa3b, v140
	v_exp_f32_e32 v138, v138
	v_lshlrev_b32_e32 v139, 16, v215
	v_and_b32_e32 v140, 0xffff0000, v219
	v_add_f32_e32 v138, 1.0, v138
	v_rcp_f32_e32 v138, v138
	s_nop 0
	v_fmac_f32_e32 v145, v138, v139
	v_mul_f32_e32 v138, 0xbfb8aa3b, v141
	v_exp_f32_e32 v138, v138
	v_and_b32_e32 v139, 0xffff0000, v215
	v_lshlrev_b32_e32 v141, 16, v213
	v_add_f32_e32 v138, 1.0, v138
	v_rcp_f32_e32 v138, v138
	s_nop 0
	v_fmac_f32_e32 v140, v138, v139
	v_cvt_pk_bf16_f32 v138, v143, v144
	v_cvt_pk_bf16_f32 v139, v145, v140
	global_store_dwordx2 v[216:217], v[138:139], off offset:256
	v_mul_f32_e32 v138, v144, v144
	v_mul_f32_e32 v139, v140, v140
	v_fmac_f32_e32 v138, v143, v143
	v_fmac_f32_e32 v139, v145, v145
	v_add_f32_e32 v138, v138, v139
	v_lshlrev_b32_e32 v139, 16, v212
	v_lshlrev_b32_e32 v140, 16, v210
	v_fmac_f32_e32 v139, v134, v140
	v_mul_f32_e32 v134, 0xbfb8aa3b, v135
	v_exp_f32_e32 v134, v134
	v_and_b32_e32 v140, 0xffff0000, v212
	v_and_b32_e32 v135, 0xffff0000, v210
	v_add_f32_e32 v138, v142, v138
	v_add_f32_e32 v134, 1.0, v134
	v_rcp_f32_e32 v134, v134
	s_nop 0
	v_fmac_f32_e32 v140, v134, v135
	v_mul_f32_e32 v134, 0xbfb8aa3b, v136
	v_exp_f32_e32 v134, v134
	v_lshlrev_b32_e32 v135, 16, v211
	v_and_b32_e32 v136, 0xffff0000, v213
	v_add_f32_e32 v134, 1.0, v134
	v_rcp_f32_e32 v134, v134
	s_nop 0
	v_fmac_f32_e32 v141, v134, v135
	v_mul_f32_e32 v134, 0xbfb8aa3b, v137
	v_exp_f32_e32 v134, v134
	v_and_b32_e32 v135, 0xffff0000, v211
	v_add_f32_e32 v134, 1.0, v134
	v_rcp_f32_e32 v134, v134
	s_nop 0
	v_fmac_f32_e32 v136, v134, v135
	v_cvt_pk_bf16_f32 v134, v139, v140
	v_cvt_pk_bf16_f32 v135, v141, v136
	global_store_dwordx2 v[216:217], v[134:135], off offset:288
	v_mul_f32_e32 v134, v140, v140
	v_mul_f32_e32 v135, v136, v136
	v_fmac_f32_e32 v134, v139, v139
	v_fmac_f32_e32 v135, v141, v141
	v_and_b32_e32 v136, 64, v209
	v_add_f32_e32 v134, v134, v135
	v_xor_b32_e32 v135, 16, v209
	v_add_u32_e32 v136, 64, v136
	v_cmp_lt_i32_e32 vcc, v135, v136
	v_add_f32_e32 v134, v138, v134
	s_nop 0
	v_cndmask_b32_e32 v135, v209, v135, vcc
	v_lshlrev_b32_e32 v141, 2, v135
	ds_bpermute_b32 v135, v141, v134
	s_waitcnt lgkmcnt(0)
	v_add_f32_e32 v134, v134, v135
	v_xor_b32_e32 v135, 32, v209
	v_cmp_lt_i32_e32 vcc, v135, v136
	s_nop 1
	v_cndmask_b32_e32 v135, v209, v135, vcc
	v_lshlrev_b32_e32 v150, 2, v135
	ds_bpermute_b32 v135, v150, v134
	s_and_saveexec_b64 s[70:71], s[40:41]
	s_cbranch_execz .LBB0_1366
	s_waitcnt lgkmcnt(0)
	v_add_f32_e32 v134, v134, v135
	ds_write_b32 v240, v134
; __device__ __forceinline__ float bflo(unsigned w) { return __uint_as_float(w << 16); }
; __device__ __forceinline__ float bfhi(unsigned w) { return __uint_as_float(w & 0xffff0000u); }
; __device__ __forceinline__ unsigned pk2(float lo, float hi) { return pg8::cvt_pk_bf16(lo, hi); }
; __device__ __forceinline__ float sigmoidf_(float x) { return __builtin_amdgcn_rcpf(1.0f + __expf(-x)); }
;     __device__ __forceinline__ void operator()(const f32x4 (&acc)[2][2][4][2], const Unit& u, int wr, int wc, int fr, int fq) const {
;     ...
;             for (int gg = 0; gg < 2; ++gg) {
;                 const int g = hb * 2 + gg, ai = g >> 2, m = g & 3, row = row0 + ai * 128 + m * 16;
;                 const size_t off = (size_t)row * D + col0;
;                 const float rs = rsv[g];
;                 float ss = 0.f;
; #pragma unroll
;                 for (int k = 0; k < 4; ++k) { const int bj = k >> 1, n = k & 1; const size_t o = off + bj * 128 + n * 16;
;                     const u32x2v rw = rin[gg][k], pw = pin[gg][k]; const f32x4 a = acc[ai][bj][m][n] * rs;
;                     f32x4 res; res[0] = bflo(rw.x) + sigmoidf_(a[0]) * bflo(pw.x); res[1] = bfhi(rw.x) + sigmoidf_(a[1]) * bfhi(pw.x); res[2] = bflo(rw.y) + sigmoidf_(a[2]) * bflo(pw.y); res[3] = bfhi(rw.y) + sigmoidf_(a[3]) * bfhi(pw.y);
;                     u32x2v w; w.x = pk2(res[0], res[1]); w.y = pk2(res[2], res[3]); *(u32x2v*)(out + o) = w; ss += (res[0] * res[0] + res[1] * res[1]) + (res[2] * res[2] + res[3] * res[3]); }
;                 ss += __shfl_xor(ss, 16); ss += __shfl_xor(ss, 32); if (fq == 0) part[(ai * 128 + wr * 64 + m * 16 + fr) * 4 + wc] = ss;
.LBB0_1366:
	s_or_b64 exec, exec, s[70:71]
	v_add_f32_e32 v134, v154, v155
	s_waitcnt lgkmcnt(0)
	v_add_f32_e32 v135, v156, v157
	v_add_f32_e32 v134, v134, v135
	v_fmamk_f32 v134, v134, 0x3a800000, v159
	v_rsq_f32_e32 v136, v134
	v_lshlrev_b32_e32 v138, 16, v206
	v_lshlrev_b64 v[134:135], 11, v[194:195]
	v_lshl_add_u64 v[134:135], v[174:175], 0, v[134:135]
	v_pk_mul_f32 v[130:131], v[130:131], v[136:137] op_sel_hi:[1,0]
	v_pk_mul_f32 v[132:133], v[132:133], v[136:137] op_sel_hi:[1,0]
	v_mul_f32_e32 v130, 0xbfb8aa3b, v130
	v_exp_f32_e32 v130, v130
	v_mul_f32_e32 v131, 0xbfb8aa3b, v131
	v_exp_f32_e32 v131, v131
	v_lshlrev_b32_e32 v137, 16, v204
	v_add_f32_e32 v130, 1.0, v130
	v_rcp_f32_e32 v130, v130
	v_add_f32_e32 v131, 1.0, v131
	v_rcp_f32_e32 v131, v131
	v_fmac_f32_e32 v137, v130, v138
	v_and_b32_e32 v138, 0xffff0000, v204
	v_and_b32_e32 v130, 0xffff0000, v206
	v_fmac_f32_e32 v138, v131, v130
	v_mul_f32_e32 v130, 0xbfb8aa3b, v132
	v_exp_f32_e32 v130, v130
	v_mul_f32_e32 v131, 0xbfb8aa3b, v133
	v_exp_f32_e32 v131, v131
	v_pk_mul_f32 v[126:127], v[126:127], v[136:137] op_sel_hi:[1,0]
	v_add_f32_e32 v130, 1.0, v130
	v_mul_f32_e32 v126, 0xbfb8aa3b, v126
	v_rcp_f32_e32 v130, v130
	v_add_f32_e32 v131, 1.0, v131
	v_exp_f32_e32 v126, v126
	v_mul_f32_e32 v127, 0xbfb8aa3b, v127
	v_rcp_f32_e32 v131, v131
	v_exp_f32_e32 v127, v127
	v_lshlrev_b32_e32 v132, 16, v205
	v_lshlrev_b32_e32 v133, 16, v207
	v_fmac_f32_e32 v132, v130, v133
	v_and_b32_e32 v133, 0xffff0000, v205
	v_and_b32_e32 v130, 0xffff0000, v207
	v_add_f32_e32 v126, 1.0, v126
	v_fmac_f32_e32 v133, v131, v130
	v_cvt_pk_bf16_f32 v130, v137, v138
	v_cvt_pk_bf16_f32 v131, v132, v133
	v_rcp_f32_e32 v126, v126
	v_add_f32_e32 v127, 1.0, v127
	global_store_dwordx2 v[134:135], v[130:131], off
	v_mul_f32_e32 v130, v138, v138
	v_mul_f32_e32 v131, v133, v133
	v_rcp_f32_e32 v127, v127
	v_fmac_f32_e32 v130, v137, v137
	v_fmac_f32_e32 v131, v132, v132
	v_add_f32_e32 v130, v130, v131
	v_lshlrev_b32_e32 v131, 16, v200
	v_lshlrev_b32_e32 v132, 16, v202
	v_pk_mul_f32 v[128:129], v[128:129], v[136:137] op_sel_hi:[1,0]
	v_fmac_f32_e32 v131, v126, v132
	v_and_b32_e32 v132, 0xffff0000, v200
	v_and_b32_e32 v126, 0xffff0000, v202
	v_fmac_f32_e32 v132, v127, v126
	v_mul_f32_e32 v126, 0xbfb8aa3b, v128
	v_exp_f32_e32 v126, v126
	v_mul_f32_e32 v128, 0xbfb8aa3b, v129
	v_exp_f32_e32 v128, v128
	v_pk_mul_f32 v[122:123], v[122:123], v[136:137] op_sel_hi:[1,0]
	v_add_f32_e32 v126, 1.0, v126
	v_rcp_f32_e32 v126, v126
	v_add_f32_e32 v128, 1.0, v128
	v_mul_f32_e32 v122, 0xbfb8aa3b, v122
	v_rcp_f32_e32 v128, v128
	v_exp_f32_e32 v122, v122
	v_mul_f32_e32 v123, 0xbfb8aa3b, v123
	v_exp_f32_e32 v123, v123
	v_lshlrev_b32_e32 v127, 16, v201
	v_lshlrev_b32_e32 v129, 16, v203
	v_fmac_f32_e32 v127, v126, v129
	v_and_b32_e32 v129, 0xffff0000, v201
	v_and_b32_e32 v126, 0xffff0000, v203
	v_fmac_f32_e32 v129, v128, v126
	v_mul_f32_e32 v128, v132, v132
	v_add_f32_e32 v122, 1.0, v122
	v_cvt_pk_bf16_f32 v126, v131, v132
	v_fmac_f32_e32 v128, v131, v131
	v_mul_f32_e32 v131, v129, v129
	v_rcp_f32_e32 v122, v122
	v_add_f32_e32 v123, 1.0, v123
	v_fmac_f32_e32 v131, v127, v127
	v_rcp_f32_e32 v123, v123
	v_add_f32_e32 v128, v128, v131
	v_add_f32_e32 v128, v130, v128
	v_lshlrev_b32_e32 v130, 16, v196
	v_lshlrev_b32_e32 v131, 16, v198
	v_pk_mul_f32 v[124:125], v[124:125], v[136:137] op_sel_hi:[1,0]
	v_fmac_f32_e32 v130, v122, v131
	v_and_b32_e32 v122, 0xffff0000, v196
	v_and_b32_e32 v131, 0xffff0000, v198
	v_fmac_f32_e32 v122, v123, v131
	v_mul_f32_e32 v123, 0xbfb8aa3b, v124
	v_exp_f32_e32 v123, v123
	v_mul_f32_e32 v125, 0xbfb8aa3b, v125
	v_exp_f32_e32 v125, v125
	v_pk_mul_f32 v[118:119], v[118:119], v[136:137] op_sel_hi:[1,0]
	v_add_f32_e32 v123, 1.0, v123
	v_rcp_f32_e32 v123, v123
	v_add_f32_e32 v125, 1.0, v125
	v_mul_f32_e32 v118, 0xbfb8aa3b, v118
	v_rcp_f32_e32 v125, v125
	v_exp_f32_e32 v118, v118
	v_mul_f32_e32 v119, 0xbfb8aa3b, v119
	v_exp_f32_e32 v119, v119
	v_lshlrev_b32_e32 v124, 16, v197
	v_lshlrev_b32_e32 v131, 16, v199
	v_fmac_f32_e32 v124, v123, v131
	v_and_b32_e32 v123, 0xffff0000, v197
	v_and_b32_e32 v131, 0xffff0000, v199
	v_fmac_f32_e32 v123, v125, v131
	v_add_f32_e32 v118, 1.0, v118
	v_mul_f32_e32 v125, v122, v122
	v_mul_f32_e32 v131, v123, v123
	v_rcp_f32_e32 v118, v118
	v_add_f32_e32 v119, 1.0, v119
	v_fmac_f32_e32 v125, v130, v130
	v_fmac_f32_e32 v131, v124, v124
	v_rcp_f32_e32 v119, v119
	v_add_f32_e32 v125, v125, v131
	v_add_f32_e32 v125, v128, v125
	v_lshlrev_b32_e32 v128, 16, v190
	v_lshlrev_b32_e32 v131, 16, v192
	v_pk_mul_f32 v[120:121], v[120:121], v[136:137] op_sel_hi:[1,0]
	v_fmac_f32_e32 v128, v118, v131
	v_and_b32_e32 v131, 0xffff0000, v190
	v_and_b32_e32 v118, 0xffff0000, v192
	v_fmac_f32_e32 v131, v119, v118
	v_mul_f32_e32 v118, 0xbfb8aa3b, v120
	v_exp_f32_e32 v118, v118
	v_mul_f32_e32 v119, 0xbfb8aa3b, v121
	v_exp_f32_e32 v119, v119
	v_lshlrev_b32_e32 v132, 16, v191
	v_add_f32_e32 v118, 1.0, v118
	v_rcp_f32_e32 v118, v118
	v_add_f32_e32 v119, 1.0, v119
	v_rcp_f32_e32 v119, v119
	v_lshlrev_b32_e32 v120, 16, v193
	v_fmac_f32_e32 v132, v118, v120
	v_and_b32_e32 v133, 0xffff0000, v191
	v_and_b32_e32 v118, 0xffff0000, v193
	v_fmac_f32_e32 v133, v119, v118
	v_mul_f32_e32 v118, v131, v131
	v_mul_f32_e32 v119, v133, v133
	v_fmac_f32_e32 v118, v128, v128
	v_fmac_f32_e32 v119, v132, v132
	v_add_f32_e32 v118, v118, v119
	v_add_f32_e32 v118, v125, v118
	ds_bpermute_b32 v119, v141, v118
	v_cvt_pk_bf16_f32 v127, v127, v129
	global_store_dwordx2 v[134:135], v[126:127], off offset:32
	v_cvt_pk_bf16_f32 v120, v130, v122
	v_cvt_pk_bf16_f32 v121, v124, v123
	s_waitcnt lgkmcnt(0)
	v_add_f32_e32 v118, v118, v119
	ds_bpermute_b32 v119, v150, v118
	global_store_dwordx2 v[134:135], v[120:121], off offset:256
	v_cvt_pk_bf16_f32 v120, v128, v131
	v_cvt_pk_bf16_f32 v121, v132, v133
	global_store_dwordx2 v[134:135], v[120:121], off offset:288
	s_and_saveexec_b64 s[70:71], s[40:41]
	s_cbranch_execz .LBB0_1368
	s_waitcnt lgkmcnt(0)
	v_add_f32_e32 v118, v118, v119
	ds_write_b32 v240, v118 offset:256
; __device__ __forceinline__ float bflo(unsigned w) { return __uint_as_float(w << 16); }
; __device__ __forceinline__ float bfhi(unsigned w) { return __uint_as_float(w & 0xffff0000u); }
; __device__ __forceinline__ unsigned pk2(float lo, float hi) { return pg8::cvt_pk_bf16(lo, hi); }
; __device__ __forceinline__ float sigmoidf_(float x) { return __builtin_amdgcn_rcpf(1.0f + __expf(-x)); }
;     __device__ __forceinline__ void operator()(const f32x4 (&acc)[2][2][4][2], const Unit& u, int wr, int wc, int fr, int fq) const {
;     ...
;         for (int hb = 0; hb < 4; ++hb) {
;             u32x2v rin[2][4], pin[2][4];
; #pragma unroll
;             for (int gg = 0; gg < 2; ++gg) { const int g = hb * 2 + gg; const size_t offn = (size_t)(row0 + (g >> 2) * 128 + (g & 3) * 16) * D + col0;
; #pragma unroll
;                 for (int k = 0; k < 4; ++k) { const size_t o = offn + (k >> 1) * 128 + (k & 1) * 16; rin[gg][k] = *(const u32x2v*)(in + o); pin[gg][k] = *(const u32x2v*)(P + o); } }
; #pragma unroll
;             for (int gg = 0; gg < 2; ++gg) {
;                 const int g = hb * 2 + gg, ai = g >> 2, m = g & 3, row = row0 + ai * 128 + m * 16;
;                 const size_t off = (size_t)row * D + col0;
;                 const float rs = rsv[g];
;                 float ss = 0.f;
; #pragma unroll
;                 for (int k = 0; k < 4; ++k) { const int bj = k >> 1, n = k & 1; const size_t o = off + bj * 128 + n * 16;
;                     const u32x2v rw = rin[gg][k], pw = pin[gg][k]; const f32x4 a = acc[ai][bj][m][n] * rs;
;                     f32x4 res; res[0] = bflo(rw.x) + sigmoidf_(a[0]) * bflo(pw.x); res[1] = bfhi(rw.x) + sigmoidf_(a[1]) * bfhi(pw.x); res[2] = bflo(rw.y) + sigmoidf_(a[2]) * bflo(pw.y); res[3] = bfhi(rw.y) + sigmoidf_(a[3]) * bfhi(pw.y);
;                     u32x2v w; w.x = pk2(res[0], res[1]); w.y = pk2(res[2], res[3]); *(u32x2v*)(out + o) = w; ss += (res[0] * res[0] + res[1] * res[1]) + (res[2] * res[2] + res[3] * res[3]); }
;                 ss += __shfl_xor(ss, 16); ss += __shfl_xor(ss, 32); if (fq == 0) part[(ai * 128 + wr * 64 + m * 16 + fr) * 4 + wc] = ss;
.LBB0_1368:
	s_or_b64 exec, exec, s[70:71]
	v_add_f32_e32 v118, v146, v147
	s_waitcnt lgkmcnt(0)
	v_add_f32_e32 v119, v148, v149
	v_add_f32_e32 v118, v118, v119
	v_fmamk_f32 v118, v118, 0x3a800000, v159
	v_rsq_f32_e32 v140, v118
	v_lshlrev_b64 v[118:119], 10, v[188:189]
	v_lshl_add_u64 v[118:119], v[118:119], 0, v[180:181]
	v_lshlrev_b64 v[118:119], 1, v[118:119]
	v_lshl_add_u64 v[120:121], s[78:79], 0, v[118:119]
	global_load_dwordx2 v[152:153], v[120:121], off
	v_lshl_add_u64 v[118:119], s[90:91], 0, v[118:119]
	global_load_dwordx2 v[154:155], v[118:119], off
	global_load_dwordx2 v[148:149], v[120:121], off offset:32
	global_load_dwordx2 v[146:147], v[118:119], off offset:32
	global_load_dwordx2 v[144:145], v[120:121], off offset:256
	global_load_dwordx2 v[142:143], v[118:119], off offset:256
	global_load_dwordx2 v[136:137], v[120:121], off offset:288
	global_load_dwordx2 v[134:135], v[118:119], off offset:288
	v_pk_mul_f32 v[110:111], v[110:111], v[140:141] op_sel_hi:[1,0]
	v_pk_mul_f32 v[112:113], v[112:113], v[140:141] op_sel_hi:[1,0]
	v_mul_f32_e32 v110, 0xbfb8aa3b, v110
	v_exp_f32_e32 v110, v110
	v_pk_mul_f32 v[102:103], v[102:103], v[140:141] op_sel_hi:[1,0]
	v_lshlrev_b64 v[118:119], 10, v[186:187]
	v_mul_f32_e32 v102, 0xbfb8aa3b, v102
	v_add_f32_e32 v110, 1.0, v110
	v_rcp_f32_e32 v110, v110
	v_exp_f32_e32 v102, v102
	v_lshl_add_u64 v[118:119], v[118:119], 0, v[180:181]
	v_lshlrev_b64 v[118:119], 1, v[118:119]
	v_lshl_add_u64 v[120:121], s[78:79], 0, v[118:119]
	v_lshl_add_u64 v[138:139], s[90:91], 0, v[118:119]
	global_load_dwordx2 v[130:131], v[120:121], off
	global_load_dwordx2 v[132:133], v[138:139], off
	global_load_dwordx2 v[126:127], v[120:121], off offset:32
	global_load_dwordx2 v[128:129], v[138:139], off offset:32
	global_load_dwordx2 v[122:123], v[120:121], off offset:256
	global_load_dwordx2 v[124:125], v[138:139], off offset:256
	global_load_dwordx2 v[118:119], v[120:121], off offset:288
	s_nop 0
	global_load_dwordx2 v[120:121], v[138:139], off offset:288
	v_lshlrev_b64 v[138:139], 11, v[188:189]
	v_add_f32_e32 v102, 1.0, v102
	v_lshl_add_u64 v[138:139], v[174:175], 0, v[138:139]
	v_rcp_f32_e32 v102, v102
	v_pk_mul_f32 v[104:105], v[104:105], v[140:141] op_sel_hi:[1,0]
	v_pk_mul_f32 v[98:99], v[98:99], v[140:141] op_sel_hi:[1,0]
	v_pk_mul_f32 v[100:101], v[100:101], v[140:141] op_sel_hi:[1,0]
	v_mul_f32_e32 v98, 0xbfb8aa3b, v98
	v_exp_f32_e32 v98, v98
	v_pk_mul_f32 v[94:95], v[94:95], v[140:141] op_sel_hi:[1,0]
	v_pk_mul_f32 v[96:97], v[96:97], v[140:141] op_sel_hi:[1,0]
	v_mul_f32_e32 v94, 0xbfb8aa3b, v94
	v_add_f32_e32 v98, 1.0, v98
	v_rcp_f32_e32 v98, v98
	v_exp_f32_e32 v94, v94
	s_waitcnt vmcnt(0) lgkmcnt(0)
	v_lshlrev_b32_e32 v156, 16, v154
	v_add_f32_e32 v94, 1.0, v94
	v_rcp_f32_e32 v94, v94
	v_lshlrev_b32_e32 v151, 16, v152
	v_fmac_f32_e32 v151, v110, v156
	v_mul_f32_e32 v110, 0xbfb8aa3b, v111
	v_exp_f32_e32 v110, v110
	v_and_b32_e32 v152, 0xffff0000, v152
	v_and_b32_e32 v111, 0xffff0000, v154
	v_lshlrev_b32_e32 v154, 16, v153
	v_add_f32_e32 v110, 1.0, v110
	v_rcp_f32_e32 v110, v110
	s_nop 0
	v_fmac_f32_e32 v152, v110, v111
	v_mul_f32_e32 v110, 0xbfb8aa3b, v112
	v_exp_f32_e32 v110, v110
	v_lshlrev_b32_e32 v111, 16, v155
	v_and_b32_e32 v112, 0xffff0000, v153
	v_add_f32_e32 v110, 1.0, v110
	v_rcp_f32_e32 v110, v110
	s_nop 0
	v_fmac_f32_e32 v154, v110, v111
	v_mul_f32_e32 v110, 0xbfb8aa3b, v113
	v_exp_f32_e32 v110, v110
	v_and_b32_e32 v111, 0xffff0000, v155
	v_lshlrev_b32_e32 v113, 16, v149
	v_add_f32_e32 v110, 1.0, v110
	v_rcp_f32_e32 v110, v110
	s_nop 0
	v_fmac_f32_e32 v112, v110, v111
	v_cvt_pk_bf16_f32 v110, v151, v152
	v_cvt_pk_bf16_f32 v111, v154, v112
	global_store_dwordx2 v[138:139], v[110:111], off
	v_mul_f32_e32 v110, v152, v152
	v_mul_f32_e32 v111, v112, v112
	v_fmac_f32_e32 v110, v151, v151
	v_fmac_f32_e32 v111, v154, v154
	v_add_f32_e32 v110, v110, v111
	v_lshlrev_b32_e32 v111, 16, v148
	v_lshlrev_b32_e32 v112, 16, v146
	v_fmac_f32_e32 v111, v102, v112
	v_mul_f32_e32 v102, 0xbfb8aa3b, v103
	v_exp_f32_e32 v102, v102
	v_and_b32_e32 v112, 0xffff0000, v148
	v_and_b32_e32 v103, 0xffff0000, v146
	v_add_f32_e32 v102, 1.0, v102
	v_rcp_f32_e32 v102, v102
	s_nop 0
	v_fmac_f32_e32 v112, v102, v103
	v_mul_f32_e32 v102, 0xbfb8aa3b, v104
	v_exp_f32_e32 v102, v102
	v_lshlrev_b32_e32 v103, 16, v147
	v_and_b32_e32 v104, 0xffff0000, v149
	v_add_f32_e32 v102, 1.0, v102
	v_rcp_f32_e32 v102, v102
	s_nop 0
	v_fmac_f32_e32 v113, v102, v103
	v_mul_f32_e32 v102, 0xbfb8aa3b, v105
	v_exp_f32_e32 v102, v102
	v_and_b32_e32 v103, 0xffff0000, v147
	v_lshlrev_b32_e32 v105, 16, v145
	v_add_f32_e32 v102, 1.0, v102
	v_rcp_f32_e32 v102, v102
	s_nop 0
	v_fmac_f32_e32 v104, v102, v103
	v_cvt_pk_bf16_f32 v102, v111, v112
	v_cvt_pk_bf16_f32 v103, v113, v104
	global_store_dwordx2 v[138:139], v[102:103], off offset:32
	v_mul_f32_e32 v102, v112, v112
	v_mul_f32_e32 v103, v104, v104
	v_fmac_f32_e32 v102, v111, v111
	v_fmac_f32_e32 v103, v113, v113
	v_add_f32_e32 v102, v102, v103
	v_lshlrev_b32_e32 v103, 16, v144
	v_lshlrev_b32_e32 v104, 16, v142
	v_fmac_f32_e32 v103, v98, v104
	v_mul_f32_e32 v98, 0xbfb8aa3b, v99
	v_exp_f32_e32 v98, v98
	v_and_b32_e32 v104, 0xffff0000, v144
	v_and_b32_e32 v99, 0xffff0000, v142
	v_add_f32_e32 v102, v110, v102
	v_add_f32_e32 v98, 1.0, v98
	v_rcp_f32_e32 v98, v98
	s_nop 0
	v_fmac_f32_e32 v104, v98, v99
	v_mul_f32_e32 v98, 0xbfb8aa3b, v100
	v_exp_f32_e32 v98, v98
	v_lshlrev_b32_e32 v99, 16, v143
	v_and_b32_e32 v100, 0xffff0000, v145
	v_add_f32_e32 v98, 1.0, v98
	v_rcp_f32_e32 v98, v98
	s_nop 0
	v_fmac_f32_e32 v105, v98, v99
	v_mul_f32_e32 v98, 0xbfb8aa3b, v101
	v_exp_f32_e32 v98, v98
	v_and_b32_e32 v99, 0xffff0000, v143
; __device__ __forceinline__ float bflo(unsigned w) { return __uint_as_float(w << 16); }
; __device__ __forceinline__ float bfhi(unsigned w) { return __uint_as_float(w & 0xffff0000u); }
; __device__ __forceinline__ unsigned pk2(float lo, float hi) { return pg8::cvt_pk_bf16(lo, hi); }
; __device__ __forceinline__ float sigmoidf_(float x) { return __builtin_amdgcn_rcpf(1.0f + __expf(-x)); }
;     __device__ __forceinline__ void operator()(const f32x4 (&acc)[2][2][4][2], const Unit& u, int wr, int wc, int fr, int fq) const {
;     ...
;             for (int gg = 0; gg < 2; ++gg) {
;                 const int g = hb * 2 + gg, ai = g >> 2, m = g & 3, row = row0 + ai * 128 + m * 16;
;                 const size_t off = (size_t)row * D + col0;
;                 const float rs = rsv[g];
;                 float ss = 0.f;
; #pragma unroll
;                 for (int k = 0; k < 4; ++k) { const int bj = k >> 1, n = k & 1; const size_t o = off + bj * 128 + n * 16;
;                     const u32x2v rw = rin[gg][k], pw = pin[gg][k]; const f32x4 a = acc[ai][bj][m][n] * rs;
;                     f32x4 res; res[0] = bflo(rw.x) + sigmoidf_(a[0]) * bflo(pw.x); res[1] = bfhi(rw.x) + sigmoidf_(a[1]) * bfhi(pw.x); res[2] = bflo(rw.y) + sigmoidf_(a[2]) * bflo(pw.y); res[3] = bfhi(rw.y) + sigmoidf_(a[3]) * bfhi(pw.y);
;                     u32x2v w; w.x = pk2(res[0], res[1]); w.y = pk2(res[2], res[3]); *(u32x2v*)(out + o) = w; ss += (res[0] * res[0] + res[1] * res[1]) + (res[2] * res[2] + res[3] * res[3]); }
;                 ss += __shfl_xor(ss, 16); ss += __shfl_xor(ss, 32); if (fq == 0) part[(ai * 128 + wr * 64 + m * 16 + fr) * 4 + wc] = ss;
	v_lshlrev_b32_e32 v101, 16, v137
	v_add_f32_e32 v98, 1.0, v98
	v_rcp_f32_e32 v98, v98
	s_nop 0
	v_fmac_f32_e32 v100, v98, v99
	v_cvt_pk_bf16_f32 v98, v103, v104
	v_cvt_pk_bf16_f32 v99, v105, v100
	global_store_dwordx2 v[138:139], v[98:99], off offset:256
	v_mul_f32_e32 v98, v104, v104
	v_mul_f32_e32 v99, v100, v100
	v_fmac_f32_e32 v98, v103, v103
	v_fmac_f32_e32 v99, v105, v105
	v_add_f32_e32 v98, v98, v99
	v_lshlrev_b32_e32 v99, 16, v136
	v_lshlrev_b32_e32 v100, 16, v134
	v_fmac_f32_e32 v99, v94, v100
	v_mul_f32_e32 v94, 0xbfb8aa3b, v95
	v_exp_f32_e32 v94, v94
	v_and_b32_e32 v100, 0xffff0000, v136
	v_and_b32_e32 v95, 0xffff0000, v134
	v_add_f32_e32 v98, v102, v98
	v_add_f32_e32 v94, 1.0, v94
	v_rcp_f32_e32 v94, v94
	s_nop 0
	v_fmac_f32_e32 v100, v94, v95
	v_mul_f32_e32 v94, 0xbfb8aa3b, v96
	v_exp_f32_e32 v94, v94
	v_lshlrev_b32_e32 v95, 16, v135
	v_and_b32_e32 v96, 0xffff0000, v137
	v_add_f32_e32 v94, 1.0, v94
	v_rcp_f32_e32 v94, v94
	s_nop 0
	v_fmac_f32_e32 v101, v94, v95
	v_mul_f32_e32 v94, 0xbfb8aa3b, v97
	v_exp_f32_e32 v94, v94
	v_and_b32_e32 v95, 0xffff0000, v135
	v_add_f32_e32 v94, 1.0, v94
	v_rcp_f32_e32 v94, v94
	s_nop 0
	v_fmac_f32_e32 v96, v94, v95
	v_cvt_pk_bf16_f32 v94, v99, v100
	v_cvt_pk_bf16_f32 v95, v101, v96
	global_store_dwordx2 v[138:139], v[94:95], off offset:288
	v_mul_f32_e32 v94, v100, v100
	v_mul_f32_e32 v95, v96, v96
	v_fmac_f32_e32 v94, v99, v99
	v_fmac_f32_e32 v95, v101, v101
	v_add_f32_e32 v94, v94, v95
	v_add_f32_e32 v94, v98, v94
	ds_bpermute_b32 v95, v141, v94
	s_waitcnt lgkmcnt(0)
	v_add_f32_e32 v94, v94, v95
	ds_bpermute_b32 v95, v150, v94
	s_and_saveexec_b64 s[70:71], s[40:41]
	s_cbranch_execz .LBB0_1370
	s_waitcnt lgkmcnt(0)
	v_add_f32_e32 v94, v94, v95
	ds_write_b32 v240, v94 offset:512
.LBB0_1370:
	s_or_b64 exec, exec, s[70:71]
	v_add_f32_e32 v94, v114, v115
	s_waitcnt lgkmcnt(0)
	v_add_f32_e32 v95, v116, v117
	v_add_f32_e32 v94, v94, v95
	v_fmamk_f32 v94, v94, 0x3a800000, v159
	v_rsq_f32_e32 v96, v94
	v_lshlrev_b32_e32 v98, 16, v132
	v_lshlrev_b64 v[94:95], 11, v[186:187]
	v_lshl_add_u64 v[94:95], v[174:175], 0, v[94:95]
	v_pk_mul_f32 v[90:91], v[90:91], v[96:97] op_sel_hi:[1,0]
	v_pk_mul_f32 v[92:93], v[92:93], v[96:97] op_sel_hi:[1,0]
	v_mul_f32_e32 v90, 0xbfb8aa3b, v90
	v_exp_f32_e32 v90, v90
	v_mul_f32_e32 v91, 0xbfb8aa3b, v91
	v_exp_f32_e32 v91, v91
	v_lshlrev_b32_e32 v97, 16, v130
	v_add_f32_e32 v90, 1.0, v90
	v_rcp_f32_e32 v90, v90
	v_add_f32_e32 v91, 1.0, v91
	v_rcp_f32_e32 v91, v91
	v_fmac_f32_e32 v97, v90, v98
	v_and_b32_e32 v98, 0xffff0000, v130
	v_and_b32_e32 v90, 0xffff0000, v132
	v_fmac_f32_e32 v98, v91, v90
	v_mul_f32_e32 v90, 0xbfb8aa3b, v92
	v_exp_f32_e32 v90, v90
	v_mul_f32_e32 v91, 0xbfb8aa3b, v93
	v_exp_f32_e32 v91, v91
	v_pk_mul_f32 v[86:87], v[86:87], v[96:97] op_sel_hi:[1,0]
	v_add_f32_e32 v90, 1.0, v90
	v_mul_f32_e32 v86, 0xbfb8aa3b, v86
	v_rcp_f32_e32 v90, v90
	v_add_f32_e32 v91, 1.0, v91
	v_exp_f32_e32 v86, v86
	v_mul_f32_e32 v87, 0xbfb8aa3b, v87
	v_rcp_f32_e32 v91, v91
	v_exp_f32_e32 v87, v87
	v_lshlrev_b32_e32 v92, 16, v131
	v_lshlrev_b32_e32 v93, 16, v133
	v_fmac_f32_e32 v92, v90, v93
	v_and_b32_e32 v93, 0xffff0000, v131
	v_and_b32_e32 v90, 0xffff0000, v133
	v_add_f32_e32 v86, 1.0, v86
	v_fmac_f32_e32 v93, v91, v90
	v_cvt_pk_bf16_f32 v90, v97, v98
	v_cvt_pk_bf16_f32 v91, v92, v93
	v_rcp_f32_e32 v86, v86
	v_add_f32_e32 v87, 1.0, v87
	global_store_dwordx2 v[94:95], v[90:91], off
	v_mul_f32_e32 v90, v98, v98
	v_mul_f32_e32 v91, v93, v93
	v_rcp_f32_e32 v87, v87
	v_fmac_f32_e32 v90, v97, v97
	v_fmac_f32_e32 v91, v92, v92
	v_add_f32_e32 v90, v90, v91
	v_lshlrev_b32_e32 v91, 16, v126
	v_lshlrev_b32_e32 v92, 16, v128
	v_pk_mul_f32 v[88:89], v[88:89], v[96:97] op_sel_hi:[1,0]
	v_fmac_f32_e32 v91, v86, v92
	v_and_b32_e32 v92, 0xffff0000, v126
	v_and_b32_e32 v86, 0xffff0000, v128
	v_fmac_f32_e32 v92, v87, v86
	v_mul_f32_e32 v86, 0xbfb8aa3b, v88
	v_exp_f32_e32 v86, v86
	v_mul_f32_e32 v88, 0xbfb8aa3b, v89
	v_exp_f32_e32 v88, v88
	v_pk_mul_f32 v[82:83], v[82:83], v[96:97] op_sel_hi:[1,0]
	v_add_f32_e32 v86, 1.0, v86
	v_rcp_f32_e32 v86, v86
	v_add_f32_e32 v88, 1.0, v88
	v_mul_f32_e32 v82, 0xbfb8aa3b, v82
	v_rcp_f32_e32 v88, v88
	v_exp_f32_e32 v82, v82
	v_mul_f32_e32 v83, 0xbfb8aa3b, v83
	v_exp_f32_e32 v83, v83
	v_lshlrev_b32_e32 v87, 16, v127
	v_lshlrev_b32_e32 v89, 16, v129
	v_fmac_f32_e32 v87, v86, v89
	v_and_b32_e32 v89, 0xffff0000, v127
	v_and_b32_e32 v86, 0xffff0000, v129
	v_fmac_f32_e32 v89, v88, v86
	v_mul_f32_e32 v88, v92, v92
	v_add_f32_e32 v82, 1.0, v82
	v_cvt_pk_bf16_f32 v86, v91, v92
	v_fmac_f32_e32 v88, v91, v91
	v_mul_f32_e32 v91, v89, v89
	v_rcp_f32_e32 v82, v82
	v_add_f32_e32 v83, 1.0, v83
	v_fmac_f32_e32 v91, v87, v87
	v_rcp_f32_e32 v83, v83
	v_add_f32_e32 v88, v88, v91
	v_add_f32_e32 v88, v90, v88
	v_lshlrev_b32_e32 v90, 16, v122
	v_lshlrev_b32_e32 v91, 16, v124
	v_pk_mul_f32 v[84:85], v[84:85], v[96:97] op_sel_hi:[1,0]
	v_fmac_f32_e32 v90, v82, v91
	v_and_b32_e32 v82, 0xffff0000, v122
	v_and_b32_e32 v91, 0xffff0000, v124
	v_fmac_f32_e32 v82, v83, v91
	v_mul_f32_e32 v83, 0xbfb8aa3b, v84
	v_exp_f32_e32 v83, v83
	v_mul_f32_e32 v85, 0xbfb8aa3b, v85
	v_exp_f32_e32 v85, v85
	v_pk_mul_f32 v[78:79], v[78:79], v[96:97] op_sel_hi:[1,0]
	v_add_f32_e32 v83, 1.0, v83
	v_rcp_f32_e32 v83, v83
	v_add_f32_e32 v85, 1.0, v85
	v_mul_f32_e32 v78, 0xbfb8aa3b, v78
	v_rcp_f32_e32 v85, v85
	v_exp_f32_e32 v78, v78
	v_mul_f32_e32 v79, 0xbfb8aa3b, v79
	v_exp_f32_e32 v79, v79
	v_lshlrev_b32_e32 v84, 16, v123
	v_lshlrev_b32_e32 v91, 16, v125
	v_fmac_f32_e32 v84, v83, v91
	v_and_b32_e32 v83, 0xffff0000, v123
	v_and_b32_e32 v91, 0xffff0000, v125
	v_fmac_f32_e32 v83, v85, v91
	v_add_f32_e32 v78, 1.0, v78
	v_mul_f32_e32 v85, v82, v82
	v_mul_f32_e32 v91, v83, v83
	v_rcp_f32_e32 v78, v78
	v_add_f32_e32 v79, 1.0, v79
	v_fmac_f32_e32 v85, v90, v90
	v_fmac_f32_e32 v91, v84, v84
	v_rcp_f32_e32 v79, v79
	v_add_f32_e32 v85, v85, v91
	v_add_f32_e32 v85, v88, v85
	v_lshlrev_b32_e32 v88, 16, v118
	v_lshlrev_b32_e32 v91, 16, v120
	v_pk_mul_f32 v[80:81], v[80:81], v[96:97] op_sel_hi:[1,0]
	v_fmac_f32_e32 v88, v78, v91
	v_and_b32_e32 v91, 0xffff0000, v118
	v_and_b32_e32 v78, 0xffff0000, v120
	v_fmac_f32_e32 v91, v79, v78
	v_mul_f32_e32 v78, 0xbfb8aa3b, v80
	v_exp_f32_e32 v78, v78
	v_mul_f32_e32 v79, 0xbfb8aa3b, v81
	v_exp_f32_e32 v79, v79
	v_lshlrev_b32_e32 v92, 16, v119
	v_add_f32_e32 v78, 1.0, v78
	v_rcp_f32_e32 v78, v78
	v_add_f32_e32 v79, 1.0, v79
	v_rcp_f32_e32 v79, v79
	v_lshlrev_b32_e32 v80, 16, v121
	v_fmac_f32_e32 v92, v78, v80
	v_and_b32_e32 v93, 0xffff0000, v119
	v_and_b32_e32 v78, 0xffff0000, v121
	v_fmac_f32_e32 v93, v79, v78
	v_mul_f32_e32 v78, v91, v91
	v_mul_f32_e32 v79, v93, v93
	v_fmac_f32_e32 v78, v88, v88
	v_fmac_f32_e32 v79, v92, v92
	v_add_f32_e32 v78, v78, v79
	v_add_f32_e32 v78, v85, v78
	ds_bpermute_b32 v79, v141, v78
	v_cvt_pk_bf16_f32 v87, v87, v89
	global_store_dwordx2 v[94:95], v[86:87], off offset:32
	v_cvt_pk_bf16_f32 v80, v90, v82
	v_cvt_pk_bf16_f32 v81, v84, v83
	s_waitcnt lgkmcnt(0)
; __device__ __forceinline__ float bflo(unsigned w) { return __uint_as_float(w << 16); }
; __device__ __forceinline__ float bfhi(unsigned w) { return __uint_as_float(w & 0xffff0000u); }
; __device__ __forceinline__ unsigned pk2(float lo, float hi) { return pg8::cvt_pk_bf16(lo, hi); }
; __device__ __forceinline__ float sigmoidf_(float x) { return __builtin_amdgcn_rcpf(1.0f + __expf(-x)); }
;     __device__ __forceinline__ void operator()(const f32x4 (&acc)[2][2][4][2], const Unit& u, int wr, int wc, int fr, int fq) const {
;     ...
;         for (int hb = 0; hb < 4; ++hb) {
;             u32x2v rin[2][4], pin[2][4];
; #pragma unroll
;             for (int gg = 0; gg < 2; ++gg) { const int g = hb * 2 + gg; const size_t offn = (size_t)(row0 + (g >> 2) * 128 + (g & 3) * 16) * D + col0;
; #pragma unroll
;                 for (int k = 0; k < 4; ++k) { const size_t o = offn + (k >> 1) * 128 + (k & 1) * 16; rin[gg][k] = *(const u32x2v*)(in + o); pin[gg][k] = *(const u32x2v*)(P + o); } }
; #pragma unroll
;             for (int gg = 0; gg < 2; ++gg) {
;                 const int g = hb * 2 + gg, ai = g >> 2, m = g & 3, row = row0 + ai * 128 + m * 16;
;                 const size_t off = (size_t)row * D + col0;
;                 const float rs = rsv[g];
;                 float ss = 0.f;
; #pragma unroll
;                 for (int k = 0; k < 4; ++k) { const int bj = k >> 1, n = k & 1; const size_t o = off + bj * 128 + n * 16;
;                     const u32x2v rw = rin[gg][k], pw = pin[gg][k]; const f32x4 a = acc[ai][bj][m][n] * rs;
;                     f32x4 res; res[0] = bflo(rw.x) + sigmoidf_(a[0]) * bflo(pw.x); res[1] = bfhi(rw.x) + sigmoidf_(a[1]) * bfhi(pw.x); res[2] = bflo(rw.y) + sigmoidf_(a[2]) * bflo(pw.y); res[3] = bfhi(rw.y) + sigmoidf_(a[3]) * bfhi(pw.y);
;                     u32x2v w; w.x = pk2(res[0], res[1]); w.y = pk2(res[2], res[3]); *(u32x2v*)(out + o) = w; ss += (res[0] * res[0] + res[1] * res[1]) + (res[2] * res[2] + res[3] * res[3]); }
;                 ss += __shfl_xor(ss, 16); ss += __shfl_xor(ss, 32); if (fq == 0) part[(ai * 128 + wr * 64 + m * 16 + fr) * 4 + wc] = ss;
	v_add_f32_e32 v78, v78, v79
	ds_bpermute_b32 v79, v150, v78
	global_store_dwordx2 v[94:95], v[80:81], off offset:256
	v_cvt_pk_bf16_f32 v80, v88, v91
	v_cvt_pk_bf16_f32 v81, v92, v93
	global_store_dwordx2 v[94:95], v[80:81], off offset:288
	s_and_saveexec_b64 s[70:71], s[40:41]
	s_cbranch_execz .LBB0_1372
	s_waitcnt lgkmcnt(0)
	v_add_f32_e32 v78, v78, v79
	ds_write_b32 v240, v78 offset:768
.LBB0_1372:
	s_or_b64 exec, exec, s[70:71]
	v_add_f32_e32 v78, v106, v107
	s_waitcnt lgkmcnt(0)
	v_add_f32_e32 v79, v108, v109
	v_add_f32_e32 v78, v78, v79
	v_fmamk_f32 v78, v78, 0x3a800000, v159
	v_rsq_f32_e32 v100, v78
	v_lshlrev_b64 v[78:79], 10, v[184:185]
	v_lshl_add_u64 v[78:79], v[78:79], 0, v[180:181]
	v_lshlrev_b64 v[78:79], 1, v[78:79]
	v_lshl_add_u64 v[80:81], s[78:79], 0, v[78:79]
	global_load_dwordx2 v[110:111], v[80:81], off
	v_lshl_add_u64 v[78:79], s[90:91], 0, v[78:79]
	global_load_dwordx2 v[112:113], v[78:79], off
	global_load_dwordx2 v[108:109], v[80:81], off offset:32
	global_load_dwordx2 v[106:107], v[78:79], off offset:32
	global_load_dwordx2 v[104:105], v[80:81], off offset:256
	global_load_dwordx2 v[102:103], v[78:79], off offset:256
	global_load_dwordx2 v[96:97], v[80:81], off offset:288
	global_load_dwordx2 v[94:95], v[78:79], off offset:288
	v_pk_mul_f32 v[70:71], v[70:71], v[100:101] op_sel_hi:[1,0]
	v_pk_mul_f32 v[72:73], v[72:73], v[100:101] op_sel_hi:[1,0]
	v_mul_f32_e32 v70, 0xbfb8aa3b, v70
	v_exp_f32_e32 v70, v70
	v_lshlrev_b64 v[78:79], 10, v[178:179]
	v_lshl_add_u64 v[78:79], v[78:79], 0, v[180:181]
	v_lshl_add_u64 v[78:79], v[78:79], 1, v[164:165]
	v_add_f32_e32 v70, 1.0, v70
	v_rcp_f32_e32 v70, v70
	v_lshl_add_u64 v[80:81], s[78:79], 0, v[78:79]
	v_lshl_add_u64 v[98:99], s[90:91], 0, v[78:79]
	global_load_dwordx2 v[90:91], v[80:81], off
	global_load_dwordx2 v[92:93], v[98:99], off
	global_load_dwordx2 v[86:87], v[80:81], off offset:32
	global_load_dwordx2 v[88:89], v[98:99], off offset:32
	global_load_dwordx2 v[82:83], v[80:81], off offset:256
	global_load_dwordx2 v[84:85], v[98:99], off offset:256
	global_load_dwordx2 v[78:79], v[80:81], off offset:288
	s_nop 0
	global_load_dwordx2 v[80:81], v[98:99], off offset:288
	v_lshlrev_b64 v[98:99], 11, v[184:185]
	v_lshl_add_u64 v[98:99], v[174:175], 0, v[98:99]
	s_waitcnt vmcnt(0) lgkmcnt(0)
	v_lshlrev_b32_e32 v114, 16, v112
	v_lshlrev_b32_e32 v101, 16, v110
	v_fmac_f32_e32 v101, v70, v114
	v_mul_f32_e32 v70, 0xbfb8aa3b, v71
	v_exp_f32_e32 v70, v70
	v_and_b32_e32 v110, 0xffff0000, v110
	v_and_b32_e32 v71, 0xffff0000, v112
	v_lshlrev_b32_e32 v112, 16, v111
	v_add_f32_e32 v70, 1.0, v70
	v_rcp_f32_e32 v70, v70
	v_pk_mul_f32 v[62:63], v[62:63], v[100:101] op_sel_hi:[1,0]
	v_pk_mul_f32 v[64:65], v[64:65], v[100:101] op_sel_hi:[1,0]
	v_mul_f32_e32 v62, 0xbfb8aa3b, v62
	v_fmac_f32_e32 v110, v70, v71
	v_mul_f32_e32 v70, 0xbfb8aa3b, v72
	v_exp_f32_e32 v70, v70
	v_lshlrev_b32_e32 v71, 16, v113
	v_exp_f32_e32 v62, v62
	v_and_b32_e32 v72, 0xffff0000, v111
	v_add_f32_e32 v70, 1.0, v70
	v_rcp_f32_e32 v70, v70
	v_add_f32_e32 v62, 1.0, v62
	v_rcp_f32_e32 v62, v62
	v_pk_mul_f32 v[58:59], v[58:59], v[100:101] op_sel_hi:[1,0]
	v_fmac_f32_e32 v112, v70, v71
	v_mul_f32_e32 v70, 0xbfb8aa3b, v73
	v_exp_f32_e32 v70, v70
	v_and_b32_e32 v71, 0xffff0000, v113
	v_lshlrev_b32_e32 v73, 16, v109
	v_mul_f32_e32 v58, 0xbfb8aa3b, v58
	v_add_f32_e32 v70, 1.0, v70
	v_rcp_f32_e32 v70, v70
	v_exp_f32_e32 v58, v58
	v_pk_mul_f32 v[60:61], v[60:61], v[100:101] op_sel_hi:[1,0]
	v_pk_mul_f32 v[54:55], v[54:55], v[100:101] op_sel_hi:[1,0]
	v_fmac_f32_e32 v72, v70, v71
	v_cvt_pk_bf16_f32 v70, v101, v110
	v_cvt_pk_bf16_f32 v71, v112, v72
	global_store_dwordx2 v[98:99], v[70:71], off
	v_mul_f32_e32 v70, v110, v110
	v_mul_f32_e32 v71, v72, v72
	v_fmac_f32_e32 v70, v101, v101
	v_fmac_f32_e32 v71, v112, v112
	v_add_f32_e32 v70, v70, v71
	v_lshlrev_b32_e32 v71, 16, v108
	v_lshlrev_b32_e32 v72, 16, v106
	v_fmac_f32_e32 v71, v62, v72
	v_mul_f32_e32 v62, 0xbfb8aa3b, v63
	v_exp_f32_e32 v62, v62
	v_and_b32_e32 v72, 0xffff0000, v108
	v_and_b32_e32 v63, 0xffff0000, v106
	v_add_f32_e32 v58, 1.0, v58
	v_add_f32_e32 v62, 1.0, v62
	v_rcp_f32_e32 v62, v62
	v_rcp_f32_e32 v58, v58
	v_mul_f32_e32 v54, 0xbfb8aa3b, v54
	v_exp_f32_e32 v54, v54
	v_fmac_f32_e32 v72, v62, v63
	v_mul_f32_e32 v62, 0xbfb8aa3b, v64
	v_exp_f32_e32 v62, v62
	v_lshlrev_b32_e32 v63, 16, v107
	v_and_b32_e32 v64, 0xffff0000, v109
	v_add_f32_e32 v54, 1.0, v54
	v_add_f32_e32 v62, 1.0, v62
	v_rcp_f32_e32 v62, v62
	v_rcp_f32_e32 v54, v54
	v_pk_mul_f32 v[56:57], v[56:57], v[100:101] op_sel_hi:[1,0]
	v_fmac_f32_e32 v73, v62, v63
	v_mul_f32_e32 v62, 0xbfb8aa3b, v65
	v_exp_f32_e32 v62, v62
	v_and_b32_e32 v63, 0xffff0000, v107
	v_lshlrev_b32_e32 v65, 16, v105
	v_add_f32_e32 v62, 1.0, v62
	v_rcp_f32_e32 v62, v62
	s_nop 0
	v_fmac_f32_e32 v64, v62, v63
	v_cvt_pk_bf16_f32 v62, v71, v72
	v_cvt_pk_bf16_f32 v63, v73, v64
	global_store_dwordx2 v[98:99], v[62:63], off offset:32
	v_mul_f32_e32 v62, v72, v72
	v_mul_f32_e32 v63, v64, v64
	v_fmac_f32_e32 v62, v71, v71
	v_fmac_f32_e32 v63, v73, v73
	v_add_f32_e32 v62, v62, v63
	v_lshlrev_b32_e32 v63, 16, v104
	v_lshlrev_b32_e32 v64, 16, v102
	v_fmac_f32_e32 v63, v58, v64
	v_mul_f32_e32 v58, 0xbfb8aa3b, v59
	v_exp_f32_e32 v58, v58
	v_and_b32_e32 v64, 0xffff0000, v104
	v_and_b32_e32 v59, 0xffff0000, v102
	v_add_f32_e32 v62, v70, v62
	v_add_f32_e32 v58, 1.0, v58
	v_rcp_f32_e32 v58, v58
	s_nop 0
	v_fmac_f32_e32 v64, v58, v59
	v_mul_f32_e32 v58, 0xbfb8aa3b, v60
	v_exp_f32_e32 v58, v58
	v_lshlrev_b32_e32 v59, 16, v103
	v_and_b32_e32 v60, 0xffff0000, v105
	v_add_f32_e32 v58, 1.0, v58
	v_rcp_f32_e32 v58, v58
	s_nop 0
	v_fmac_f32_e32 v65, v58, v59
; __device__ __forceinline__ float bflo(unsigned w) { return __uint_as_float(w << 16); }
; __device__ __forceinline__ float bfhi(unsigned w) { return __uint_as_float(w & 0xffff0000u); }
; __device__ __forceinline__ unsigned pk2(float lo, float hi) { return pg8::cvt_pk_bf16(lo, hi); }
; __device__ __forceinline__ float sigmoidf_(float x) { return __builtin_amdgcn_rcpf(1.0f + __expf(-x)); }
;     __device__ __forceinline__ void operator()(const f32x4 (&acc)[2][2][4][2], const Unit& u, int wr, int wc, int fr, int fq) const {
;     ...
;             for (int gg = 0; gg < 2; ++gg) {
;                 const int g = hb * 2 + gg, ai = g >> 2, m = g & 3, row = row0 + ai * 128 + m * 16;
;                 const size_t off = (size_t)row * D + col0;
;                 const float rs = rsv[g];
;                 float ss = 0.f;
; #pragma unroll
;                 for (int k = 0; k < 4; ++k) { const int bj = k >> 1, n = k & 1; const size_t o = off + bj * 128 + n * 16;
;                     const u32x2v rw = rin[gg][k], pw = pin[gg][k]; const f32x4 a = acc[ai][bj][m][n] * rs;
;                     f32x4 res; res[0] = bflo(rw.x) + sigmoidf_(a[0]) * bflo(pw.x); res[1] = bfhi(rw.x) + sigmoidf_(a[1]) * bfhi(pw.x); res[2] = bflo(rw.y) + sigmoidf_(a[2]) * bflo(pw.y); res[3] = bfhi(rw.y) + sigmoidf_(a[3]) * bfhi(pw.y);
;                     u32x2v w; w.x = pk2(res[0], res[1]); w.y = pk2(res[2], res[3]); *(u32x2v*)(out + o) = w; ss += (res[0] * res[0] + res[1] * res[1]) + (res[2] * res[2] + res[3] * res[3]); }
;                 ss += __shfl_xor(ss, 16); ss += __shfl_xor(ss, 32); if (fq == 0) part[(ai * 128 + wr * 64 + m * 16 + fr) * 4 + wc] = ss;
	v_mul_f32_e32 v58, 0xbfb8aa3b, v61
	v_exp_f32_e32 v58, v58
	v_and_b32_e32 v59, 0xffff0000, v103
	v_lshlrev_b32_e32 v61, 16, v97
	v_add_f32_e32 v58, 1.0, v58
	v_rcp_f32_e32 v58, v58
	s_nop 0
	v_fmac_f32_e32 v60, v58, v59
	v_cvt_pk_bf16_f32 v58, v63, v64
	v_cvt_pk_bf16_f32 v59, v65, v60
	global_store_dwordx2 v[98:99], v[58:59], off offset:256
	v_mul_f32_e32 v58, v64, v64
	v_mul_f32_e32 v59, v60, v60
	v_fmac_f32_e32 v58, v63, v63
	v_fmac_f32_e32 v59, v65, v65
	v_add_f32_e32 v58, v58, v59
	v_lshlrev_b32_e32 v59, 16, v96
	v_lshlrev_b32_e32 v60, 16, v94
	v_fmac_f32_e32 v59, v54, v60
	v_mul_f32_e32 v54, 0xbfb8aa3b, v55
	v_exp_f32_e32 v54, v54
	v_and_b32_e32 v60, 0xffff0000, v96
	v_and_b32_e32 v55, 0xffff0000, v94
	v_add_f32_e32 v58, v62, v58
	v_add_f32_e32 v54, 1.0, v54
	v_rcp_f32_e32 v54, v54
	s_nop 0
	v_fmac_f32_e32 v60, v54, v55
	v_mul_f32_e32 v54, 0xbfb8aa3b, v56
	v_exp_f32_e32 v54, v54
	v_lshlrev_b32_e32 v55, 16, v95
	v_and_b32_e32 v56, 0xffff0000, v97
	v_add_f32_e32 v54, 1.0, v54
	v_rcp_f32_e32 v54, v54
	s_nop 0
	v_fmac_f32_e32 v61, v54, v55
	v_mul_f32_e32 v54, 0xbfb8aa3b, v57
	v_exp_f32_e32 v54, v54
	v_and_b32_e32 v55, 0xffff0000, v95
	v_add_f32_e32 v54, 1.0, v54
	v_rcp_f32_e32 v54, v54
	s_nop 0
	v_fmac_f32_e32 v56, v54, v55
	v_cvt_pk_bf16_f32 v54, v59, v60
	v_cvt_pk_bf16_f32 v55, v61, v56
	global_store_dwordx2 v[98:99], v[54:55], off offset:288
	v_mul_f32_e32 v54, v60, v60
	v_mul_f32_e32 v55, v56, v56
	v_fmac_f32_e32 v54, v59, v59
	v_fmac_f32_e32 v55, v61, v61
	v_add_f32_e32 v54, v54, v55
	v_add_f32_e32 v54, v58, v54
	ds_bpermute_b32 v55, v141, v54
	s_waitcnt lgkmcnt(0)
	v_add_f32_e32 v54, v54, v55
	ds_bpermute_b32 v55, v150, v54
	s_and_saveexec_b64 s[70:71], s[40:41]
	s_cbranch_execz .LBB0_1374
	s_waitcnt lgkmcnt(0)
	v_add_f32_e32 v54, v54, v55
	ds_write_b32 v240, v54 offset:2048
.LBB0_1374:
	s_or_b64 exec, exec, s[70:71]
	v_add_f32_e32 v54, v74, v75
	s_waitcnt lgkmcnt(0)
	v_add_f32_e32 v55, v76, v77
	v_add_f32_e32 v54, v54, v55
	v_fmamk_f32 v54, v54, 0x3a800000, v159
	v_rsq_f32_e32 v56, v54
	v_lshlrev_b32_e32 v58, 16, v92
	v_lshlrev_b64 v[54:55], 11, v[182:183]
	v_lshl_add_u64 v[54:55], v[174:175], 0, v[54:55]
	v_pk_mul_f32 v[50:51], v[50:51], v[56:57] op_sel_hi:[1,0]
	v_pk_mul_f32 v[52:53], v[52:53], v[56:57] op_sel_hi:[1,0]
	v_mul_f32_e32 v50, 0xbfb8aa3b, v50
	v_exp_f32_e32 v50, v50
	v_mul_f32_e32 v51, 0xbfb8aa3b, v51
	v_exp_f32_e32 v51, v51
	v_lshlrev_b32_e32 v57, 16, v90
	v_add_f32_e32 v50, 1.0, v50
	v_rcp_f32_e32 v50, v50
	v_add_f32_e32 v51, 1.0, v51
	v_rcp_f32_e32 v51, v51
	v_fmac_f32_e32 v57, v50, v58
	v_and_b32_e32 v58, 0xffff0000, v90
	v_and_b32_e32 v50, 0xffff0000, v92
	v_fmac_f32_e32 v58, v51, v50
	v_mul_f32_e32 v50, 0xbfb8aa3b, v52
	v_exp_f32_e32 v50, v50
	v_mul_f32_e32 v51, 0xbfb8aa3b, v53
	v_exp_f32_e32 v51, v51
	v_pk_mul_f32 v[46:47], v[46:47], v[56:57] op_sel_hi:[1,0]
	v_add_f32_e32 v50, 1.0, v50
	v_mul_f32_e32 v46, 0xbfb8aa3b, v46
	v_rcp_f32_e32 v50, v50
	v_add_f32_e32 v51, 1.0, v51
	v_exp_f32_e32 v46, v46
	v_mul_f32_e32 v47, 0xbfb8aa3b, v47
	v_rcp_f32_e32 v51, v51
	v_exp_f32_e32 v47, v47
	v_lshlrev_b32_e32 v52, 16, v91
	v_lshlrev_b32_e32 v53, 16, v93
	v_fmac_f32_e32 v52, v50, v53
	v_and_b32_e32 v53, 0xffff0000, v91
	v_and_b32_e32 v50, 0xffff0000, v93
	v_add_f32_e32 v46, 1.0, v46
	v_fmac_f32_e32 v53, v51, v50
	v_cvt_pk_bf16_f32 v50, v57, v58
	v_cvt_pk_bf16_f32 v51, v52, v53
	v_rcp_f32_e32 v46, v46
	v_add_f32_e32 v47, 1.0, v47
	global_store_dwordx2 v[54:55], v[50:51], off
	v_mul_f32_e32 v50, v58, v58
	v_mul_f32_e32 v51, v53, v53
	v_rcp_f32_e32 v47, v47
	v_fmac_f32_e32 v50, v57, v57
	v_fmac_f32_e32 v51, v52, v52
	v_add_f32_e32 v50, v50, v51
	v_lshlrev_b32_e32 v51, 16, v86
	v_lshlrev_b32_e32 v52, 16, v88
	v_pk_mul_f32 v[48:49], v[48:49], v[56:57] op_sel_hi:[1,0]
	v_fmac_f32_e32 v51, v46, v52
	v_and_b32_e32 v52, 0xffff0000, v86
	v_and_b32_e32 v46, 0xffff0000, v88
	v_fmac_f32_e32 v52, v47, v46
	v_mul_f32_e32 v46, 0xbfb8aa3b, v48
	v_exp_f32_e32 v46, v46
	v_mul_f32_e32 v48, 0xbfb8aa3b, v49
	v_exp_f32_e32 v48, v48
	v_pk_mul_f32 v[42:43], v[42:43], v[56:57] op_sel_hi:[1,0]
	v_add_f32_e32 v46, 1.0, v46
	v_rcp_f32_e32 v46, v46
	v_add_f32_e32 v48, 1.0, v48
	v_mul_f32_e32 v42, 0xbfb8aa3b, v42
	v_rcp_f32_e32 v48, v48
	v_exp_f32_e32 v42, v42
	v_mul_f32_e32 v43, 0xbfb8aa3b, v43
	v_exp_f32_e32 v43, v43
	v_lshlrev_b32_e32 v47, 16, v87
	v_lshlrev_b32_e32 v49, 16, v89
	v_fmac_f32_e32 v47, v46, v49
	v_and_b32_e32 v49, 0xffff0000, v87
	v_and_b32_e32 v46, 0xffff0000, v89
	v_fmac_f32_e32 v49, v48, v46
	v_mul_f32_e32 v48, v52, v52
	v_add_f32_e32 v42, 1.0, v42
	v_cvt_pk_bf16_f32 v46, v51, v52
	v_fmac_f32_e32 v48, v51, v51
	v_mul_f32_e32 v51, v49, v49
	v_rcp_f32_e32 v42, v42
	v_add_f32_e32 v43, 1.0, v43
	v_fmac_f32_e32 v51, v47, v47
	v_rcp_f32_e32 v43, v43
	v_add_f32_e32 v48, v48, v51
	v_add_f32_e32 v48, v50, v48
	v_lshlrev_b32_e32 v50, 16, v82
	v_lshlrev_b32_e32 v51, 16, v84
	v_pk_mul_f32 v[44:45], v[44:45], v[56:57] op_sel_hi:[1,0]
	v_fmac_f32_e32 v50, v42, v51
	v_and_b32_e32 v42, 0xffff0000, v82
	v_and_b32_e32 v51, 0xffff0000, v84
	v_fmac_f32_e32 v42, v43, v51
	v_mul_f32_e32 v43, 0xbfb8aa3b, v44
	v_exp_f32_e32 v43, v43
	v_mul_f32_e32 v45, 0xbfb8aa3b, v45
	v_exp_f32_e32 v45, v45
	v_pk_mul_f32 v[38:39], v[38:39], v[56:57] op_sel_hi:[1,0]
	v_add_f32_e32 v43, 1.0, v43
	v_rcp_f32_e32 v43, v43
	v_add_f32_e32 v45, 1.0, v45
	v_mul_f32_e32 v38, 0xbfb8aa3b, v38
	v_rcp_f32_e32 v45, v45
	v_exp_f32_e32 v38, v38
	v_mul_f32_e32 v39, 0xbfb8aa3b, v39
	v_exp_f32_e32 v39, v39
	v_lshlrev_b32_e32 v44, 16, v83
	v_lshlrev_b32_e32 v51, 16, v85
	v_fmac_f32_e32 v44, v43, v51
	v_and_b32_e32 v43, 0xffff0000, v83
	v_and_b32_e32 v51, 0xffff0000, v85
	v_fmac_f32_e32 v43, v45, v51
	v_add_f32_e32 v38, 1.0, v38
	v_mul_f32_e32 v45, v42, v42
	v_mul_f32_e32 v51, v43, v43
	v_rcp_f32_e32 v38, v38
	v_add_f32_e32 v39, 1.0, v39
	v_fmac_f32_e32 v45, v50, v50
	v_fmac_f32_e32 v51, v44, v44
	v_rcp_f32_e32 v39, v39
	v_add_f32_e32 v45, v45, v51
	v_add_f32_e32 v45, v48, v45
	v_lshlrev_b32_e32 v48, 16, v78
	v_lshlrev_b32_e32 v51, 16, v80
	v_pk_mul_f32 v[40:41], v[40:41], v[56:57] op_sel_hi:[1,0]
	v_fmac_f32_e32 v48, v38, v51
	v_and_b32_e32 v51, 0xffff0000, v78
	v_and_b32_e32 v38, 0xffff0000, v80
	v_fmac_f32_e32 v51, v39, v38
	v_mul_f32_e32 v38, 0xbfb8aa3b, v40
	v_exp_f32_e32 v38, v38
	v_mul_f32_e32 v39, 0xbfb8aa3b, v41
	v_exp_f32_e32 v39, v39
	v_lshlrev_b32_e32 v52, 16, v79
	v_add_f32_e32 v38, 1.0, v38
	v_rcp_f32_e32 v38, v38
	v_add_f32_e32 v39, 1.0, v39
	v_rcp_f32_e32 v39, v39
	v_lshlrev_b32_e32 v40, 16, v81
	v_fmac_f32_e32 v52, v38, v40
	v_and_b32_e32 v53, 0xffff0000, v79
	v_and_b32_e32 v38, 0xffff0000, v81
	v_fmac_f32_e32 v53, v39, v38
	v_mul_f32_e32 v38, v51, v51
	v_mul_f32_e32 v39, v53, v53
	v_fmac_f32_e32 v38, v48, v48
	v_fmac_f32_e32 v39, v52, v52
	v_add_f32_e32 v38, v38, v39
	v_add_f32_e32 v38, v45, v38
	ds_bpermute_b32 v39, v141, v38
	v_cvt_pk_bf16_f32 v47, v47, v49
	global_store_dwordx2 v[54:55], v[46:47], off offset:32
	v_cvt_pk_bf16_f32 v40, v50, v42
	v_cvt_pk_bf16_f32 v41, v44, v43
	s_waitcnt lgkmcnt(0)
; __device__ __forceinline__ float bflo(unsigned w) { return __uint_as_float(w << 16); }
; __device__ __forceinline__ float bfhi(unsigned w) { return __uint_as_float(w & 0xffff0000u); }
; __device__ __forceinline__ unsigned pk2(float lo, float hi) { return pg8::cvt_pk_bf16(lo, hi); }
; __device__ __forceinline__ float sigmoidf_(float x) { return __builtin_amdgcn_rcpf(1.0f + __expf(-x)); }
;     __device__ __forceinline__ void operator()(const f32x4 (&acc)[2][2][4][2], const Unit& u, int wr, int wc, int fr, int fq) const {
;     ...
;         for (int hb = 0; hb < 4; ++hb) {
;             u32x2v rin[2][4], pin[2][4];
; #pragma unroll
;             for (int gg = 0; gg < 2; ++gg) { const int g = hb * 2 + gg; const size_t offn = (size_t)(row0 + (g >> 2) * 128 + (g & 3) * 16) * D + col0;
; #pragma unroll
;                 for (int k = 0; k < 4; ++k) { const size_t o = offn + (k >> 1) * 128 + (k & 1) * 16; rin[gg][k] = *(const u32x2v*)(in + o); pin[gg][k] = *(const u32x2v*)(P + o); } }
; #pragma unroll
;             for (int gg = 0; gg < 2; ++gg) {
;                 const int g = hb * 2 + gg, ai = g >> 2, m = g & 3, row = row0 + ai * 128 + m * 16;
;                 const size_t off = (size_t)row * D + col0;
;                 const float rs = rsv[g];
;                 float ss = 0.f;
; #pragma unroll
;                 for (int k = 0; k < 4; ++k) { const int bj = k >> 1, n = k & 1; const size_t o = off + bj * 128 + n * 16;
;                     const u32x2v rw = rin[gg][k], pw = pin[gg][k]; const f32x4 a = acc[ai][bj][m][n] * rs;
;                     f32x4 res; res[0] = bflo(rw.x) + sigmoidf_(a[0]) * bflo(pw.x); res[1] = bfhi(rw.x) + sigmoidf_(a[1]) * bfhi(pw.x); res[2] = bflo(rw.y) + sigmoidf_(a[2]) * bflo(pw.y); res[3] = bfhi(rw.y) + sigmoidf_(a[3]) * bfhi(pw.y);
;                     u32x2v w; w.x = pk2(res[0], res[1]); w.y = pk2(res[2], res[3]); *(u32x2v*)(out + o) = w; ss += (res[0] * res[0] + res[1] * res[1]) + (res[2] * res[2] + res[3] * res[3]); }
;                 ss += __shfl_xor(ss, 16); ss += __shfl_xor(ss, 32); if (fq == 0) part[(ai * 128 + wr * 64 + m * 16 + fr) * 4 + wc] = ss;
	v_add_f32_e32 v38, v38, v39
	ds_bpermute_b32 v39, v150, v38
	global_store_dwordx2 v[54:55], v[40:41], off offset:256
	v_cvt_pk_bf16_f32 v40, v48, v51
	v_cvt_pk_bf16_f32 v41, v52, v53
	global_store_dwordx2 v[54:55], v[40:41], off offset:288
	s_and_saveexec_b64 s[70:71], s[40:41]
	s_cbranch_execz .LBB0_1376
	s_waitcnt lgkmcnt(0)
	v_add_f32_e32 v38, v38, v39
	ds_write_b32 v240, v38 offset:2304
.LBB0_1376:
	s_or_b64 exec, exec, s[70:71]
	v_add_f32_e32 v38, v66, v67
	s_waitcnt lgkmcnt(0)
	v_add_f32_e32 v39, v68, v69
	v_add_f32_e32 v38, v38, v39
	v_fmamk_f32 v38, v38, 0x3a800000, v159
	v_rsq_f32_e32 v60, v38
	v_lshlrev_b64 v[38:39], 10, v[178:179]
	v_lshl_add_u64 v[38:39], v[38:39], 0, v[180:181]
	v_lshlrev_b64 v[38:39], 1, v[38:39]
	s_mov_b64 s[50:51], 0x50000
	v_lshl_add_u64 v[40:41], v[38:39], 0, s[50:51]
	v_lshl_add_u64 v[42:43], s[78:79], 0, v[40:41]
	global_load_dwordx2 v[70:71], v[42:43], off
	v_lshl_add_u64 v[40:41], s[90:91], 0, v[40:41]
	global_load_dwordx2 v[72:73], v[40:41], off
	global_load_dwordx2 v[68:69], v[42:43], off offset:32
	global_load_dwordx2 v[66:67], v[40:41], off offset:32
	global_load_dwordx2 v[64:65], v[42:43], off offset:256
	global_load_dwordx2 v[62:63], v[40:41], off offset:256
	global_load_dwordx2 v[56:57], v[42:43], off offset:288
	global_load_dwordx2 v[54:55], v[40:41], off offset:288
	v_pk_mul_f32 v[30:31], v[30:31], v[60:61] op_sel_hi:[1,0]
	v_pk_mul_f32 v[32:33], v[32:33], v[60:61] op_sel_hi:[1,0]
	v_mul_f32_e32 v30, 0xbfb8aa3b, v30
	v_exp_f32_e32 v30, v30
	s_mov_b64 s[50:51], 0x58000
	v_lshl_add_u64 v[38:39], v[38:39], 0, s[50:51]
	v_lshl_add_u64 v[40:41], s[78:79], 0, v[38:39]
	v_add_f32_e32 v30, 1.0, v30
	v_rcp_f32_e32 v30, v30
	v_lshl_add_u64 v[58:59], s[90:91], 0, v[38:39]
	global_load_dwordx2 v[50:51], v[40:41], off
	global_load_dwordx2 v[52:53], v[58:59], off
	global_load_dwordx2 v[46:47], v[40:41], off offset:32
	global_load_dwordx2 v[48:49], v[58:59], off offset:32
	global_load_dwordx2 v[42:43], v[40:41], off offset:256
	global_load_dwordx2 v[44:45], v[58:59], off offset:256
	global_load_dwordx2 v[38:39], v[40:41], off offset:288
	s_nop 0
	global_load_dwordx2 v[40:41], v[58:59], off offset:288
	v_lshlrev_b64 v[58:59], 11, v[176:177]
	v_lshl_add_u64 v[58:59], v[174:175], 0, v[58:59]
	s_waitcnt vmcnt(0) lgkmcnt(0)
	v_lshlrev_b32_e32 v74, 16, v72
	v_lshlrev_b32_e32 v61, 16, v70
	v_fmac_f32_e32 v61, v30, v74
	v_mul_f32_e32 v30, 0xbfb8aa3b, v31
	v_exp_f32_e32 v30, v30
	v_and_b32_e32 v70, 0xffff0000, v70
	v_and_b32_e32 v31, 0xffff0000, v72
	v_lshlrev_b32_e32 v72, 16, v71
	v_add_f32_e32 v30, 1.0, v30
	v_rcp_f32_e32 v30, v30
	v_pk_mul_f32 v[26:27], v[26:27], v[60:61] op_sel_hi:[1,0]
	v_pk_mul_f32 v[28:29], v[28:29], v[60:61] op_sel_hi:[1,0]
	v_mul_f32_e32 v26, 0xbfb8aa3b, v26
	v_fmac_f32_e32 v70, v30, v31
	v_mul_f32_e32 v30, 0xbfb8aa3b, v32
	v_exp_f32_e32 v30, v30
	v_lshlrev_b32_e32 v31, 16, v73
	v_exp_f32_e32 v26, v26
	v_and_b32_e32 v32, 0xffff0000, v71
	v_add_f32_e32 v30, 1.0, v30
	v_rcp_f32_e32 v30, v30
	v_add_f32_e32 v26, 1.0, v26
	v_rcp_f32_e32 v26, v26
	v_pk_mul_f32 v[22:23], v[22:23], v[60:61] op_sel_hi:[1,0]
	v_fmac_f32_e32 v72, v30, v31
	v_mul_f32_e32 v30, 0xbfb8aa3b, v33
	v_exp_f32_e32 v30, v30
	v_and_b32_e32 v31, 0xffff0000, v73
	v_lshlrev_b32_e32 v33, 16, v69
	v_mul_f32_e32 v22, 0xbfb8aa3b, v22
	v_add_f32_e32 v30, 1.0, v30
	v_rcp_f32_e32 v30, v30
	v_exp_f32_e32 v22, v22
	v_pk_mul_f32 v[24:25], v[24:25], v[60:61] op_sel_hi:[1,0]
	v_pk_mul_f32 v[18:19], v[18:19], v[60:61] op_sel_hi:[1,0]
	v_fmac_f32_e32 v32, v30, v31
	v_cvt_pk_bf16_f32 v30, v61, v70
	v_cvt_pk_bf16_f32 v31, v72, v32
	global_store_dwordx2 v[58:59], v[30:31], off
	v_mul_f32_e32 v30, v70, v70
	v_mul_f32_e32 v31, v32, v32
	v_fmac_f32_e32 v30, v61, v61
	v_fmac_f32_e32 v31, v72, v72
	v_add_f32_e32 v30, v30, v31
	v_lshlrev_b32_e32 v31, 16, v68
	v_lshlrev_b32_e32 v32, 16, v66
	v_fmac_f32_e32 v31, v26, v32
	v_mul_f32_e32 v26, 0xbfb8aa3b, v27
	v_exp_f32_e32 v26, v26
	v_and_b32_e32 v32, 0xffff0000, v68
	v_and_b32_e32 v27, 0xffff0000, v66
	v_add_f32_e32 v22, 1.0, v22
	v_add_f32_e32 v26, 1.0, v26
	v_rcp_f32_e32 v26, v26
	v_rcp_f32_e32 v22, v22
	v_mul_f32_e32 v18, 0xbfb8aa3b, v18
	v_exp_f32_e32 v18, v18
	v_fmac_f32_e32 v32, v26, v27
	v_mul_f32_e32 v26, 0xbfb8aa3b, v28
	v_exp_f32_e32 v26, v26
	v_lshlrev_b32_e32 v27, 16, v67
	v_and_b32_e32 v28, 0xffff0000, v69
	v_add_f32_e32 v18, 1.0, v18
	v_add_f32_e32 v26, 1.0, v26
	v_rcp_f32_e32 v26, v26
	v_rcp_f32_e32 v18, v18
	v_pk_mul_f32 v[20:21], v[20:21], v[60:61] op_sel_hi:[1,0]
	v_fmac_f32_e32 v33, v26, v27
	v_mul_f32_e32 v26, 0xbfb8aa3b, v29
	v_exp_f32_e32 v26, v26
	v_and_b32_e32 v27, 0xffff0000, v67
	v_lshlrev_b32_e32 v29, 16, v65
	v_add_f32_e32 v26, 1.0, v26
	v_rcp_f32_e32 v26, v26
	s_nop 0
	v_fmac_f32_e32 v28, v26, v27
	v_cvt_pk_bf16_f32 v26, v31, v32
	v_cvt_pk_bf16_f32 v27, v33, v28
	global_store_dwordx2 v[58:59], v[26:27], off offset:32
	v_mul_f32_e32 v26, v32, v32
	v_mul_f32_e32 v27, v28, v28
	v_fmac_f32_e32 v26, v31, v31
	v_fmac_f32_e32 v27, v33, v33
	v_add_f32_e32 v26, v26, v27
	v_lshlrev_b32_e32 v27, 16, v64
	v_lshlrev_b32_e32 v28, 16, v62
	v_fmac_f32_e32 v27, v22, v28
	v_mul_f32_e32 v22, 0xbfb8aa3b, v23
	v_exp_f32_e32 v22, v22
	v_and_b32_e32 v28, 0xffff0000, v64
	v_and_b32_e32 v23, 0xffff0000, v62
	v_add_f32_e32 v26, v30, v26
	v_add_f32_e32 v22, 1.0, v22
	v_rcp_f32_e32 v22, v22
	s_nop 0
	v_fmac_f32_e32 v28, v22, v23
	v_mul_f32_e32 v22, 0xbfb8aa3b, v24
	v_exp_f32_e32 v22, v22
	v_lshlrev_b32_e32 v23, 16, v63
	v_and_b32_e32 v24, 0xffff0000, v65
	v_add_f32_e32 v22, 1.0, v22
	v_rcp_f32_e32 v22, v22
	s_nop 0
	v_fmac_f32_e32 v29, v22, v23
	v_mul_f32_e32 v22, 0xbfb8aa3b, v25
	v_exp_f32_e32 v22, v22
; __device__ __forceinline__ float bflo(unsigned w) { return __uint_as_float(w << 16); }
; __device__ __forceinline__ float bfhi(unsigned w) { return __uint_as_float(w & 0xffff0000u); }
; __device__ __forceinline__ unsigned pk2(float lo, float hi) { return pg8::cvt_pk_bf16(lo, hi); }
; __device__ __forceinline__ float sigmoidf_(float x) { return __builtin_amdgcn_rcpf(1.0f + __expf(-x)); }
;     __device__ __forceinline__ void operator()(const f32x4 (&acc)[2][2][4][2], const Unit& u, int wr, int wc, int fr, int fq) const {
;     ...
;             for (int gg = 0; gg < 2; ++gg) {
;                 const int g = hb * 2 + gg, ai = g >> 2, m = g & 3, row = row0 + ai * 128 + m * 16;
;                 const size_t off = (size_t)row * D + col0;
;                 const float rs = rsv[g];
;                 float ss = 0.f;
; #pragma unroll
;                 for (int k = 0; k < 4; ++k) { const int bj = k >> 1, n = k & 1; const size_t o = off + bj * 128 + n * 16;
;                     const u32x2v rw = rin[gg][k], pw = pin[gg][k]; const f32x4 a = acc[ai][bj][m][n] * rs;
;                     f32x4 res; res[0] = bflo(rw.x) + sigmoidf_(a[0]) * bflo(pw.x); res[1] = bfhi(rw.x) + sigmoidf_(a[1]) * bfhi(pw.x); res[2] = bflo(rw.y) + sigmoidf_(a[2]) * bflo(pw.y); res[3] = bfhi(rw.y) + sigmoidf_(a[3]) * bfhi(pw.y);
;                     u32x2v w; w.x = pk2(res[0], res[1]); w.y = pk2(res[2], res[3]); *(u32x2v*)(out + o) = w; ss += (res[0] * res[0] + res[1] * res[1]) + (res[2] * res[2] + res[3] * res[3]); }
;                 ss += __shfl_xor(ss, 16); ss += __shfl_xor(ss, 32); if (fq == 0) part[(ai * 128 + wr * 64 + m * 16 + fr) * 4 + wc] = ss;
	v_and_b32_e32 v23, 0xffff0000, v63
	v_lshlrev_b32_e32 v25, 16, v57
	v_add_f32_e32 v22, 1.0, v22
	v_rcp_f32_e32 v22, v22
	s_nop 0
	v_fmac_f32_e32 v24, v22, v23
	v_cvt_pk_bf16_f32 v22, v27, v28
	v_cvt_pk_bf16_f32 v23, v29, v24
	global_store_dwordx2 v[58:59], v[22:23], off offset:256
	v_mul_f32_e32 v22, v28, v28
	v_mul_f32_e32 v23, v24, v24
	v_fmac_f32_e32 v22, v27, v27
	v_fmac_f32_e32 v23, v29, v29
	v_add_f32_e32 v22, v22, v23
	v_lshlrev_b32_e32 v23, 16, v56
	v_lshlrev_b32_e32 v24, 16, v54
	v_fmac_f32_e32 v23, v18, v24
	v_mul_f32_e32 v18, 0xbfb8aa3b, v19
	v_exp_f32_e32 v18, v18
	v_and_b32_e32 v24, 0xffff0000, v56
	v_and_b32_e32 v19, 0xffff0000, v54
	v_add_f32_e32 v22, v26, v22
	v_add_f32_e32 v18, 1.0, v18
	v_rcp_f32_e32 v18, v18
	s_nop 0
	v_fmac_f32_e32 v24, v18, v19
	v_mul_f32_e32 v18, 0xbfb8aa3b, v20
	v_exp_f32_e32 v18, v18
	v_lshlrev_b32_e32 v19, 16, v55
	v_and_b32_e32 v20, 0xffff0000, v57
	v_add_f32_e32 v18, 1.0, v18
	v_rcp_f32_e32 v18, v18
	s_nop 0
	v_fmac_f32_e32 v25, v18, v19
	v_mul_f32_e32 v18, 0xbfb8aa3b, v21
	v_exp_f32_e32 v18, v18
	v_and_b32_e32 v19, 0xffff0000, v55
	v_add_f32_e32 v18, 1.0, v18
	v_rcp_f32_e32 v18, v18
	s_nop 0
	v_fmac_f32_e32 v20, v18, v19
	v_cvt_pk_bf16_f32 v18, v23, v24
	v_cvt_pk_bf16_f32 v19, v25, v20
	global_store_dwordx2 v[58:59], v[18:19], off offset:288
	v_mul_f32_e32 v18, v24, v24
	v_mul_f32_e32 v19, v20, v20
	v_fmac_f32_e32 v18, v23, v23
	v_fmac_f32_e32 v19, v25, v25
	v_add_f32_e32 v18, v18, v19
	v_add_f32_e32 v18, v22, v18
	ds_bpermute_b32 v19, v141, v18
	s_waitcnt lgkmcnt(0)
	v_add_f32_e32 v18, v18, v19
	ds_bpermute_b32 v19, v150, v18
	s_and_saveexec_b64 s[70:71], s[40:41]
	s_cbranch_execz .LBB0_1378
	s_waitcnt lgkmcnt(0)
	v_add_f32_e32 v18, v18, v19
	ds_write_b32 v240, v18 offset:2560
; #define LAS __attribute__((address_space(3)))
; __device__ __forceinline__ float bflo(unsigned w) { return __uint_as_float(w << 16); }
; __device__ __forceinline__ float bfhi(unsigned w) { return __uint_as_float(w & 0xffff0000u); }
; __device__ __forceinline__ unsigned pk2(float lo, float hi) { return pg8::cvt_pk_bf16(lo, hi); }
; __device__ __forceinline__ float sigmoidf_(float x) { return __builtin_amdgcn_rcpf(1.0f + __expf(-x)); }
;     __device__ __forceinline__ void operator()(const f32x4 (&acc)[2][2][4][2], const Unit& u, int wr, int wc, int fr, int fq) const {
;     ...
;             for (int gg = 0; gg < 2; ++gg) {
;                 const int g = hb * 2 + gg, ai = g >> 2, m = g & 3, row = row0 + ai * 128 + m * 16;
;                 const size_t off = (size_t)row * D + col0;
;                 const float rs = rsv[g];
;                 float ss = 0.f;
; #pragma unroll
;                 for (int k = 0; k < 4; ++k) { const int bj = k >> 1, n = k & 1; const size_t o = off + bj * 128 + n * 16;
;                     const u32x2v rw = rin[gg][k], pw = pin[gg][k]; const f32x4 a = acc[ai][bj][m][n] * rs;
;                     f32x4 res; res[0] = bflo(rw.x) + sigmoidf_(a[0]) * bflo(pw.x); res[1] = bfhi(rw.x) + sigmoidf_(a[1]) * bfhi(pw.x); res[2] = bflo(rw.y) + sigmoidf_(a[2]) * bflo(pw.y); res[3] = bfhi(rw.y) + sigmoidf_(a[3]) * bfhi(pw.y);
;                     u32x2v w; w.x = pk2(res[0], res[1]); w.y = pk2(res[2], res[3]); *(u32x2v*)(out + o) = w; ss += (res[0] * res[0] + res[1] * res[1]) + (res[2] * res[2] + res[3] * res[3]); }
;                 ss += __shfl_xor(ss, 16); ss += __shfl_xor(ss, 32); if (fq == 0) part[(ai * 128 + wr * 64 + m * 16 + fr) * 4 + wc] = ss;
;             }
;         }
;         asm volatile("s_waitcnt lgkmcnt(0)" ::: "memory"); __builtin_amdgcn_s_barrier(); asm volatile("" ::: "memory");
;         { int t = threadIdx.x; asm volatile("" : "+v"(t)); if (t < 256) { const f32x4 p = *(const LAS f32x4*)(part + t * 4); rss_out[(size_t)(u.pm * 256 + t) * 4 + u.pn] = (p[0] + p[1]) + (p[2] + p[3]); } }
.LBB0_1378:
	s_or_b64 exec, exec, s[70:71]
	v_add_f32_e32 v18, v34, v35
	s_waitcnt lgkmcnt(0)
	v_add_f32_e32 v19, v36, v37
	v_add_f32_e32 v18, v18, v19
	v_fmamk_f32 v18, v18, 0x3a800000, v159
	v_rsq_f32_e32 v20, v18
	v_lshlrev_b32_e32 v22, 16, v52
	v_lshlrev_b64 v[18:19], 11, v[172:173]
	v_lshl_add_u64 v[18:19], v[174:175], 0, v[18:19]
	v_pk_mul_f32 v[14:15], v[14:15], v[20:21] op_sel_hi:[1,0]
	v_pk_mul_f32 v[16:17], v[16:17], v[20:21] op_sel_hi:[1,0]
	v_mul_f32_e32 v14, 0xbfb8aa3b, v14
	v_exp_f32_e32 v14, v14
	v_mul_f32_e32 v15, 0xbfb8aa3b, v15
	v_exp_f32_e32 v15, v15
	v_lshlrev_b32_e32 v21, 16, v50
	v_add_f32_e32 v14, 1.0, v14
	v_rcp_f32_e32 v14, v14
	v_add_f32_e32 v15, 1.0, v15
	v_rcp_f32_e32 v15, v15
	v_fmac_f32_e32 v21, v14, v22
	v_and_b32_e32 v22, 0xffff0000, v50
	v_and_b32_e32 v14, 0xffff0000, v52
	v_fmac_f32_e32 v22, v15, v14
	v_mul_f32_e32 v14, 0xbfb8aa3b, v16
	v_exp_f32_e32 v14, v14
	v_mul_f32_e32 v15, 0xbfb8aa3b, v17
	v_exp_f32_e32 v15, v15
	v_pk_mul_f32 v[10:11], v[10:11], v[20:21] op_sel_hi:[1,0]
	v_add_f32_e32 v14, 1.0, v14
	v_mul_f32_e32 v10, 0xbfb8aa3b, v10
	v_rcp_f32_e32 v14, v14
	v_add_f32_e32 v15, 1.0, v15
	v_exp_f32_e32 v10, v10
	v_mul_f32_e32 v11, 0xbfb8aa3b, v11
	v_rcp_f32_e32 v15, v15
	v_exp_f32_e32 v11, v11
	v_lshlrev_b32_e32 v16, 16, v51
	v_lshlrev_b32_e32 v17, 16, v53
	v_fmac_f32_e32 v16, v14, v17
	v_and_b32_e32 v17, 0xffff0000, v51
	v_and_b32_e32 v14, 0xffff0000, v53
	v_add_f32_e32 v10, 1.0, v10
	v_fmac_f32_e32 v17, v15, v14
	v_cvt_pk_bf16_f32 v14, v21, v22
	v_cvt_pk_bf16_f32 v15, v16, v17
	v_rcp_f32_e32 v10, v10
	v_add_f32_e32 v11, 1.0, v11
	global_store_dwordx2 v[18:19], v[14:15], off
	v_mul_f32_e32 v14, v22, v22
	v_mul_f32_e32 v15, v17, v17
	v_rcp_f32_e32 v11, v11
	v_fmac_f32_e32 v14, v21, v21
	v_fmac_f32_e32 v15, v16, v16
	v_add_f32_e32 v14, v14, v15
	v_lshlrev_b32_e32 v15, 16, v46
	v_lshlrev_b32_e32 v16, 16, v48
	v_pk_mul_f32 v[12:13], v[12:13], v[20:21] op_sel_hi:[1,0]
	v_fmac_f32_e32 v15, v10, v16
	v_and_b32_e32 v16, 0xffff0000, v46
	v_and_b32_e32 v10, 0xffff0000, v48
	v_fmac_f32_e32 v16, v11, v10
	v_mul_f32_e32 v10, 0xbfb8aa3b, v12
	v_exp_f32_e32 v10, v10
	v_mul_f32_e32 v12, 0xbfb8aa3b, v13
	v_exp_f32_e32 v12, v12
	v_pk_mul_f32 v[6:7], v[6:7], v[20:21] op_sel_hi:[1,0]
	v_add_f32_e32 v10, 1.0, v10
	v_rcp_f32_e32 v10, v10
	v_add_f32_e32 v12, 1.0, v12
	v_mul_f32_e32 v6, 0xbfb8aa3b, v6
	v_rcp_f32_e32 v12, v12
	v_exp_f32_e32 v6, v6
	v_mul_f32_e32 v7, 0xbfb8aa3b, v7
	v_exp_f32_e32 v7, v7
	v_lshlrev_b32_e32 v11, 16, v47
	v_lshlrev_b32_e32 v13, 16, v49
	v_fmac_f32_e32 v11, v10, v13
	v_and_b32_e32 v13, 0xffff0000, v47
	v_and_b32_e32 v10, 0xffff0000, v49
	v_fmac_f32_e32 v13, v12, v10
	v_mul_f32_e32 v12, v16, v16
	v_add_f32_e32 v6, 1.0, v6
	v_cvt_pk_bf16_f32 v10, v15, v16
	v_fmac_f32_e32 v12, v15, v15
	v_mul_f32_e32 v15, v13, v13
	v_rcp_f32_e32 v6, v6
	v_add_f32_e32 v7, 1.0, v7
	v_fmac_f32_e32 v15, v11, v11
	v_rcp_f32_e32 v7, v7
	v_add_f32_e32 v12, v12, v15
	v_add_f32_e32 v12, v14, v12
	v_lshlrev_b32_e32 v14, 16, v42
	v_lshlrev_b32_e32 v15, 16, v44
	v_pk_mul_f32 v[8:9], v[8:9], v[20:21] op_sel_hi:[1,0]
	v_fmac_f32_e32 v14, v6, v15
	v_and_b32_e32 v6, 0xffff0000, v42
	v_and_b32_e32 v15, 0xffff0000, v44
	v_fmac_f32_e32 v6, v7, v15
	v_mul_f32_e32 v7, 0xbfb8aa3b, v8
	v_exp_f32_e32 v7, v7
	v_mul_f32_e32 v9, 0xbfb8aa3b, v9
	v_exp_f32_e32 v9, v9
	v_pk_mul_f32 v[2:3], v[2:3], v[20:21] op_sel_hi:[1,0]
	v_add_f32_e32 v7, 1.0, v7
	v_rcp_f32_e32 v7, v7
	v_add_f32_e32 v9, 1.0, v9
	v_mul_f32_e32 v2, 0xbfb8aa3b, v2
	v_rcp_f32_e32 v9, v9
	v_exp_f32_e32 v2, v2
	v_mul_f32_e32 v3, 0xbfb8aa3b, v3
	v_exp_f32_e32 v3, v3
	v_lshlrev_b32_e32 v8, 16, v43
	v_lshlrev_b32_e32 v15, 16, v45
	v_fmac_f32_e32 v8, v7, v15
	v_and_b32_e32 v7, 0xffff0000, v43
	v_and_b32_e32 v15, 0xffff0000, v45
	v_fmac_f32_e32 v7, v9, v15
	v_add_f32_e32 v2, 1.0, v2
	v_mul_f32_e32 v9, v6, v6
	v_mul_f32_e32 v15, v7, v7
	v_rcp_f32_e32 v2, v2
	v_add_f32_e32 v3, 1.0, v3
	v_fmac_f32_e32 v9, v14, v14
	v_fmac_f32_e32 v15, v8, v8
	v_rcp_f32_e32 v3, v3
	v_add_f32_e32 v9, v9, v15
	v_add_f32_e32 v9, v12, v9
	v_lshlrev_b32_e32 v12, 16, v38
	v_lshlrev_b32_e32 v15, 16, v40
	v_pk_mul_f32 v[4:5], v[4:5], v[20:21] op_sel_hi:[1,0]
	v_fmac_f32_e32 v12, v2, v15
	v_and_b32_e32 v15, 0xffff0000, v38
	v_and_b32_e32 v2, 0xffff0000, v40
	v_fmac_f32_e32 v15, v3, v2
	v_mul_f32_e32 v2, 0xbfb8aa3b, v4
	v_exp_f32_e32 v2, v2
	v_mul_f32_e32 v3, 0xbfb8aa3b, v5
	v_exp_f32_e32 v3, v3
	v_lshlrev_b32_e32 v16, 16, v39
	v_add_f32_e32 v2, 1.0, v2
	v_rcp_f32_e32 v2, v2
	v_add_f32_e32 v3, 1.0, v3
	v_rcp_f32_e32 v3, v3
	v_lshlrev_b32_e32 v4, 16, v41
	v_fmac_f32_e32 v16, v2, v4
	v_and_b32_e32 v17, 0xffff0000, v39
	v_and_b32_e32 v2, 0xffff0000, v41
	v_fmac_f32_e32 v17, v3, v2
	v_mul_f32_e32 v2, v15, v15
	v_mul_f32_e32 v3, v17, v17
	v_fmac_f32_e32 v2, v12, v12
	v_fmac_f32_e32 v3, v16, v16
	v_add_f32_e32 v2, v2, v3
	v_add_f32_e32 v2, v9, v2
	ds_bpermute_b32 v3, v141, v2
	v_cvt_pk_bf16_f32 v11, v11, v13
	global_store_dwordx2 v[18:19], v[10:11], off offset:32
	v_cvt_pk_bf16_f32 v4, v14, v6
	v_cvt_pk_bf16_f32 v5, v8, v7
	s_waitcnt lgkmcnt(0)
	v_add_f32_e32 v2, v2, v3
	ds_bpermute_b32 v3, v150, v2
	global_store_dwordx2 v[18:19], v[4:5], off offset:256
	v_cvt_pk_bf16_f32 v4, v12, v15
	v_cvt_pk_bf16_f32 v5, v16, v17
	global_store_dwordx2 v[18:19], v[4:5], off offset:288
	s_and_saveexec_b64 s[70:71], s[40:41]
	s_cbranch_execz .LBB0_1380
	s_waitcnt lgkmcnt(0)
	v_add_f32_e32 v2, v2, v3
	ds_write_b32 v240, v2 offset:2816
.LBB0_1380:
	s_or_b64 exec, exec, s[70:71]
	s_waitcnt lgkmcnt(0)
	s_barrier
	v_mov_b32_e32 v2, v158
	s_movk_i32 s49, 0x100
	s_nop 0
	v_cmp_gt_i32_e32 vcc, s49, v2
	s_and_saveexec_b64 s[70:71], vcc
	s_cbranch_execz .LBB0_1382
	s_waitcnt lgkmcnt(0)
	v_lshl_add_u32 v3, v2, 4, 0
	v_add_u32_e32 v3, 0x20000, v3
	ds_read_b128 v[4:7], v3
	v_add_u32_e32 v2, s19, v2
	v_ashrrev_i32_e32 v3, 31, v2
	s_ashr_i32 s19, s18, 31
	v_lshl_add_u64 v[2:3], v[2:3], 4, s[80:81]
	s_waitcnt lgkmcnt(0)
	v_mov_b32_e32 v8, v5
	v_mov_b32_e32 v9, v6
	v_mov_b32_e32 v5, v7
	v_pk_add_f32 v[4:5], v[8:9], v[4:5]
	v_lshl_add_u64 v[2:3], s[18:19], 2, v[2:3]
	v_add_f32_e32 v4, v4, v5
	global_store_dword v[2:3], v4, off

; __global__ void __launch_bounds__(NTHR, 2) hymba_fwd(Args args) {
	.amdhsa_kernel _Z9hymba_fwd4Args
		.amdhsa_group_segment_fixed_size 0
		.amdhsa_private_segment_fixed_size 0
		.amdhsa_kernarg_size 512
		.amdhsa_user_sgpr_count 2
		.amdhsa_user_sgpr_dispatch_ptr 0
		.amdhsa_user_sgpr_queue_ptr 0
		.amdhsa_user_sgpr_kernarg_segment_ptr 1
		.amdhsa_user_sgpr_dispatch_id 0
		.amdhsa_user_sgpr_kernarg_preload_length 0
		.amdhsa_user_sgpr_kernarg_preload_offset 0
		.amdhsa_user_sgpr_private_segment_size 0
		.amdhsa_uses_dynamic_stack 0
		.amdhsa_enable_private_segment 0
		.amdhsa_system_sgpr_workgroup_id_x 1
		.amdhsa_system_sgpr_workgroup_id_y 0
		.amdhsa_system_sgpr_workgroup_id_z 0
		.amdhsa_system_sgpr_workgroup_info 0
		.amdhsa_system_vgpr_workitem_id 2
		.amdhsa_next_free_vgpr 256
		.amdhsa_next_free_sgpr 102
		.amdhsa_accum_offset 256
		.amdhsa_reserve_vcc 1
		.amdhsa_float_round_mode_32 0
		.amdhsa_float_round_mode_16_64 0
		.amdhsa_float_denorm_mode_32 3
		.amdhsa_float_denorm_mode_16_64 3
		.amdhsa_dx10_clamp 1
		.amdhsa_ieee_mode 1
		.amdhsa_fp16_overflow 0
		.amdhsa_tg_split 0
		.amdhsa_exception_fp_ieee_invalid_op 0
		.amdhsa_exception_fp_denorm_src 0
		.amdhsa_exception_fp_ieee_div_zero 0
		.amdhsa_exception_fp_ieee_overflow 0
		.amdhsa_exception_fp_ieee_underflow 0
		.amdhsa_exception_fp_ieee_inexact 0
		.amdhsa_exception_int_div_zero 0
	.end_amdhsa_kernel

; __global__ void __launch_bounds__(NTHR, 2) hymba_fwd(Args args) {
amdhsa.kernels:
  - .agpr_count:     0
    .args:
      - .offset:         0
        .size:           256
        .value_kind:     by_value
      - .offset:         256
        .size:           4
        .value_kind:     hidden_block_count_x
      - .offset:         260
        .size:           4
        .value_kind:     hidden_block_count_y
      - .offset:         264
        .size:           4
        .value_kind:     hidden_block_count_z
      - .offset:         268
        .size:           2
        .value_kind:     hidden_group_size_x
      - .offset:         270
        .size:           2
        .value_kind:     hidden_group_size_y
      - .offset:         272
        .size:           2
        .value_kind:     hidden_group_size_z
      - .offset:         274
        .size:           2
        .value_kind:     hidden_remainder_x
      - .offset:         276
        .size:           2
        .value_kind:     hidden_remainder_y
      - .offset:         278
        .size:           2
        .value_kind:     hidden_remainder_z
      - .offset:         296
        .size:           8
        .value_kind:     hidden_global_offset_x
      - .offset:         304
        .size:           8
        .value_kind:     hidden_global_offset_y
      - .offset:         312
        .size:           8
        .value_kind:     hidden_global_offset_z
      - .offset:         320
        .size:           2
        .value_kind:     hidden_grid_dims
      - .offset:         344
        .size:           8
        .value_kind:     hidden_multigrid_sync_arg
      - .offset:         376
        .size:           4
        .value_kind:     hidden_dynamic_lds_size
    .group_segment_fixed_size: 0
    .kernarg_segment_align: 8
    .kernarg_segment_size: 512
    .language:       OpenCL C
    .language_version:
      - 2
      - 0
    .max_flat_workgroup_size: 512
    .name:           _Z9hymba_fwd4Args
    .private_segment_fixed_size: 0
    .sgpr_count:     108
    .sgpr_spill_count: 230
    .symbol:         _Z9hymba_fwd4Args.kd
    .uniform_work_group_size: 1
    .uses_dynamic_stack: false
    .vgpr_count:     256
    .vgpr_spill_count: 0
    .wavefront_size: 64
